# EW row loops A/D: removed the loop-top full store drain so the next iteration's row loads issue while previous stores are still in flight
# baseline (speedup 1.0000x reference)
; template <bool XIN_BF, bool XOUT_BF>
; __device__ __forceinline__ void ew_rows(const void* xsrc, void* xdst, const bf16* y, float scale, const float* gpost, const float* gpre, bf16* hout, int gw, int ngw, int lane) {
;     ...
;     for (int row0 = gw; row0 < TOK; row0 += NR * ngw) {
;         v2u xb[XIN_BF ? NR : 1][8]; f32x4 xf[XIN_BF ? 1 : NR][8]; v2u yb[NR][8];
; #pragma unroll
;         for (int r = 0; r < NR; ++r) { const int row = (row0 + r * ngw < TOK) ? row0 + r * ngw : row0;
;             if (XIN_BF) { const v2u* xr = (const v2u*)((const bf16*)xsrc + (size_t)row * DM) + lane;
; #pragma unroll
;                 for (int j = 0; j < 8; ++j) xb[XIN_BF ? r : 0][j] = xr[64 * j];
;             } else { const f32x4* xr = (const f32x4*)((const float*)xsrc + (size_t)row * DM) + lane;
; #pragma unroll
;                 for (int j = 0; j < 8; ++j) xf[XIN_BF ? 0 : r][j] = xr[64 * j]; }
;             if (y) { const v2u* yr = (const v2u*)(y + (size_t)row * DM) + lane;
; #pragma unroll
;                 for (int j = 0; j < 8; ++j) yb[r][j] = yr[64 * j]; }
;         }
;         asm volatile("" ::: "memory");
; #pragma unroll
;         for (int r = 0; r < NR; ++r) { const int row = row0 + r * ngw; if (row >= TOK) break;
;             f32x4 xv[8];
; #pragma unroll
;             for (int j = 0; j < 8; ++j) { if (XIN_BF) { const v2u w = xb[XIN_BF ? r : 0][j]; xv[j] = (f32x4){__uint_as_float(w.x << 16), __uint_as_float(w.x & 0xffff0000u), __uint_as_float(w.y << 16), __uint_as_float(w.y & 0xffff0000u)}; } else xv[j] = xf[XIN_BF ? 0 : r][j]; }
;             if (y) {
;                 f32x4 yv[8]; float ss = 0.f;
; #pragma unroll
;                 for (int j = 0; j < 8; ++j) { const v2u w = yb[r][j]; yv[j] = (f32x4){__uint_as_float(w.x << 16), __uint_as_float(w.x & 0xffff0000u), __uint_as_float(w.y << 16), __uint_as_float(w.y & 0xffff0000u)};
;                     ss += (yv[j].x * yv[j].x + yv[j].y * yv[j].y) + (yv[j].z * yv[j].z + yv[j].w * yv[j].w); }
.LBB0_747:
	v_lshl_add_u64 v[128:129], s[76:77], 0, v[160:161]
	global_load_dwordx2 v[0:1], v[128:129], off
	global_load_dwordx2 v[2:3], v[128:129], off offset:512
	global_load_dwordx2 v[138:139], v[128:129], off offset:1024
	global_load_dwordx2 v[144:145], v[128:129], off offset:1536
	global_load_dwordx2 v[146:147], v[128:129], off offset:2048
	global_load_dwordx2 v[148:149], v[128:129], off offset:2560
	global_load_dwordx2 v[156:157], v[128:129], off offset:3072
	global_load_dwordx2 v[164:165], v[128:129], off offset:3584
	v_lshl_add_u64 v[126:127], s[44:45], 0, v[160:161]
	v_add_co_u32_e32 v30, vcc, 0x10000000, v126
	s_add_i32 s86, s3, s1
	s_nop 0
	v_addc_co_u32_e32 v31, vcc, 0, v127, vcc
	global_load_dwordx2 v[174:175], v[30:31], off
	global_load_dwordx2 v[176:177], v[30:31], off offset:512
	global_load_dwordx2 v[178:179], v[30:31], off offset:1024
	global_load_dwordx2 v[180:181], v[30:31], off offset:1536
	global_load_dwordx2 v[172:173], v[30:31], off offset:2048
	global_load_dwordx2 v[170:171], v[30:31], off offset:2560
	global_load_dwordx2 v[168:169], v[30:31], off offset:3072
	global_load_dwordx2 v[166:167], v[30:31], off offset:3584
	s_cmpk_lt_i32 s86, 0x4000
	s_cselect_b32 s4, s86, s1
	s_ashr_i32 s5, s4, 31
	s_lshl_b64 s[4:5], s[4:5], 12
	s_add_i32 s82, s0, s1
	s_cmpk_lt_i32 s82, 0x4000
	s_cselect_b64 s[84:85], -1, 0
	s_and_b64 s[28:29], s[84:85], exec
	s_cselect_b32 s28, s82, s1
	s_ashr_i32 s29, s28, 31
	s_mul_i32 s9, s2, 24
	s_lshl_b64 s[28:29], s[28:29], 12
	s_add_i32 s78, s9, s1
	s_cmpk_lt_i32 s78, 0x4000
	s_cselect_b64 s[80:81], -1, 0
	s_and_b64 s[52:53], s[80:81], exec
	v_lshl_add_u64 v[30:31], v[4:5], 0, s[4:5]
	s_cselect_b32 s52, s78, s1
	global_load_dwordx2 v[124:125], v[30:31], off
	global_load_dwordx2 v[122:123], v[30:31], off offset:512
	global_load_dwordx2 v[120:121], v[30:31], off offset:1024
	global_load_dwordx2 v[118:119], v[30:31], off offset:1536
	global_load_dwordx2 v[116:117], v[30:31], off offset:2048
	global_load_dwordx2 v[114:115], v[30:31], off offset:2560
	global_load_dwordx2 v[112:113], v[30:31], off offset:3072
	global_load_dwordx2 v[110:111], v[30:31], off offset:3584
	v_lshl_add_u64 v[30:31], v[6:7], 0, s[4:5]
	s_ashr_i32 s53, s52, 31
	global_load_dwordx2 v[108:109], v[30:31], off
	global_load_dwordx2 v[106:107], v[30:31], off offset:512
	global_load_dwordx2 v[104:105], v[30:31], off offset:1024
	global_load_dwordx2 v[102:103], v[30:31], off offset:1536
	global_load_dwordx2 v[100:101], v[30:31], off offset:2048
	global_load_dwordx2 v[98:99], v[30:31], off offset:2560
	global_load_dwordx2 v[96:97], v[30:31], off offset:3072
	global_load_dwordx2 v[94:95], v[30:31], off offset:3584
	v_lshl_add_u64 v[30:31], v[4:5], 0, s[28:29]
	s_lshl_b64 s[52:53], s[52:53], 12
	global_load_dwordx2 v[92:93], v[30:31], off
	global_load_dwordx2 v[90:91], v[30:31], off offset:512
	global_load_dwordx2 v[88:89], v[30:31], off offset:1024
	global_load_dwordx2 v[86:87], v[30:31], off offset:1536
	global_load_dwordx2 v[84:85], v[30:31], off offset:2048
	global_load_dwordx2 v[82:83], v[30:31], off offset:2560
	global_load_dwordx2 v[80:81], v[30:31], off offset:3072
	global_load_dwordx2 v[78:79], v[30:31], off offset:3584
	v_lshl_add_u64 v[30:31], v[6:7], 0, s[28:29]
	global_load_dwordx2 v[76:77], v[30:31], off
	global_load_dwordx2 v[74:75], v[30:31], off offset:512
	global_load_dwordx2 v[72:73], v[30:31], off offset:1024
	global_load_dwordx2 v[70:71], v[30:31], off offset:1536
	global_load_dwordx2 v[68:69], v[30:31], off offset:2048
	global_load_dwordx2 v[66:67], v[30:31], off offset:2560
	global_load_dwordx2 v[64:65], v[30:31], off offset:3072
	global_load_dwordx2 v[62:63], v[30:31], off offset:3584
	v_lshl_add_u64 v[30:31], v[4:5], 0, s[52:53]
	global_load_dwordx2 v[60:61], v[30:31], off
	global_load_dwordx2 v[58:59], v[30:31], off offset:512
	global_load_dwordx2 v[56:57], v[30:31], off offset:1024
	global_load_dwordx2 v[54:55], v[30:31], off offset:1536
	global_load_dwordx2 v[52:53], v[30:31], off offset:2048
	global_load_dwordx2 v[50:51], v[30:31], off offset:2560
	global_load_dwordx2 v[48:49], v[30:31], off offset:3072
	global_load_dwordx2 v[46:47], v[30:31], off offset:3584
	v_lshl_add_u64 v[30:31], v[6:7], 0, s[52:53]
	global_load_dwordx2 v[44:45], v[30:31], off
	global_load_dwordx2 v[42:43], v[30:31], off offset:512
	global_load_dwordx2 v[40:41], v[30:31], off offset:1024
	global_load_dwordx2 v[38:39], v[30:31], off offset:1536
	global_load_dwordx2 v[36:37], v[30:31], off offset:2048
	global_load_dwordx2 v[34:35], v[30:31], off offset:2560
	global_load_dwordx2 v[32:33], v[30:31], off offset:3072
	s_nop 0
	global_load_dwordx2 v[30:31], v[30:31], off offset:3584
	s_cmpk_gt_i32 s86, 0x3fff
	s_waitcnt vmcnt(62)
	v_lshlrev_b32_e32 v132, 16, v0
	v_and_b32_e32 v133, 0xffff0000, v0
	v_lshlrev_b32_e32 v130, 16, v1
	s_waitcnt vmcnt(60)
	v_lshlrev_b32_e32 v142, 16, v144
	v_and_b32_e32 v143, 0xffff0000, v144
	v_and_b32_e32 v131, 0xffff0000, v1
	v_lshlrev_b32_e32 v136, 16, v2
	s_waitcnt vmcnt(55)
	v_and_b32_e32 v197, 0xffff0000, v175
	v_lshlrev_b32_e32 v196, 16, v175
	v_mul_f32_e32 v144, v197, v197
	s_waitcnt vmcnt(54)
	v_and_b32_e32 v193, 0xffff0000, v177
	v_and_b32_e32 v192, 0xffff0000, v176
	v_and_b32_e32 v137, 0xffff0000, v2
	v_lshlrev_b32_e32 v134, 16, v3
	v_and_b32_e32 v135, 0xffff0000, v3
	v_lshlrev_b32_e32 v154, 16, v145
	v_and_b32_e32 v155, 0xffff0000, v145
	v_lshlrev_b32_e32 v0, 16, v156
	v_and_b32_e32 v1, 0xffff0000, v156
	v_lshlrev_b32_e32 v2, 16, v157
	v_and_b32_e32 v3, 0xffff0000, v157
	v_and_b32_e32 v195, 0xffff0000, v174
	v_pk_fma_f32 v[156:157], v[196:197], v[196:197], v[144:145] op_sel_hi:[1,1,0]
	v_lshlrev_b32_e32 v191, 16, v177
	v_lshlrev_b32_e32 v190, 16, v176
	v_pk_mul_f32 v[144:145], v[192:193], v[192:193]
	v_lshlrev_b32_e32 v194, 16, v174
	v_pk_fma_f32 v[174:175], v[190:191], v[190:191], v[144:145]
	s_waitcnt vmcnt(52)
; __device__ __forceinline__ float wave_sum(float v) {
; #pragma unroll
;     for (int o = 1; o < 64; o <<= 1) v += __shfl_xor(v, o);
;     return v;
; }
; template <bool XIN_BF, bool XOUT_BF>
; __device__ __forceinline__ void ew_rows(const void* xsrc, void* xdst, const bf16* y, float scale, const float* gpost, const float* gpre, bf16* hout, int gw, int ngw, int lane) {
;     ...
;             if (y) {
;                 f32x4 yv[8]; float ss = 0.f;
; #pragma unroll
;                 for (int j = 0; j < 8; ++j) { const v2u w = yb[r][j]; yv[j] = (f32x4){__uint_as_float(w.x << 16), __uint_as_float(w.x & 0xffff0000u), __uint_as_float(w.y << 16), __uint_as_float(w.y & 0xffff0000u)};
;                     ss += (yv[j].x * yv[j].x + yv[j].y * yv[j].y) + (yv[j].z * yv[j].z + yv[j].w * yv[j].w); }
;                 const float rs = rsqrtf(wave_sum(ss) * (1.0f / DM) + 1e-6f) * scale;
; #pragma unroll
;                 for (int j = 0; j < 8; ++j) { const f32x4 g = ((const f32x4*)gpost)[lane + 64 * j]; xv[j] = xv[j] + yv[j] * g * rs; }
	v_and_b32_e32 v145, 0xffff0000, v180
	v_mul_f32_e32 v144, v195, v195
	v_lshlrev_b32_e32 v183, 16, v180
	v_pk_fma_f32 v[176:177], v[194:195], v[194:195], v[144:145] op_sel_hi:[1,1,0]
	v_lshlrev_b32_e32 v186, 16, v178
	v_and_b32_e32 v187, 0xffff0000, v178
	v_lshlrev_b32_e32 v188, 16, v179
	v_and_b32_e32 v189, 0xffff0000, v179
	v_mov_b32_e32 v182, v176
	v_mov_b32_e32 v178, v156
	v_mov_b32_e32 v179, v183
	v_mul_f32_e32 v180, v145, v145
	v_pk_add_f32 v[156:157], v[176:177], v[156:157]
	v_pk_mul_f32 v[176:177], v[182:183], v[178:179]
	v_pk_add_f32 v[174:175], v[174:175], v[174:175] op_sel:[0,1] op_sel_hi:[1,0]
	v_mov_b32_e32 v157, v177
	v_mov_b32_e32 v175, v180
	v_mul_f32_e32 v144, v187, v187
	v_lshlrev_b32_e32 v184, 16, v181
	v_and_b32_e32 v185, 0xffff0000, v181
	v_pk_add_f32 v[156:157], v[156:157], v[174:175]
	v_pk_fma_f32 v[174:175], v[186:187], v[186:187], v[144:145] op_sel_hi:[1,1,0]
	v_mul_f32_e32 v144, v189, v189
	v_mul_f32_e32 v181, v184, v184
	v_mul_f32_e32 v198, v185, v185
	v_pk_fma_f32 v[176:177], v[188:189], v[188:189], v[144:145] op_sel_hi:[1,1,0]
	v_mov_b32_e32 v175, v181
	v_mov_b32_e32 v177, v198
	v_pk_add_f32 v[174:175], v[174:175], v[176:177]
	s_waitcnt vmcnt(51)
	v_and_b32_e32 v181, 0xffff0000, v173
	v_and_b32_e32 v180, 0xffff0000, v172
	v_pk_add_f32 v[198:199], v[156:157], v[174:175]
	v_lshlrev_b32_e32 v157, 16, v173
	v_lshlrev_b32_e32 v156, 16, v172
	v_pk_mul_f32 v[172:173], v[180:181], v[180:181]
	s_waitcnt vmcnt(50)
	v_and_b32_e32 v179, 0xffff0000, v171
	v_and_b32_e32 v178, 0xffff0000, v170
	v_pk_fma_f32 v[172:173], v[156:157], v[156:157], v[172:173]
	v_lshlrev_b32_e32 v177, 16, v171
	v_lshlrev_b32_e32 v176, 16, v170
	v_pk_mul_f32 v[170:171], v[178:179], v[178:179]
	v_pk_add_f32 v[200:201], v[172:173], v[172:173] op_sel:[0,1] op_sel_hi:[1,0]
	v_pk_fma_f32 v[222:223], v[176:177], v[176:177], v[170:171]
	s_waitcnt vmcnt(48)
	v_lshlrev_b32_e32 v171, 16, v166
	v_pk_add_f32 v[198:199], v[198:199], v[198:199] op_sel:[0,1] op_sel_hi:[1,0]
	v_mov_b32_e32 v224, v200
	v_mov_b32_e32 v170, v198
	v_mov_b32_e32 v225, v171
	v_pk_add_f32 v[198:199], v[198:199], v[200:201]
	v_pk_mul_f32 v[200:201], v[170:171], v[224:225]
	ds_read_b128 v[224:227], v253
	v_lshlrev_b32_e32 v174, 16, v169
	v_and_b32_e32 v175, 0xffff0000, v169
	v_and_b32_e32 v169, 0xffff0000, v166
	v_and_b32_e32 v173, 0xffff0000, v168
	v_mul_f32_e32 v144, v169, v169
	v_mov_b32_e32 v199, v201
	v_pk_add_f32 v[200:201], v[222:223], v[222:223] op_sel:[0,1] op_sel_hi:[1,0]
	v_lshlrev_b32_e32 v172, 16, v168
	v_lshlrev_b32_e32 v166, 16, v167
	v_mov_b32_e32 v201, v144
	v_mul_f32_e32 v144, v173, v173
	v_and_b32_e32 v167, 0xffff0000, v167
	v_mul_f32_e32 v168, v166, v166
	v_pk_add_f32 v[198:199], v[198:199], v[200:201]
	v_pk_fma_f32 v[200:201], v[172:173], v[172:173], v[144:145] op_sel_hi:[1,1,0]
	v_mul_f32_e32 v144, v175, v175
	v_mul_f32_e32 v182, v167, v167
	v_mov_b32_e32 v201, v168
	v_pk_fma_f32 v[222:223], v[174:175], v[174:175], v[144:145] op_sel_hi:[1,1,0]
	v_and_b32_e32 v168, 64, v210
	v_mov_b32_e32 v223, v182
	v_add_u32_e32 v168, 64, v168
	v_xor_b32_e32 v170, 1, v210
	v_pk_add_f32 v[200:201], v[200:201], v[222:223]
	v_cmp_lt_i32_e32 vcc, v170, v168
	v_pk_add_f32 v[198:199], v[198:199], v[200:201]
	v_lshlrev_b32_e32 v140, 16, v138
	v_cndmask_b32_e32 v170, v210, v170, vcc
	v_add_f32_e32 v144, v198, v199
	v_lshlrev_b32_e32 v182, 2, v170
	ds_bpermute_b32 v170, v182, v144
	v_and_b32_e32 v141, 0xffff0000, v138
	v_lshlrev_b32_e32 v138, 16, v139
	v_and_b32_e32 v139, 0xffff0000, v139
	v_lshlrev_b32_e32 v150, 16, v146
	s_waitcnt lgkmcnt(0)
	v_add_f32_e32 v144, v144, v170
	v_xor_b32_e32 v170, 2, v210
	v_cmp_lt_i32_e32 vcc, v170, v168
	v_and_b32_e32 v151, 0xffff0000, v146
	v_lshlrev_b32_e32 v152, 16, v147
	v_cndmask_b32_e32 v170, v210, v170, vcc
	v_lshlrev_b32_e32 v198, 2, v170
	ds_bpermute_b32 v170, v198, v144
	v_and_b32_e32 v153, 0xffff0000, v147
	v_lshlrev_b32_e32 v146, 16, v148
	v_and_b32_e32 v147, 0xffff0000, v148
	v_lshlrev_b32_e32 v148, 16, v149
	s_waitcnt lgkmcnt(0)
	v_add_f32_e32 v144, v144, v170
	v_xor_b32_e32 v170, 4, v210
	v_cmp_lt_i32_e32 vcc, v170, v168
	v_and_b32_e32 v149, 0xffff0000, v149
	v_lshlrev_b32_e32 v158, 16, v164
	v_cndmask_b32_e32 v170, v210, v170, vcc
	v_lshlrev_b32_e32 v199, 2, v170
	ds_bpermute_b32 v170, v199, v144
	v_and_b32_e32 v159, 0xffff0000, v164
	v_lshlrev_b32_e32 v164, 16, v165
	v_and_b32_e32 v165, 0xffff0000, v165
	s_waitcnt lgkmcnt(0)
	v_add_f32_e32 v144, v144, v170
	v_xor_b32_e32 v170, 8, v210
	v_cmp_lt_i32_e32 vcc, v170, v168
	s_waitcnt vmcnt(0) lgkmcnt(0)
	v_pk_mul_f32 v[194:195], v[224:225], v[194:195]
	v_cndmask_b32_e32 v170, v210, v170, vcc
	v_lshlrev_b32_e32 v200, 2, v170
	ds_bpermute_b32 v170, v200, v144
	v_pk_mul_f32 v[196:197], v[226:227], v[196:197]
	v_mov_b32_e32 v225, v192
	v_mov_b32_e32 v192, v191
	v_mov_b32_e32 v224, v190
	s_waitcnt lgkmcnt(0)
	v_add_f32_e32 v144, v144, v170
	v_xor_b32_e32 v170, 16, v210
	v_cmp_lt_i32_e32 vcc, v170, v168
	s_nop 1
	v_cndmask_b32_e32 v170, v210, v170, vcc
	v_lshlrev_b32_e32 v201, 2, v170
	ds_bpermute_b32 v170, v201, v144
	s_waitcnt lgkmcnt(0)
	v_add_f32_e32 v144, v144, v170
	v_xor_b32_e32 v170, 32, v210
	v_cmp_lt_i32_e32 vcc, v170, v168
	s_nop 1
	v_cndmask_b32_e32 v168, v210, v170, vcc
	v_lshlrev_b32_e32 v222, 2, v168
	ds_bpermute_b32 v168, v222, v144
	s_waitcnt lgkmcnt(0)
	v_add_f32_e32 v144, v144, v168
	v_fmamk_f32 v144, v144, 0x3a000000, v204
	v_cmp_gt_f32_e32 vcc, s34, v144
	v_mul_f32_e32 v168, 0x4b800000, v144
	s_nop 0
	v_cndmask_b32_e32 v144, v144, v168, vcc
	v_rsq_f32_e32 v144, v144
	s_nop 0
	v_mul_f32_e32 v168, 0x45800000, v144
	v_cndmask_b32_e32 v144, v144, v168, vcc
	v_mul_f32_e32 v170, v163, v144
	v_pk_fma_f32 v[130:131], v[196:197], v[170:171], v[130:131] op_sel_hi:[1,0,1]
	v_pk_fma_f32 v[132:133], v[194:195], v[170:171], v[132:133] op_sel_hi:[1,0,1]
	ds_read_b128 v[194:197], v253 offset:1024
	v_mov_b32_e32 v144, v183
	v_mov_b32_e32 v168, v171
	s_waitcnt lgkmcnt(0)
; __device__ __forceinline__ unsigned pk2(float lo, float hi) { const f32x2 v = {lo, hi}; const bf16x2_cv b = __builtin_convertvector(v, bf16x2_cv); return __builtin_bit_cast(unsigned, b); }
; __device__ __forceinline__ unsigned pk2(float lo, float hi) { return f2bf(lo) | (f2bf(hi) << 16); }
; template <bool XIN_BF, bool XOUT_BF>
; __device__ __forceinline__ void ew_rows(const void* xsrc, void* xdst, const bf16* y, float scale, const float* gpost, const float* gpre, bf16* hout, int gw, int ngw, int lane) {
;     ...
;                 for (int j = 0; j < 8; ++j) { const f32x4 g = ((const f32x4*)gpost)[lane + 64 * j]; xv[j] = xv[j] + yv[j] * g * rs; }
;                 if (XOUT_BF) { v2u* xo = (v2u*)((bf16*)xdst + (size_t)row * DM) + lane;
; #pragma unroll
;                     for (int j = 0; j < 8; ++j) xo[64 * j] = (v2u){pk2(xv[j].x, xv[j].y), pk2(xv[j].z, xv[j].w)};
	v_pk_mul_f32 v[190:191], v[196:197], v[192:193]
	s_nop 0
	v_pk_fma_f32 v[134:135], v[190:191], v[170:171], v[134:135] op_sel_hi:[1,0,1]
	ds_read_b128 v[190:193], v253 offset:2048
	v_pk_mul_f32 v[194:195], v[194:195], v[224:225]
	s_waitcnt lgkmcnt(0)
	v_pk_mul_f32 v[186:187], v[190:191], v[186:187]
	v_pk_mul_f32 v[188:189], v[192:193], v[188:189]
	v_pk_fma_f32 v[140:141], v[186:187], v[170:171], v[140:141] op_sel_hi:[1,0,1]
	v_pk_fma_f32 v[138:139], v[188:189], v[170:171], v[138:139] op_sel_hi:[1,0,1]
	ds_read_b128 v[186:189], v253 offset:3072
	v_pk_fma_f32 v[136:137], v[194:195], v[170:171], v[136:137] op_sel_hi:[1,0,1]
	s_waitcnt lgkmcnt(0)
	v_pk_mul_f32 v[184:185], v[184:185], v[188:189]
	v_pk_mul_f32 v[144:145], v[144:145], v[186:187]
	s_nop 0
	v_pk_fma_f32 v[144:145], v[144:145], v[170:171], v[142:143] op_sel_hi:[1,0,1]
	v_pk_fma_f32 v[142:143], v[184:185], v[170:171], v[154:155] op_sel_hi:[1,0,1]
	ds_read_b128 v[184:187], v253 offset:4096
	v_mov_b32_e32 v154, v156
	v_mov_b32_e32 v155, v180
	v_mov_b32_e32 v180, v157
	s_waitcnt lgkmcnt(0)
	v_pk_mul_f32 v[184:185], v[184:185], v[154:155]
	v_pk_mul_f32 v[154:155], v[186:187], v[180:181]
	v_pk_fma_f32 v[156:157], v[184:185], v[170:171], v[150:151] op_sel_hi:[1,0,1]
	v_pk_fma_f32 v[154:155], v[154:155], v[170:171], v[152:153] op_sel_hi:[1,0,1]
	ds_read_b128 v[150:153], v253 offset:5120
	v_mov_b32_e32 v180, v177
	v_mov_b32_e32 v181, v179
	v_mov_b32_e32 v177, v178
	s_waitcnt lgkmcnt(0)
	v_pk_mul_f32 v[180:181], v[152:153], v[180:181]
	v_pk_mul_f32 v[150:151], v[150:151], v[176:177]
	s_nop 0
	v_pk_fma_f32 v[152:153], v[150:151], v[170:171], v[146:147] op_sel_hi:[1,0,1]
	v_pk_fma_f32 v[150:151], v[180:181], v[170:171], v[148:149] op_sel_hi:[1,0,1]
	ds_read_b128 v[146:149], v253 offset:6144
	s_waitcnt lgkmcnt(0)
	v_pk_mul_f32 v[174:175], v[148:149], v[174:175]
	v_pk_mul_f32 v[146:147], v[146:147], v[172:173]
	s_nop 0
	v_pk_fma_f32 v[148:149], v[146:147], v[170:171], v[0:1] op_sel_hi:[1,0,1]
	v_pk_fma_f32 v[146:147], v[174:175], v[170:171], v[2:3] op_sel_hi:[1,0,1]
	ds_read_b128 v[0:3], v253 offset:7168
	s_waitcnt lgkmcnt(0)
	v_pk_mul_f32 v[168:169], v[168:169], v[0:1]
	v_pk_mul_f32 v[0:1], v[166:167], v[2:3]
	v_pk_fma_f32 v[2:3], v[168:169], v[170:171], v[158:159] op_sel_hi:[1,0,1]
	v_bfe_u32 v158, v132, 16, 1
	v_add3_u32 v158, v132, v158, s46
	v_bfe_u32 v159, v133, 16, 1
	v_lshrrev_b32_e32 v158, 16, v158
	v_add3_u32 v159, v133, v159, s46
	v_and_or_b32 v158, v159, s33, v158
	v_bfe_u32 v159, v130, 16, 1
	v_pk_fma_f32 v[0:1], v[0:1], v[170:171], v[164:165] op_sel_hi:[1,0,1]
	v_add3_u32 v159, v130, v159, s46
	v_bfe_u32 v164, v131, 16, 1
	v_lshrrev_b32_e32 v159, 16, v159
	v_add3_u32 v164, v131, v164, s46
	v_and_or_b32 v159, v164, s33, v159
	global_store_dwordx2 v[128:129], v[158:159], off
	v_bfe_u32 v158, v136, 16, 1
	v_add3_u32 v158, v136, v158, s46
	v_bfe_u32 v159, v137, 16, 1
	v_lshrrev_b32_e32 v158, 16, v158
	v_add3_u32 v159, v137, v159, s46
	v_and_or_b32 v158, v159, s33, v158
	v_bfe_u32 v159, v134, 16, 1
	v_add3_u32 v159, v134, v159, s46
	v_bfe_u32 v164, v135, 16, 1
	v_lshrrev_b32_e32 v159, 16, v159
	v_add3_u32 v164, v135, v164, s46
	v_and_or_b32 v159, v164, s33, v159
	global_store_dwordx2 v[128:129], v[158:159], off offset:512
	v_bfe_u32 v158, v140, 16, 1
	v_add3_u32 v158, v140, v158, s46
	v_bfe_u32 v159, v141, 16, 1
	v_lshrrev_b32_e32 v158, 16, v158
	v_add3_u32 v159, v141, v159, s46
	v_and_or_b32 v158, v159, s33, v158
	v_bfe_u32 v159, v138, 16, 1
	v_add3_u32 v159, v138, v159, s46
	v_bfe_u32 v164, v139, 16, 1
	v_lshrrev_b32_e32 v159, 16, v159
	v_add3_u32 v164, v139, v164, s46
	v_and_or_b32 v159, v164, s33, v159
	global_store_dwordx2 v[128:129], v[158:159], off offset:1024
	v_bfe_u32 v158, v144, 16, 1
	v_add3_u32 v158, v144, v158, s46
	v_bfe_u32 v159, v145, 16, 1
	v_lshrrev_b32_e32 v158, 16, v158
	v_add3_u32 v159, v145, v159, s46
	v_and_or_b32 v158, v159, s33, v158
	v_bfe_u32 v159, v142, 16, 1
	v_add3_u32 v159, v142, v159, s46
	v_bfe_u32 v164, v143, 16, 1
	v_lshrrev_b32_e32 v159, 16, v159
	v_add3_u32 v164, v143, v164, s46
	v_and_or_b32 v159, v164, s33, v159
	global_store_dwordx2 v[128:129], v[158:159], off offset:1536
	v_bfe_u32 v158, v156, 16, 1
	v_add3_u32 v158, v156, v158, s46
	v_bfe_u32 v159, v157, 16, 1
	v_lshrrev_b32_e32 v158, 16, v158
	v_add3_u32 v159, v157, v159, s46
	v_and_or_b32 v158, v159, s33, v158
	v_bfe_u32 v159, v154, 16, 1
	v_add3_u32 v159, v154, v159, s46
	v_bfe_u32 v164, v155, 16, 1
	v_lshrrev_b32_e32 v159, 16, v159
	v_add3_u32 v164, v155, v164, s46
	v_and_or_b32 v159, v164, s33, v159
	global_store_dwordx2 v[128:129], v[158:159], off offset:2048
	v_bfe_u32 v158, v152, 16, 1
	v_add3_u32 v158, v152, v158, s46
	v_bfe_u32 v159, v153, 16, 1
	v_lshrrev_b32_e32 v158, 16, v158
	v_add3_u32 v159, v153, v159, s46
	v_and_or_b32 v158, v159, s33, v158
	v_bfe_u32 v159, v150, 16, 1
	v_add3_u32 v159, v150, v159, s46
	v_bfe_u32 v164, v151, 16, 1
	v_lshrrev_b32_e32 v159, 16, v159
	v_add3_u32 v164, v151, v164, s46
	v_and_or_b32 v159, v164, s33, v159
	global_store_dwordx2 v[128:129], v[158:159], off offset:2560
	v_bfe_u32 v158, v148, 16, 1
	v_add3_u32 v158, v148, v158, s46
	v_bfe_u32 v159, v149, 16, 1
	v_lshrrev_b32_e32 v158, 16, v158
	v_add3_u32 v159, v149, v159, s46
	v_and_or_b32 v158, v159, s33, v158
	v_bfe_u32 v159, v146, 16, 1
	v_add3_u32 v159, v146, v159, s46
	v_bfe_u32 v164, v147, 16, 1
	v_lshrrev_b32_e32 v159, 16, v159
	v_add3_u32 v164, v147, v164, s46
	v_and_or_b32 v159, v164, s33, v159
	global_store_dwordx2 v[128:129], v[158:159], off offset:3072
	v_bfe_u32 v158, v2, 16, 1
	v_add3_u32 v158, v2, v158, s46
	v_bfe_u32 v159, v3, 16, 1
	v_lshrrev_b32_e32 v158, 16, v158
	v_add3_u32 v159, v3, v159, s46
; __device__ __forceinline__ unsigned pk2(float lo, float hi) { const f32x2 v = {lo, hi}; const bf16x2_cv b = __builtin_convertvector(v, bf16x2_cv); return __builtin_bit_cast(unsigned, b); }
; __device__ __forceinline__ unsigned pk2(float lo, float hi) { return f2bf(lo) | (f2bf(hi) << 16); }
; template <bool XIN_BF, bool XOUT_BF>
; __device__ __forceinline__ void ew_rows(const void* xsrc, void* xdst, const bf16* y, float scale, const float* gpost, const float* gpre, bf16* hout, int gw, int ngw, int lane) {
;     ...
;                     for (int j = 0; j < 8; ++j) xo[64 * j] = (v2u){pk2(xv[j].x, xv[j].y), pk2(xv[j].z, xv[j].w)};
;                 } else { f32x4* xo = (f32x4*)((float*)xdst + (size_t)row * DM) + lane;
; #pragma unroll
;                     for (int j = 0; j < 8; ++j) xo[64 * j] = xv[j]; }
;             }
;             if (hout) {
;                 float s2 = 0.f;
; #pragma unroll
;                 for (int j = 0; j < 8; ++j) s2 += (xv[j].x * xv[j].x + xv[j].y * xv[j].y) + (xv[j].z * xv[j].z + xv[j].w * xv[j].w);
;                 const float rs2 = rsqrtf(wave_sum(s2) * (1.0f / DM) + 1e-6f);
;                 v2u* ho = (v2u*)(hout + (size_t)row * DM) + lane;
; #pragma unroll
;                 for (int j = 0; j < 8; ++j) { const f32x4 g = ((const f32x4*)gpre)[lane + 64 * j]; const f32x4 t = xv[j] * g * rs2; ho[64 * j] = (v2u){pk2(t.x, t.y), pk2(t.z, t.w)}; }
	v_and_or_b32 v158, v159, s33, v158
	v_bfe_u32 v159, v0, 16, 1
	v_add3_u32 v159, v0, v159, s46
	v_bfe_u32 v164, v1, 16, 1
	v_lshrrev_b32_e32 v159, 16, v159
	v_add3_u32 v164, v1, v164, s46
	v_and_or_b32 v159, v164, s33, v159
	global_store_dwordx2 v[128:129], v[158:159], off offset:3584
	v_mov_b32_e32 v158, v133
	v_mov_b32_e32 v159, v137
	v_mov_b32_e32 v128, v132
	v_mov_b32_e32 v129, v136
	v_pk_mul_f32 v[158:159], v[158:159], v[158:159]
	v_mov_b32_e32 v164, v131
	v_mov_b32_e32 v165, v135
	v_pk_fma_f32 v[128:129], v[128:129], v[128:129], v[158:159]
	v_mov_b32_e32 v158, v130
	v_mov_b32_e32 v159, v134
	v_pk_mul_f32 v[164:165], v[164:165], v[164:165]
	s_nop 0
	v_pk_fma_f32 v[158:159], v[158:159], v[158:159], v[164:165]
	v_pk_mul_f32 v[164:165], v[140:141], v[140:141]
	v_pk_add_f32 v[128:129], v[128:129], v[158:159]
	v_pk_mul_f32 v[158:159], v[138:139], v[138:139]
	v_pk_add_f32 v[128:129], v[128:129], v[128:129] op_sel_hi:[0,1]
	v_pk_mov_b32 v[166:167], v[164:165], v[158:159] op_sel:[1,0]
	v_mov_b32_e32 v165, v159
	v_mul_f32_e32 v128, v144, v144
	v_pk_add_f32 v[158:159], v[166:167], v[164:165]
	v_pk_fma_f32 v[164:165], v[144:145], v[144:145], v[128:129] op_sel_hi:[1,1,0]
	v_mul_f32_e32 v128, v142, v142
	v_pk_add_f32 v[158:159], v[158:159], v[158:159] op_sel_hi:[0,1]
	v_pk_fma_f32 v[166:167], v[142:143], v[142:143], v[128:129] op_sel_hi:[1,1,0]
	v_mul_f32_e32 v164, v156, v156
	v_mul_f32_e32 v166, v157, v157
	v_mul_f32_e32 v158, v154, v154
	v_mul_f32_e32 v128, v155, v155
	v_pk_add_f32 v[164:165], v[164:165], v[166:167]
	v_pk_add_f32 v[128:129], v[158:159], v[128:129]
	v_pk_mul_f32 v[158:159], v[150:151], v[150:151]
	v_pk_add_f32 v[128:129], v[164:165], v[128:129]
	v_pk_mul_f32 v[164:165], v[152:153], v[152:153]
	v_pk_add_f32 v[128:129], v[128:129], v[128:129] op_sel_hi:[0,1]
	v_pk_mov_b32 v[166:167], v[164:165], v[158:159] op_sel:[1,0]
	v_mov_b32_e32 v165, v159
	v_mul_f32_e32 v128, v148, v148
	v_pk_add_f32 v[158:159], v[166:167], v[164:165]
	v_pk_fma_f32 v[164:165], v[148:149], v[148:149], v[128:129] op_sel_hi:[1,1,0]
	v_mul_f32_e32 v128, v146, v146
	v_pk_add_f32 v[158:159], v[158:159], v[158:159] op_sel_hi:[0,1]
	v_pk_fma_f32 v[166:167], v[146:147], v[146:147], v[128:129] op_sel_hi:[1,1,0]
	v_mul_f32_e32 v164, v2, v2
	v_mul_f32_e32 v166, v3, v3
	v_mul_f32_e32 v158, v0, v0
	v_mul_f32_e32 v128, v1, v1
	v_pk_add_f32 v[164:165], v[164:165], v[166:167]
	v_pk_add_f32 v[128:129], v[158:159], v[128:129]
	s_nop 0
	v_pk_add_f32 v[128:129], v[164:165], v[128:129]
	ds_read_b128 v[164:167], v253 offset:8192
	v_add_f32_e32 v128, v128, v129
	ds_bpermute_b32 v129, v182, v128
	s_waitcnt lgkmcnt(0)
	v_add_f32_e32 v128, v128, v129
	ds_bpermute_b32 v129, v198, v128
	s_waitcnt lgkmcnt(0)
	v_add_f32_e32 v128, v128, v129
	ds_bpermute_b32 v129, v199, v128
	s_waitcnt lgkmcnt(0)
	v_add_f32_e32 v128, v128, v129
	ds_bpermute_b32 v129, v200, v128
	s_waitcnt lgkmcnt(0)
	v_add_f32_e32 v128, v128, v129
	ds_bpermute_b32 v129, v201, v128
	s_waitcnt lgkmcnt(0)
	v_add_f32_e32 v128, v128, v129
	ds_bpermute_b32 v129, v222, v128
	s_waitcnt lgkmcnt(0)
	v_add_f32_e32 v128, v128, v129
	v_fmamk_f32 v128, v128, 0x3a000000, v204
	v_cmp_gt_f32_e32 vcc, s34, v128
	v_mul_f32_e32 v129, 0x4b800000, v128
	s_waitcnt lgkmcnt(0)
	v_pk_mul_f32 v[132:133], v[132:133], v[164:165]
	v_cndmask_b32_e32 v128, v128, v129, vcc
	v_rsq_f32_e32 v128, v128
	v_pk_mul_f32 v[130:131], v[130:131], v[166:167]
	v_mul_f32_e32 v129, 0x45800000, v128
	v_cndmask_b32_e32 v128, v128, v129, vcc
	v_pk_mul_f32 v[132:133], v[132:133], v[128:129] op_sel_hi:[1,0]
	v_pk_mul_f32 v[130:131], v[130:131], v[128:129] op_sel_hi:[1,0]
	v_bfe_u32 v129, v132, 16, 1
	v_add3_u32 v129, v132, v129, s46
	v_bfe_u32 v132, v133, 16, 1
	v_lshrrev_b32_e32 v129, 16, v129
	v_add3_u32 v132, v133, v132, s46
	v_and_or_b32 v132, v132, s33, v129
	v_bfe_u32 v129, v130, 16, 1
	v_add3_u32 v129, v130, v129, s46
	v_bfe_u32 v130, v131, 16, 1
	v_lshrrev_b32_e32 v129, 16, v129
	v_add3_u32 v130, v131, v130, s46
	v_add_co_u32_e32 v126, vcc, s20, v126
	v_and_or_b32 v133, v130, s33, v129
	s_nop 0
	v_addc_co_u32_e32 v127, vcc, 0, v127, vcc
	global_store_dwordx2 v[126:127], v[132:133], off
	ds_read_b128 v[130:133], v253 offset:9216
	s_waitcnt lgkmcnt(0)
	v_pk_mul_f32 v[130:131], v[136:137], v[130:131]
	v_pk_mul_f32 v[132:133], v[134:135], v[132:133]
	v_pk_mul_f32 v[130:131], v[130:131], v[128:129] op_sel_hi:[1,0]
	v_pk_mul_f32 v[132:133], v[132:133], v[128:129] op_sel_hi:[1,0]
	v_bfe_u32 v129, v130, 16, 1
	v_add3_u32 v129, v130, v129, s46
	v_bfe_u32 v130, v131, 16, 1
	v_lshrrev_b32_e32 v129, 16, v129
	v_add3_u32 v130, v131, v130, s46
	v_and_or_b32 v130, v130, s33, v129
	v_bfe_u32 v129, v132, 16, 1
	v_add3_u32 v129, v132, v129, s46
	v_bfe_u32 v131, v133, 16, 1
	v_lshrrev_b32_e32 v129, 16, v129
	v_add3_u32 v131, v133, v131, s46
	v_and_or_b32 v131, v131, s33, v129
	global_store_dwordx2 v[126:127], v[130:131], off offset:512
	ds_read_b128 v[130:133], v253 offset:10240
	s_waitcnt lgkmcnt(0)
	v_pk_mul_f32 v[130:131], v[140:141], v[130:131]
	v_pk_mul_f32 v[132:133], v[138:139], v[132:133]
	v_pk_mul_f32 v[130:131], v[130:131], v[128:129] op_sel_hi:[1,0]
	v_pk_mul_f32 v[132:133], v[132:133], v[128:129] op_sel_hi:[1,0]
	v_bfe_u32 v129, v130, 16, 1
	v_add3_u32 v129, v130, v129, s46
	v_bfe_u32 v130, v131, 16, 1
	v_lshrrev_b32_e32 v129, 16, v129
	v_add3_u32 v130, v131, v130, s46
	v_and_or_b32 v130, v130, s33, v129
	v_bfe_u32 v129, v132, 16, 1
	v_add3_u32 v129, v132, v129, s46
	v_bfe_u32 v131, v133, 16, 1
	v_lshrrev_b32_e32 v129, 16, v129
	v_add3_u32 v131, v133, v131, s46
	v_and_or_b32 v131, v131, s33, v129
	global_store_dwordx2 v[126:127], v[130:131], off offset:1024
	ds_read_b128 v[130:133], v253 offset:11264
	s_waitcnt lgkmcnt(0)
; __device__ __forceinline__ unsigned pk2(float lo, float hi) { const f32x2 v = {lo, hi}; const bf16x2_cv b = __builtin_convertvector(v, bf16x2_cv); return __builtin_bit_cast(unsigned, b); }
; __device__ __forceinline__ unsigned pk2(float lo, float hi) { return f2bf(lo) | (f2bf(hi) << 16); }
; template <bool XIN_BF, bool XOUT_BF>
; __device__ __forceinline__ void ew_rows(const void* xsrc, void* xdst, const bf16* y, float scale, const float* gpost, const float* gpre, bf16* hout, int gw, int ngw, int lane) {
;     ...
;         for (int r = 0; r < NR; ++r) { const int row = row0 + r * ngw; if (row >= TOK) break;
;             f32x4 xv[8];
; #pragma unroll
;             for (int j = 0; j < 8; ++j) { if (XIN_BF) { const v2u w = xb[XIN_BF ? r : 0][j]; xv[j] = (f32x4){__uint_as_float(w.x << 16), __uint_as_float(w.x & 0xffff0000u), __uint_as_float(w.y << 16), __uint_as_float(w.y & 0xffff0000u)}; } else xv[j] = xf[XIN_BF ? 0 : r][j]; }
;             if (y) {
;                 f32x4 yv[8]; float ss = 0.f;
; #pragma unroll
;                 for (int j = 0; j < 8; ++j) { const v2u w = yb[r][j]; yv[j] = (f32x4){__uint_as_float(w.x << 16), __uint_as_float(w.x & 0xffff0000u), __uint_as_float(w.y << 16), __uint_as_float(w.y & 0xffff0000u)};
;                     ss += (yv[j].x * yv[j].x + yv[j].y * yv[j].y) + (yv[j].z * yv[j].z + yv[j].w * yv[j].w); }
;     ...
;                 for (int j = 0; j < 8; ++j) { const f32x4 g = ((const f32x4*)gpre)[lane + 64 * j]; const f32x4 t = xv[j] * g * rs2; ho[64 * j] = (v2u){pk2(t.x, t.y), pk2(t.z, t.w)}; }
	v_pk_mul_f32 v[130:131], v[144:145], v[130:131]
	v_pk_mul_f32 v[132:133], v[142:143], v[132:133]
	v_pk_mul_f32 v[130:131], v[130:131], v[128:129] op_sel_hi:[1,0]
	v_pk_mul_f32 v[132:133], v[132:133], v[128:129] op_sel_hi:[1,0]
	v_bfe_u32 v129, v130, 16, 1
	v_add3_u32 v129, v130, v129, s46
	v_bfe_u32 v130, v131, 16, 1
	v_lshrrev_b32_e32 v129, 16, v129
	v_add3_u32 v130, v131, v130, s46
	v_and_or_b32 v130, v130, s33, v129
	v_bfe_u32 v129, v132, 16, 1
	v_add3_u32 v129, v132, v129, s46
	v_bfe_u32 v131, v133, 16, 1
	v_lshrrev_b32_e32 v129, 16, v129
	v_add3_u32 v131, v133, v131, s46
	v_and_or_b32 v131, v131, s33, v129
	global_store_dwordx2 v[126:127], v[130:131], off offset:1536
	ds_read_b128 v[130:133], v253 offset:12288
	s_waitcnt lgkmcnt(0)
	v_pk_mul_f32 v[130:131], v[156:157], v[130:131]
	v_pk_mul_f32 v[132:133], v[154:155], v[132:133]
	v_pk_mul_f32 v[130:131], v[130:131], v[128:129] op_sel_hi:[1,0]
	v_pk_mul_f32 v[132:133], v[132:133], v[128:129] op_sel_hi:[1,0]
	v_bfe_u32 v129, v130, 16, 1
	v_add3_u32 v129, v130, v129, s46
	v_bfe_u32 v130, v131, 16, 1
	v_lshrrev_b32_e32 v129, 16, v129
	v_add3_u32 v130, v131, v130, s46
	v_and_or_b32 v130, v130, s33, v129
	v_bfe_u32 v129, v132, 16, 1
	v_add3_u32 v129, v132, v129, s46
	v_bfe_u32 v131, v133, 16, 1
	v_lshrrev_b32_e32 v129, 16, v129
	v_add3_u32 v131, v133, v131, s46
	v_and_or_b32 v131, v131, s33, v129
	global_store_dwordx2 v[126:127], v[130:131], off offset:2048
	ds_read_b128 v[130:133], v253 offset:13312
	s_waitcnt lgkmcnt(0)
	v_pk_mul_f32 v[130:131], v[152:153], v[130:131]
	v_pk_mul_f32 v[132:133], v[150:151], v[132:133]
	v_pk_mul_f32 v[130:131], v[130:131], v[128:129] op_sel_hi:[1,0]
	v_pk_mul_f32 v[132:133], v[132:133], v[128:129] op_sel_hi:[1,0]
	v_bfe_u32 v129, v130, 16, 1
	v_add3_u32 v129, v130, v129, s46
	v_bfe_u32 v130, v131, 16, 1
	v_lshrrev_b32_e32 v129, 16, v129
	v_add3_u32 v130, v131, v130, s46
	v_and_or_b32 v130, v130, s33, v129
	v_bfe_u32 v129, v132, 16, 1
	v_add3_u32 v129, v132, v129, s46
	v_bfe_u32 v131, v133, 16, 1
	v_lshrrev_b32_e32 v129, 16, v129
	v_add3_u32 v131, v133, v131, s46
	v_and_or_b32 v131, v131, s33, v129
	global_store_dwordx2 v[126:127], v[130:131], off offset:2560
	ds_read_b128 v[130:133], v253 offset:14336
	s_waitcnt lgkmcnt(0)
	v_pk_mul_f32 v[130:131], v[148:149], v[130:131]
	v_pk_mul_f32 v[132:133], v[146:147], v[132:133]
	v_pk_mul_f32 v[130:131], v[130:131], v[128:129] op_sel_hi:[1,0]
	v_pk_mul_f32 v[132:133], v[132:133], v[128:129] op_sel_hi:[1,0]
	v_bfe_u32 v129, v130, 16, 1
	v_add3_u32 v129, v130, v129, s46
	v_bfe_u32 v130, v131, 16, 1
	v_lshrrev_b32_e32 v129, 16, v129
	v_add3_u32 v130, v131, v130, s46
	v_and_or_b32 v130, v130, s33, v129
	v_bfe_u32 v129, v132, 16, 1
	v_add3_u32 v129, v132, v129, s46
	v_bfe_u32 v131, v133, 16, 1
	v_lshrrev_b32_e32 v129, 16, v129
	v_add3_u32 v131, v133, v131, s46
	v_and_or_b32 v131, v131, s33, v129
	global_store_dwordx2 v[126:127], v[130:131], off offset:3072
	ds_read_b128 v[130:133], v253 offset:15360
	s_waitcnt lgkmcnt(0)
	v_pk_mul_f32 v[2:3], v[2:3], v[130:131]
	v_pk_mul_f32 v[0:1], v[0:1], v[132:133]
	v_pk_mul_f32 v[2:3], v[2:3], v[128:129] op_sel_hi:[1,0]
	v_pk_mul_f32 v[0:1], v[0:1], v[128:129] op_sel_hi:[1,0]
	v_bfe_u32 v128, v2, 16, 1
	v_add3_u32 v2, v2, v128, s46
	v_bfe_u32 v128, v3, 16, 1
	v_lshrrev_b32_e32 v2, 16, v2
	v_add3_u32 v3, v3, v128, s46
	v_and_or_b32 v2, v3, s33, v2
	v_bfe_u32 v3, v0, 16, 1
	v_add3_u32 v0, v0, v3, s46
	v_bfe_u32 v3, v1, 16, 1
	v_lshrrev_b32_e32 v0, 16, v0
	v_add3_u32 v1, v1, v3, s46
	v_and_or_b32 v3, v1, s33, v0
	global_store_dwordx2 v[126:127], v[2:3], off offset:3584
	s_cbranch_scc1 .LBB0_746
	v_and_b32_e32 v167, 0xffff0000, v108
	v_and_b32_e32 v169, 0xffff0000, v109
	v_lshlrev_b32_e32 v166, 16, v108
	v_lshlrev_b32_e32 v168, 16, v109
	v_mul_f32_e32 v108, v169, v169
	v_and_b32_e32 v165, 0xffff0000, v107
	v_and_b32_e32 v164, 0xffff0000, v106
	v_lshlrev_b32_e32 v155, 16, v102
	v_and_b32_e32 v153, 0xffff0000, v102
	v_mul_f32_e32 v102, v167, v167
	v_lshlrev_b32_e32 v148, 16, v124
	v_and_b32_e32 v149, 0xffff0000, v124
	v_lshlrev_b32_e32 v150, 16, v125
	v_and_b32_e32 v151, 0xffff0000, v125
	v_lshlrev_b32_e32 v142, 16, v122
	v_and_b32_e32 v143, 0xffff0000, v122
	v_lshlrev_b32_e32 v144, 16, v123
	v_and_b32_e32 v145, 0xffff0000, v123
	v_lshlrev_b32_e32 v122, 16, v110
	v_and_b32_e32 v123, 0xffff0000, v110
	v_lshlrev_b32_e32 v124, 16, v111
	v_and_b32_e32 v125, 0xffff0000, v111
	v_pk_fma_f32 v[110:111], v[168:169], v[168:169], v[108:109] op_sel_hi:[1,1,0]
	v_lshlrev_b32_e32 v159, 16, v107
	v_lshlrev_b32_e32 v158, 16, v106
	v_pk_mul_f32 v[106:107], v[164:165], v[164:165]
	v_lshlrev_b32_e32 v156, 16, v103
	v_and_b32_e32 v157, 0xffff0000, v103
	v_pk_fma_f32 v[102:103], v[166:167], v[166:167], v[102:103] op_sel_hi:[1,1,0]
	v_lshlrev_b32_e32 v0, 16, v112
	v_and_b32_e32 v1, 0xffff0000, v112
	v_lshlrev_b32_e32 v2, 16, v113
	v_and_b32_e32 v3, 0xffff0000, v113
	v_pk_fma_f32 v[112:113], v[158:159], v[158:159], v[106:107]
	v_lshlrev_b32_e32 v106, 16, v104
	v_and_b32_e32 v107, 0xffff0000, v104
	v_lshlrev_b32_e32 v108, 16, v105
	v_and_b32_e32 v109, 0xffff0000, v105
	v_mov_b32_e32 v154, v102
	v_mov_b32_e32 v104, v110
	v_mov_b32_e32 v105, v155
	v_pk_add_f32 v[102:103], v[102:103], v[110:111]
	v_pk_mul_f32 v[104:105], v[154:155], v[104:105]
	v_lshlrev_b32_e32 v132, 16, v114
	v_and_b32_e32 v133, 0xffff0000, v114
	v_mul_f32_e32 v114, v153, v153
	v_mov_b32_e32 v103, v105
	v_pk_add_f32 v[104:105], v[112:113], v[112:113] op_sel:[0,1] op_sel_hi:[1,0]
	v_mul_f32_e32 v110, v109, v109
	v_mov_b32_e32 v105, v114
	v_pk_add_f32 v[102:103], v[102:103], v[104:105]
	v_mul_f32_e32 v104, v107, v107
	v_lshlrev_b32_e32 v134, 16, v115
; template <bool XIN_BF, bool XOUT_BF>
; __device__ __forceinline__ void ew_rows(const void* xsrc, void* xdst, const bf16* y, float scale, const float* gpost, const float* gpre, bf16* hout, int gw, int ngw, int lane) {
;     ...
;                     ss += (yv[j].x * yv[j].x + yv[j].y * yv[j].y) + (yv[j].z * yv[j].z + yv[j].w * yv[j].w); }
;                 const float rs = rsqrtf(wave_sum(ss) * (1.0f / DM) + 1e-6f) * scale;
; #pragma unroll
;                 for (int j = 0; j < 8; ++j) { const f32x4 g = ((const f32x4*)gpost)[lane + 64 * j]; xv[j] = xv[j] + yv[j] * g * rs; }
	v_and_b32_e32 v135, 0xffff0000, v115
	v_mul_f32_e32 v115, v156, v156
	v_mul_f32_e32 v126, v157, v157
	v_pk_fma_f32 v[104:105], v[106:107], v[106:107], v[104:105] op_sel_hi:[1,1,0]
	v_pk_fma_f32 v[110:111], v[108:109], v[108:109], v[110:111] op_sel_hi:[1,1,0]
	v_mov_b32_e32 v105, v115
	v_mov_b32_e32 v111, v126
	v_and_b32_e32 v147, 0xffff0000, v101
	v_and_b32_e32 v146, 0xffff0000, v100
	v_pk_add_f32 v[104:105], v[104:105], v[110:111]
	v_lshlrev_b32_e32 v113, 16, v101
	v_lshlrev_b32_e32 v112, 16, v100
	v_pk_mul_f32 v[100:101], v[146:147], v[146:147]
	v_pk_add_f32 v[170:171], v[102:103], v[104:105]
	v_pk_fma_f32 v[100:101], v[112:113], v[112:113], v[100:101]
	v_and_b32_e32 v115, 0xffff0000, v99
	v_pk_add_f32 v[100:101], v[100:101], v[100:101] op_sel:[0,1] op_sel_hi:[1,0]
	v_and_b32_e32 v114, 0xffff0000, v98
	v_lshlrev_b32_e32 v131, 16, v94
	v_and_b32_e32 v129, 0xffff0000, v94
	v_lshlrev_b32_e32 v126, 16, v95
	v_and_b32_e32 v127, 0xffff0000, v95
	v_pk_add_f32 v[94:95], v[170:171], v[170:171] op_sel:[0,1] op_sel_hi:[1,0]
	v_lshlrev_b32_e32 v111, 16, v99
	v_lshlrev_b32_e32 v110, 16, v98
	v_pk_mul_f32 v[98:99], v[114:115], v[114:115]
	v_lshlrev_b32_e32 v102, 16, v96
	v_and_b32_e32 v103, 0xffff0000, v96
	v_lshlrev_b32_e32 v104, 16, v97
	v_and_b32_e32 v105, 0xffff0000, v97
	v_mov_b32_e32 v130, v94
	v_mov_b32_e32 v96, v100
	v_mov_b32_e32 v97, v131
	v_pk_fma_f32 v[98:99], v[110:111], v[110:111], v[98:99]
	v_pk_add_f32 v[94:95], v[94:95], v[100:101]
	v_pk_mul_f32 v[96:97], v[130:131], v[96:97]
	v_mul_f32_e32 v128, v129, v129
	v_mov_b32_e32 v95, v97
	v_pk_add_f32 v[96:97], v[98:99], v[98:99] op_sel:[0,1] op_sel_hi:[1,0]
	v_mul_f32_e32 v98, v105, v105
	v_mov_b32_e32 v97, v128
	v_pk_add_f32 v[94:95], v[94:95], v[96:97]
	v_mul_f32_e32 v96, v103, v103
	v_mul_f32_e32 v152, v126, v126
	v_mul_f32_e32 v154, v127, v127
	v_pk_fma_f32 v[96:97], v[102:103], v[102:103], v[96:97] op_sel_hi:[1,1,0]
	v_pk_fma_f32 v[98:99], v[104:105], v[104:105], v[98:99] op_sel_hi:[1,1,0]
	v_mov_b32_e32 v97, v152
	v_mov_b32_e32 v99, v154
	v_pk_add_f32 v[96:97], v[96:97], v[98:99]
	v_lshlrev_b32_e32 v138, 16, v120
	v_pk_add_f32 v[94:95], v[94:95], v[96:97]
	v_and_b32_e32 v139, 0xffff0000, v120
	v_add_f32_e32 v94, v94, v95
	ds_bpermute_b32 v95, v182, v94
	v_lshlrev_b32_e32 v140, 16, v121
	v_and_b32_e32 v141, 0xffff0000, v121
	v_mov_b32_e32 v152, v155
	v_lshlrev_b32_e32 v120, 16, v118
	s_waitcnt lgkmcnt(0)
	v_add_f32_e32 v94, v94, v95
	ds_bpermute_b32 v95, v198, v94
	v_and_b32_e32 v121, 0xffff0000, v118
	v_lshlrev_b32_e32 v118, 16, v119
	v_and_b32_e32 v119, 0xffff0000, v119
	v_lshlrev_b32_e32 v136, 16, v116
	s_waitcnt lgkmcnt(0)
	v_add_f32_e32 v94, v94, v95
	ds_bpermute_b32 v95, v199, v94
	v_and_b32_e32 v137, 0xffff0000, v116
	v_lshlrev_b32_e32 v116, 16, v117
	v_and_b32_e32 v117, 0xffff0000, v117
	v_mov_b32_e32 v128, v131
	s_waitcnt lgkmcnt(0)
	v_add_f32_e32 v94, v94, v95
	ds_bpermute_b32 v95, v200, v94
	s_ashr_i32 s87, s86, 31
	s_lshl_b64 s[4:5], s[86:87], 12
	s_waitcnt lgkmcnt(0)
	v_add_f32_e32 v94, v94, v95
	ds_bpermute_b32 v95, v201, v94
	s_waitcnt lgkmcnt(0)
	v_add_f32_e32 v94, v94, v95
	ds_bpermute_b32 v95, v222, v94
	s_waitcnt lgkmcnt(0)
	v_add_f32_e32 v94, v94, v95
	v_fmamk_f32 v94, v94, 0x3a000000, v204
	v_cmp_gt_f32_e32 vcc, s34, v94
	v_mul_f32_e32 v95, 0x4b800000, v94
	s_nop 0
	v_cndmask_b32_e32 v94, v94, v95, vcc
	v_rsq_f32_e32 v94, v94
	s_nop 0
	v_mul_f32_e32 v95, 0x45800000, v94
	v_cndmask_b32_e32 v94, v94, v95, vcc
	v_mul_f32_e32 v130, v163, v94
	ds_read_b128 v[94:97], v253
	s_waitcnt lgkmcnt(0)
	v_pk_mul_f32 v[98:99], v[94:95], v[166:167]
	v_pk_mul_f32 v[94:95], v[96:97], v[168:169]
	v_pk_fma_f32 v[96:97], v[98:99], v[130:131], v[148:149] op_sel_hi:[1,0,1]
	ds_read_b128 v[98:101], v253 offset:1024
	v_mov_b32_e32 v148, v158
	v_mov_b32_e32 v149, v164
	v_mov_b32_e32 v164, v159
	v_pk_fma_f32 v[94:95], v[94:95], v[130:131], v[150:151] op_sel_hi:[1,0,1]
	s_waitcnt lgkmcnt(0)
	v_pk_mul_f32 v[148:149], v[98:99], v[148:149]
	v_pk_mul_f32 v[98:99], v[100:101], v[164:165]
	v_pk_fma_f32 v[100:101], v[148:149], v[130:131], v[142:143] op_sel_hi:[1,0,1]
	v_pk_fma_f32 v[98:99], v[98:99], v[130:131], v[144:145] op_sel_hi:[1,0,1]
	ds_read_b128 v[142:145], v253 offset:2048
	s_waitcnt lgkmcnt(0)
	v_pk_mul_f32 v[142:143], v[142:143], v[106:107]
	v_pk_mul_f32 v[106:107], v[144:145], v[108:109]
	v_pk_fma_f32 v[108:109], v[142:143], v[130:131], v[138:139] op_sel_hi:[1,0,1]
	v_pk_fma_f32 v[106:107], v[106:107], v[130:131], v[140:141] op_sel_hi:[1,0,1]
	ds_read_b128 v[138:141], v253 offset:3072
	v_mov_b32_e32 v142, v112
	v_mov_b32_e32 v143, v146
	v_mov_b32_e32 v146, v113
	s_waitcnt lgkmcnt(0)
	v_pk_mul_f32 v[140:141], v[156:157], v[140:141]
	v_pk_mul_f32 v[138:139], v[152:153], v[138:139]
	v_pk_fma_f32 v[118:119], v[140:141], v[130:131], v[118:119] op_sel_hi:[1,0,1]
	v_pk_fma_f32 v[120:121], v[138:139], v[130:131], v[120:121] op_sel_hi:[1,0,1]
	ds_read_b128 v[138:141], v253 offset:4096
	s_waitcnt lgkmcnt(0)
	v_pk_mul_f32 v[138:139], v[138:139], v[142:143]
	v_pk_mul_f32 v[112:113], v[140:141], v[146:147]
	v_mov_b32_e32 v140, v111
	v_pk_fma_f32 v[112:113], v[112:113], v[130:131], v[116:117] op_sel_hi:[1,0,1]
	v_pk_fma_f32 v[116:117], v[138:139], v[130:131], v[136:137] op_sel_hi:[1,0,1]
	ds_read_b128 v[136:139], v253 offset:5120
	v_mov_b32_e32 v141, v115
	v_mov_b32_e32 v111, v114
	s_waitcnt lgkmcnt(0)
	v_pk_mul_f32 v[138:139], v[138:139], v[140:141]
	v_pk_mul_f32 v[110:111], v[136:137], v[110:111]
	s_nop 0
	v_pk_fma_f32 v[114:115], v[110:111], v[130:131], v[132:133] op_sel_hi:[1,0,1]
	v_pk_fma_f32 v[110:111], v[138:139], v[130:131], v[134:135] op_sel_hi:[1,0,1]
	ds_read_b128 v[132:135], v253 offset:6144
	s_waitcnt lgkmcnt(0)
; __device__ __forceinline__ unsigned pk2(float lo, float hi) { const f32x2 v = {lo, hi}; const bf16x2_cv b = __builtin_convertvector(v, bf16x2_cv); return __builtin_bit_cast(unsigned, b); }
; __device__ __forceinline__ unsigned pk2(float lo, float hi) { return f2bf(lo) | (f2bf(hi) << 16); }
; template <bool XIN_BF, bool XOUT_BF>
; __device__ __forceinline__ void ew_rows(const void* xsrc, void* xdst, const bf16* y, float scale, const float* gpost, const float* gpre, bf16* hout, int gw, int ngw, int lane) {
;     ...
;                 if (XOUT_BF) { v2u* xo = (v2u*)((bf16*)xdst + (size_t)row * DM) + lane;
; #pragma unroll
;                     for (int j = 0; j < 8; ++j) xo[64 * j] = (v2u){pk2(xv[j].x, xv[j].y), pk2(xv[j].z, xv[j].w)};
;                 } else { f32x4* xo = (f32x4*)((float*)xdst + (size_t)row * DM) + lane;
; #pragma unroll
;                     for (int j = 0; j < 8; ++j) xo[64 * j] = xv[j]; }
;             }
;             if (hout) {
;                 float s2 = 0.f;
; #pragma unroll
;                 for (int j = 0; j < 8; ++j) s2 += (xv[j].x * xv[j].x + xv[j].y * xv[j].y) + (xv[j].z * xv[j].z + xv[j].w * xv[j].w);
;                 const float rs2 = rsqrtf(wave_sum(s2) * (1.0f / DM) + 1e-6f);
	v_pk_mul_f32 v[134:135], v[134:135], v[104:105]
	v_pk_mul_f32 v[102:103], v[132:133], v[102:103]
	s_nop 0
	v_pk_fma_f32 v[104:105], v[102:103], v[130:131], v[0:1] op_sel_hi:[1,0,1]
	v_pk_fma_f32 v[102:103], v[134:135], v[130:131], v[2:3] op_sel_hi:[1,0,1]
	ds_read_b128 v[0:3], v253 offset:7168
	s_waitcnt lgkmcnt(0)
	v_pk_mul_f32 v[128:129], v[128:129], v[0:1]
	v_pk_mul_f32 v[0:1], v[126:127], v[2:3]
	v_bfe_u32 v126, v95, 16, 1
	v_pk_fma_f32 v[0:1], v[0:1], v[130:131], v[124:125] op_sel_hi:[1,0,1]
	v_bfe_u32 v124, v96, 16, 1
	v_add3_u32 v124, v96, v124, s46
	v_bfe_u32 v125, v97, 16, 1
	v_lshrrev_b32_e32 v124, 16, v124
	v_add3_u32 v125, v97, v125, s46
	v_and_or_b32 v124, v125, s33, v124
	v_bfe_u32 v125, v94, 16, 1
	v_add3_u32 v125, v94, v125, s46
	v_lshrrev_b32_e32 v125, 16, v125
	v_add3_u32 v126, v95, v126, s46
	v_pk_fma_f32 v[2:3], v[128:129], v[130:131], v[122:123] op_sel_hi:[1,0,1]
	v_lshl_add_u64 v[122:123], v[4:5], 0, s[4:5]
	v_and_or_b32 v125, v126, s33, v125
	global_store_dwordx2 v[122:123], v[124:125], off
	v_bfe_u32 v124, v100, 16, 1
	v_add3_u32 v124, v100, v124, s46
	v_bfe_u32 v125, v101, 16, 1
	v_lshrrev_b32_e32 v124, 16, v124
	v_add3_u32 v125, v101, v125, s46
	v_and_or_b32 v124, v125, s33, v124
	v_bfe_u32 v125, v98, 16, 1
	v_add3_u32 v125, v98, v125, s46
	v_bfe_u32 v126, v99, 16, 1
	v_lshrrev_b32_e32 v125, 16, v125
	v_add3_u32 v126, v99, v126, s46
	v_and_or_b32 v125, v126, s33, v125
	global_store_dwordx2 v[122:123], v[124:125], off offset:512
	v_bfe_u32 v124, v108, 16, 1
	v_add3_u32 v124, v108, v124, s46
	v_bfe_u32 v125, v109, 16, 1
	v_lshrrev_b32_e32 v124, 16, v124
	v_add3_u32 v125, v109, v125, s46
	v_and_or_b32 v124, v125, s33, v124
	v_bfe_u32 v125, v106, 16, 1
	v_add3_u32 v125, v106, v125, s46
	v_bfe_u32 v126, v107, 16, 1
	v_lshrrev_b32_e32 v125, 16, v125
	v_add3_u32 v126, v107, v126, s46
	v_and_or_b32 v125, v126, s33, v125
	global_store_dwordx2 v[122:123], v[124:125], off offset:1024
	v_bfe_u32 v124, v120, 16, 1
	v_add3_u32 v124, v120, v124, s46
	v_bfe_u32 v125, v121, 16, 1
	v_lshrrev_b32_e32 v124, 16, v124
	v_add3_u32 v125, v121, v125, s46
	v_and_or_b32 v124, v125, s33, v124
	v_bfe_u32 v125, v118, 16, 1
	v_add3_u32 v125, v118, v125, s46
	v_bfe_u32 v126, v119, 16, 1
	v_lshrrev_b32_e32 v125, 16, v125
	v_add3_u32 v126, v119, v126, s46
	v_and_or_b32 v125, v126, s33, v125
	global_store_dwordx2 v[122:123], v[124:125], off offset:1536
	v_bfe_u32 v124, v116, 16, 1
	v_add3_u32 v124, v116, v124, s46
	v_bfe_u32 v125, v117, 16, 1
	v_lshrrev_b32_e32 v124, 16, v124
	v_add3_u32 v125, v117, v125, s46
	v_and_or_b32 v124, v125, s33, v124
	v_bfe_u32 v125, v112, 16, 1
	v_add3_u32 v125, v112, v125, s46
	v_bfe_u32 v126, v113, 16, 1
	v_lshrrev_b32_e32 v125, 16, v125
	v_add3_u32 v126, v113, v126, s46
	v_and_or_b32 v125, v126, s33, v125
	global_store_dwordx2 v[122:123], v[124:125], off offset:2048
	v_bfe_u32 v124, v114, 16, 1
	v_add3_u32 v124, v114, v124, s46
	v_bfe_u32 v125, v115, 16, 1
	v_lshrrev_b32_e32 v124, 16, v124
	v_add3_u32 v125, v115, v125, s46
	v_and_or_b32 v124, v125, s33, v124
	v_bfe_u32 v125, v110, 16, 1
	v_add3_u32 v125, v110, v125, s46
	v_bfe_u32 v126, v111, 16, 1
	v_lshrrev_b32_e32 v125, 16, v125
	v_add3_u32 v126, v111, v126, s46
	v_and_or_b32 v125, v126, s33, v125
	global_store_dwordx2 v[122:123], v[124:125], off offset:2560
	v_bfe_u32 v124, v104, 16, 1
	v_add3_u32 v124, v104, v124, s46
	v_bfe_u32 v125, v105, 16, 1
	v_lshrrev_b32_e32 v124, 16, v124
	v_add3_u32 v125, v105, v125, s46
	v_and_or_b32 v124, v125, s33, v124
	v_bfe_u32 v125, v102, 16, 1
	v_add3_u32 v125, v102, v125, s46
	v_bfe_u32 v126, v103, 16, 1
	v_lshrrev_b32_e32 v125, 16, v125
	v_add3_u32 v126, v103, v126, s46
	v_and_or_b32 v125, v126, s33, v125
	global_store_dwordx2 v[122:123], v[124:125], off offset:3072
	v_bfe_u32 v124, v2, 16, 1
	v_add3_u32 v124, v2, v124, s46
	v_bfe_u32 v125, v3, 16, 1
	v_lshrrev_b32_e32 v124, 16, v124
	v_add3_u32 v125, v3, v125, s46
	v_and_or_b32 v124, v125, s33, v124
	v_bfe_u32 v125, v0, 16, 1
	v_add3_u32 v125, v0, v125, s46
	v_bfe_u32 v126, v1, 16, 1
	v_lshrrev_b32_e32 v125, 16, v125
	v_add3_u32 v126, v1, v126, s46
	v_and_or_b32 v125, v126, s33, v125
	global_store_dwordx2 v[122:123], v[124:125], off offset:3584
	v_mov_b32_e32 v124, v97
	v_mov_b32_e32 v125, v101
	v_mov_b32_e32 v122, v96
	v_mov_b32_e32 v123, v100
	v_pk_mul_f32 v[124:125], v[124:125], v[124:125]
	v_mov_b32_e32 v126, v95
	v_mov_b32_e32 v127, v99
	v_pk_fma_f32 v[122:123], v[122:123], v[122:123], v[124:125]
	v_mov_b32_e32 v124, v94
	v_mov_b32_e32 v125, v98
	v_pk_mul_f32 v[126:127], v[126:127], v[126:127]
	s_nop 0
	v_pk_fma_f32 v[124:125], v[124:125], v[124:125], v[126:127]
	v_pk_mul_f32 v[126:127], v[108:109], v[108:109]
	v_pk_add_f32 v[122:123], v[122:123], v[124:125]
	v_pk_mul_f32 v[124:125], v[106:107], v[106:107]
	v_pk_add_f32 v[122:123], v[122:123], v[122:123] op_sel_hi:[0,1]
	v_pk_mov_b32 v[128:129], v[126:127], v[124:125] op_sel:[1,0]
	v_mov_b32_e32 v127, v125
	v_mul_f32_e32 v122, v120, v120
	v_pk_add_f32 v[124:125], v[128:129], v[126:127]
	v_pk_fma_f32 v[126:127], v[120:121], v[120:121], v[122:123] op_sel_hi:[1,1,0]
	v_mul_f32_e32 v122, v118, v118
	v_pk_add_f32 v[124:125], v[124:125], v[124:125] op_sel_hi:[0,1]
	v_pk_fma_f32 v[128:129], v[118:119], v[118:119], v[122:123] op_sel_hi:[1,1,0]
	v_mul_f32_e32 v126, v116, v116
	v_mul_f32_e32 v128, v117, v117
	v_mul_f32_e32 v124, v112, v112
	v_mul_f32_e32 v122, v113, v113
	v_pk_add_f32 v[126:127], v[126:127], v[128:129]
	v_pk_add_f32 v[122:123], v[124:125], v[122:123]
	v_pk_mul_f32 v[124:125], v[110:111], v[110:111]
	v_pk_add_f32 v[122:123], v[126:127], v[122:123]
	v_pk_mul_f32 v[126:127], v[114:115], v[114:115]
	v_pk_add_f32 v[122:123], v[122:123], v[122:123] op_sel_hi:[0,1]
	v_pk_mov_b32 v[128:129], v[126:127], v[124:125] op_sel:[1,0]
	v_mov_b32_e32 v127, v125
	v_mul_f32_e32 v122, v104, v104
	v_pk_add_f32 v[124:125], v[128:129], v[126:127]
	v_pk_fma_f32 v[126:127], v[104:105], v[104:105], v[122:123] op_sel_hi:[1,1,0]
	v_mul_f32_e32 v122, v102, v102
	v_pk_add_f32 v[124:125], v[124:125], v[124:125] op_sel_hi:[0,1]
	v_pk_fma_f32 v[128:129], v[102:103], v[102:103], v[122:123] op_sel_hi:[1,1,0]
	v_mul_f32_e32 v126, v2, v2
	v_mul_f32_e32 v128, v3, v3
	v_mul_f32_e32 v124, v0, v0
	v_mul_f32_e32 v122, v1, v1
	v_pk_add_f32 v[126:127], v[126:127], v[128:129]
	v_pk_add_f32 v[122:123], v[124:125], v[122:123]
	s_nop 0
	v_pk_add_f32 v[122:123], v[126:127], v[122:123]
	ds_read_b128 v[126:129], v253 offset:8192
	v_add_f32_e32 v122, v122, v123
	ds_bpermute_b32 v123, v182, v122
	s_waitcnt lgkmcnt(0)
; __device__ __forceinline__ unsigned pk2(float lo, float hi) { const f32x2 v = {lo, hi}; const bf16x2_cv b = __builtin_convertvector(v, bf16x2_cv); return __builtin_bit_cast(unsigned, b); }
; __device__ __forceinline__ unsigned pk2(float lo, float hi) { return f2bf(lo) | (f2bf(hi) << 16); }
; template <bool XIN_BF, bool XOUT_BF>
; __device__ __forceinline__ void ew_rows(const void* xsrc, void* xdst, const bf16* y, float scale, const float* gpost, const float* gpre, bf16* hout, int gw, int ngw, int lane) {
;     ...
;                 const float rs2 = rsqrtf(wave_sum(s2) * (1.0f / DM) + 1e-6f);
;                 v2u* ho = (v2u*)(hout + (size_t)row * DM) + lane;
; #pragma unroll
;                 for (int j = 0; j < 8; ++j) { const f32x4 g = ((const f32x4*)gpre)[lane + 64 * j]; const f32x4 t = xv[j] * g * rs2; ho[64 * j] = (v2u){pk2(t.x, t.y), pk2(t.z, t.w)}; }
	v_add_f32_e32 v122, v122, v123
	ds_bpermute_b32 v123, v198, v122
	s_waitcnt lgkmcnt(0)
	v_add_f32_e32 v122, v122, v123
	ds_bpermute_b32 v123, v199, v122
	s_waitcnt lgkmcnt(0)
	v_add_f32_e32 v122, v122, v123
	ds_bpermute_b32 v123, v200, v122
	s_waitcnt lgkmcnt(0)
	v_add_f32_e32 v122, v122, v123
	ds_bpermute_b32 v123, v201, v122
	s_waitcnt lgkmcnt(0)
	v_add_f32_e32 v122, v122, v123
	ds_bpermute_b32 v123, v222, v122
	s_waitcnt lgkmcnt(0)
	v_add_f32_e32 v122, v122, v123
	v_fmamk_f32 v122, v122, 0x3a000000, v204
	v_cmp_gt_f32_e32 vcc, s34, v122
	v_mul_f32_e32 v123, 0x4b800000, v122
	s_waitcnt lgkmcnt(0)
	v_pk_mul_f32 v[96:97], v[96:97], v[126:127]
	v_cndmask_b32_e32 v122, v122, v123, vcc
	v_rsq_f32_e32 v122, v122
	v_pk_mul_f32 v[94:95], v[94:95], v[128:129]
	v_mul_f32_e32 v123, 0x45800000, v122
	v_cndmask_b32_e32 v124, v122, v123, vcc
	v_pk_mul_f32 v[96:97], v[96:97], v[124:125] op_sel_hi:[1,0]
	v_pk_mul_f32 v[94:95], v[94:95], v[124:125] op_sel_hi:[1,0]
	v_bfe_u32 v125, v96, 16, 1
	v_add3_u32 v96, v96, v125, s46
	v_bfe_u32 v125, v97, 16, 1
	v_lshrrev_b32_e32 v96, 16, v96
	v_add3_u32 v97, v97, v125, s46
	v_and_or_b32 v96, v97, s33, v96
	v_bfe_u32 v97, v94, 16, 1
	v_add3_u32 v94, v94, v97, s46
	v_bfe_u32 v97, v95, 16, 1
	v_lshrrev_b32_e32 v94, 16, v94
	v_add3_u32 v95, v95, v97, s46
	v_lshl_add_u64 v[122:123], v[8:9], 0, s[4:5]
	v_and_or_b32 v97, v95, s33, v94
	global_store_dwordx2 v[122:123], v[96:97], off
	ds_read_b128 v[94:97], v253 offset:9216
	s_andn2_b64 vcc, exec, s[84:85]
	s_waitcnt lgkmcnt(0)
	v_pk_mul_f32 v[94:95], v[100:101], v[94:95]
	s_nop 0
	v_pk_mul_f32 v[94:95], v[94:95], v[124:125] op_sel_hi:[1,0]
	v_pk_mul_f32 v[96:97], v[98:99], v[96:97]
	v_bfe_u32 v98, v94, 16, 1
	v_add3_u32 v94, v94, v98, s46
	v_bfe_u32 v98, v95, 16, 1
	v_pk_mul_f32 v[96:97], v[96:97], v[124:125] op_sel_hi:[1,0]
	v_lshrrev_b32_e32 v94, 16, v94
	v_add3_u32 v95, v95, v98, s46
	v_and_or_b32 v94, v95, s33, v94
	v_bfe_u32 v95, v96, 16, 1
	v_add3_u32 v95, v96, v95, s46
	v_bfe_u32 v96, v97, 16, 1
	v_lshrrev_b32_e32 v95, 16, v95
	v_add3_u32 v96, v97, v96, s46
	v_and_or_b32 v95, v96, s33, v95
	global_store_dwordx2 v[122:123], v[94:95], off offset:512
	ds_read_b128 v[94:97], v253 offset:10240
	s_waitcnt lgkmcnt(0)
	v_pk_mul_f32 v[94:95], v[108:109], v[94:95]
	s_nop 0
	v_pk_mul_f32 v[94:95], v[94:95], v[124:125] op_sel_hi:[1,0]
	v_pk_mul_f32 v[96:97], v[106:107], v[96:97]
	v_bfe_u32 v98, v94, 16, 1
	v_add3_u32 v94, v94, v98, s46
	v_bfe_u32 v98, v95, 16, 1
	v_pk_mul_f32 v[96:97], v[96:97], v[124:125] op_sel_hi:[1,0]
	v_lshrrev_b32_e32 v94, 16, v94
	v_add3_u32 v95, v95, v98, s46
	v_and_or_b32 v94, v95, s33, v94
	v_bfe_u32 v95, v96, 16, 1
	v_add3_u32 v95, v96, v95, s46
	v_bfe_u32 v96, v97, 16, 1
	v_lshrrev_b32_e32 v95, 16, v95
	v_add3_u32 v96, v97, v96, s46
	v_and_or_b32 v95, v96, s33, v95
	global_store_dwordx2 v[122:123], v[94:95], off offset:1024
	ds_read_b128 v[94:97], v253 offset:11264
	s_waitcnt lgkmcnt(0)
	v_pk_mul_f32 v[94:95], v[120:121], v[94:95]
	s_nop 0
	v_pk_mul_f32 v[94:95], v[94:95], v[124:125] op_sel_hi:[1,0]
	v_pk_mul_f32 v[96:97], v[118:119], v[96:97]
	v_bfe_u32 v98, v94, 16, 1
	v_add3_u32 v94, v94, v98, s46
	v_bfe_u32 v98, v95, 16, 1
	v_pk_mul_f32 v[96:97], v[96:97], v[124:125] op_sel_hi:[1,0]
	v_lshrrev_b32_e32 v94, 16, v94
	v_add3_u32 v95, v95, v98, s46
	v_and_or_b32 v94, v95, s33, v94
	v_bfe_u32 v95, v96, 16, 1
	v_add3_u32 v95, v96, v95, s46
	v_bfe_u32 v96, v97, 16, 1
	v_lshrrev_b32_e32 v95, 16, v95
	v_add3_u32 v96, v97, v96, s46
	v_and_or_b32 v95, v96, s33, v95
	global_store_dwordx2 v[122:123], v[94:95], off offset:1536
	ds_read_b128 v[94:97], v253 offset:12288
	s_waitcnt lgkmcnt(0)
	v_pk_mul_f32 v[94:95], v[116:117], v[94:95]
	s_nop 0
	v_pk_mul_f32 v[94:95], v[94:95], v[124:125] op_sel_hi:[1,0]
	v_pk_mul_f32 v[96:97], v[112:113], v[96:97]
	v_bfe_u32 v98, v94, 16, 1
	v_add3_u32 v94, v94, v98, s46
	v_bfe_u32 v98, v95, 16, 1
	v_pk_mul_f32 v[96:97], v[96:97], v[124:125] op_sel_hi:[1,0]
	v_lshrrev_b32_e32 v94, 16, v94
	v_add3_u32 v95, v95, v98, s46
	v_and_or_b32 v94, v95, s33, v94
	v_bfe_u32 v95, v96, 16, 1
	v_add3_u32 v95, v96, v95, s46
	v_bfe_u32 v96, v97, 16, 1
	v_lshrrev_b32_e32 v95, 16, v95
	v_add3_u32 v96, v97, v96, s46
	v_and_or_b32 v95, v96, s33, v95
	global_store_dwordx2 v[122:123], v[94:95], off offset:2048
	ds_read_b128 v[94:97], v253 offset:13312
	s_waitcnt lgkmcnt(0)
	v_pk_mul_f32 v[94:95], v[114:115], v[94:95]
	s_nop 0
	v_pk_mul_f32 v[94:95], v[94:95], v[124:125] op_sel_hi:[1,0]
	v_pk_mul_f32 v[96:97], v[110:111], v[96:97]
	v_bfe_u32 v98, v94, 16, 1
	v_add3_u32 v94, v94, v98, s46
	v_bfe_u32 v98, v95, 16, 1
	v_pk_mul_f32 v[96:97], v[96:97], v[124:125] op_sel_hi:[1,0]
	v_lshrrev_b32_e32 v94, 16, v94
	v_add3_u32 v95, v95, v98, s46
	v_and_or_b32 v94, v95, s33, v94
	v_bfe_u32 v95, v96, 16, 1
	v_add3_u32 v95, v96, v95, s46
	v_bfe_u32 v96, v97, 16, 1
	v_lshrrev_b32_e32 v95, 16, v95
	v_add3_u32 v96, v97, v96, s46
	v_and_or_b32 v95, v96, s33, v95
	global_store_dwordx2 v[122:123], v[94:95], off offset:2560
	ds_read_b128 v[94:97], v253 offset:14336
	s_waitcnt lgkmcnt(0)
	v_pk_mul_f32 v[94:95], v[104:105], v[94:95]
	s_nop 0
	v_pk_mul_f32 v[94:95], v[94:95], v[124:125] op_sel_hi:[1,0]
	v_pk_mul_f32 v[96:97], v[102:103], v[96:97]
	v_bfe_u32 v98, v94, 16, 1
	v_add3_u32 v94, v94, v98, s46
	v_bfe_u32 v98, v95, 16, 1
	v_pk_mul_f32 v[96:97], v[96:97], v[124:125] op_sel_hi:[1,0]
	v_lshrrev_b32_e32 v94, 16, v94
	v_add3_u32 v95, v95, v98, s46
	v_and_or_b32 v94, v95, s33, v94
	v_bfe_u32 v95, v96, 16, 1
	v_add3_u32 v95, v96, v95, s46
	v_bfe_u32 v96, v97, 16, 1
	v_lshrrev_b32_e32 v95, 16, v95
	v_add3_u32 v96, v97, v96, s46
	v_and_or_b32 v95, v96, s33, v95
	global_store_dwordx2 v[122:123], v[94:95], off offset:3072
	ds_read_b128 v[94:97], v253 offset:15360
	s_waitcnt lgkmcnt(0)
	v_pk_mul_f32 v[2:3], v[2:3], v[94:95]
	s_nop 0
	v_pk_mul_f32 v[2:3], v[2:3], v[124:125] op_sel_hi:[1,0]
	v_pk_mul_f32 v[0:1], v[0:1], v[96:97]
	v_bfe_u32 v94, v2, 16, 1
	v_add3_u32 v2, v2, v94, s46
	v_bfe_u32 v94, v3, 16, 1
	v_pk_mul_f32 v[0:1], v[0:1], v[124:125] op_sel_hi:[1,0]
	v_lshrrev_b32_e32 v2, 16, v2
	v_add3_u32 v3, v3, v94, s46
	v_and_or_b32 v2, v3, s33, v2
	v_bfe_u32 v3, v0, 16, 1
	v_add3_u32 v0, v0, v3, s46
	v_bfe_u32 v3, v1, 16, 1
	v_lshrrev_b32_e32 v0, 16, v0
	v_add3_u32 v1, v1, v3, s46
	v_and_or_b32 v3, v1, s33, v0
	global_store_dwordx2 v[122:123], v[2:3], off offset:3584
	s_cbranch_vccnz .LBB0_746
; template <bool XIN_BF, bool XOUT_BF>
; __device__ __forceinline__ void ew_rows(const void* xsrc, void* xdst, const bf16* y, float scale, const float* gpost, const float* gpre, bf16* hout, int gw, int ngw, int lane) {
;     ...
;         for (int r = 0; r < NR; ++r) { const int row = row0 + r * ngw; if (row >= TOK) break;
;             f32x4 xv[8];
; #pragma unroll
;             for (int j = 0; j < 8; ++j) { if (XIN_BF) { const v2u w = xb[XIN_BF ? r : 0][j]; xv[j] = (f32x4){__uint_as_float(w.x << 16), __uint_as_float(w.x & 0xffff0000u), __uint_as_float(w.y << 16), __uint_as_float(w.y & 0xffff0000u)}; } else xv[j] = xf[XIN_BF ? 0 : r][j]; }
;             if (y) {
;                 f32x4 yv[8]; float ss = 0.f;
; #pragma unroll
;                 for (int j = 0; j < 8; ++j) { const v2u w = yb[r][j]; yv[j] = (f32x4){__uint_as_float(w.x << 16), __uint_as_float(w.x & 0xffff0000u), __uint_as_float(w.y << 16), __uint_as_float(w.y & 0xffff0000u)};
;                     ss += (yv[j].x * yv[j].x + yv[j].y * yv[j].y) + (yv[j].z * yv[j].z + yv[j].w * yv[j].w); }
;                 const float rs = rsqrtf(wave_sum(ss) * (1.0f / DM) + 1e-6f) * scale;
; #pragma unroll
;                 for (int j = 0; j < 8; ++j) { const f32x4 g = ((const f32x4*)gpost)[lane + 64 * j]; xv[j] = xv[j] + yv[j] * g * rs; }
	v_and_b32_e32 v131, 0xffff0000, v76
	v_and_b32_e32 v133, 0xffff0000, v77
	v_lshlrev_b32_e32 v130, 16, v76
	v_lshlrev_b32_e32 v132, 16, v77
	v_mul_f32_e32 v76, v133, v133
	v_and_b32_e32 v129, 0xffff0000, v75
	v_and_b32_e32 v128, 0xffff0000, v74
	v_lshlrev_b32_e32 v123, 16, v70
	v_and_b32_e32 v121, 0xffff0000, v70
	v_mul_f32_e32 v70, v131, v131
	v_lshlrev_b32_e32 v116, 16, v92
	v_and_b32_e32 v117, 0xffff0000, v92
	v_lshlrev_b32_e32 v118, 16, v93
	v_and_b32_e32 v119, 0xffff0000, v93
	v_lshlrev_b32_e32 v110, 16, v90
	v_and_b32_e32 v111, 0xffff0000, v90
	v_lshlrev_b32_e32 v112, 16, v91
	v_and_b32_e32 v113, 0xffff0000, v91
	v_lshlrev_b32_e32 v90, 16, v78
	v_and_b32_e32 v91, 0xffff0000, v78
	v_lshlrev_b32_e32 v92, 16, v79
	v_and_b32_e32 v93, 0xffff0000, v79
	v_pk_fma_f32 v[78:79], v[132:133], v[132:133], v[76:77] op_sel_hi:[1,1,0]
	v_lshlrev_b32_e32 v127, 16, v75
	v_lshlrev_b32_e32 v126, 16, v74
	v_pk_mul_f32 v[74:75], v[128:129], v[128:129]
	v_lshlrev_b32_e32 v124, 16, v71
	v_and_b32_e32 v125, 0xffff0000, v71
	v_pk_fma_f32 v[70:71], v[130:131], v[130:131], v[70:71] op_sel_hi:[1,1,0]
	v_lshlrev_b32_e32 v0, 16, v80
	v_and_b32_e32 v1, 0xffff0000, v80
	v_lshlrev_b32_e32 v2, 16, v81
	v_and_b32_e32 v3, 0xffff0000, v81
	v_pk_fma_f32 v[80:81], v[126:127], v[126:127], v[74:75]
	v_lshlrev_b32_e32 v74, 16, v72
	v_and_b32_e32 v75, 0xffff0000, v72
	v_lshlrev_b32_e32 v76, 16, v73
	v_and_b32_e32 v77, 0xffff0000, v73
	v_mov_b32_e32 v122, v70
	v_mov_b32_e32 v72, v78
	v_mov_b32_e32 v73, v123
	v_pk_add_f32 v[70:71], v[70:71], v[78:79]
	v_pk_mul_f32 v[72:73], v[122:123], v[72:73]
	v_lshlrev_b32_e32 v100, 16, v82
	v_and_b32_e32 v101, 0xffff0000, v82
	v_mul_f32_e32 v82, v121, v121
	v_mov_b32_e32 v71, v73
	v_pk_add_f32 v[72:73], v[80:81], v[80:81] op_sel:[0,1] op_sel_hi:[1,0]
	v_mul_f32_e32 v78, v77, v77
	v_mov_b32_e32 v73, v82
	v_pk_add_f32 v[70:71], v[70:71], v[72:73]
	v_mul_f32_e32 v72, v75, v75
	v_lshlrev_b32_e32 v102, 16, v83
	v_and_b32_e32 v103, 0xffff0000, v83
	v_mul_f32_e32 v83, v124, v124
	v_mul_f32_e32 v94, v125, v125
	v_pk_fma_f32 v[72:73], v[74:75], v[74:75], v[72:73] op_sel_hi:[1,1,0]
	v_pk_fma_f32 v[78:79], v[76:77], v[76:77], v[78:79] op_sel_hi:[1,1,0]
	v_mov_b32_e32 v73, v83
	v_mov_b32_e32 v79, v94
	v_and_b32_e32 v115, 0xffff0000, v69
	v_and_b32_e32 v114, 0xffff0000, v68
	v_pk_add_f32 v[72:73], v[72:73], v[78:79]
	v_lshlrev_b32_e32 v81, 16, v69
	v_lshlrev_b32_e32 v80, 16, v68
	v_pk_mul_f32 v[68:69], v[114:115], v[114:115]
	v_pk_add_f32 v[134:135], v[70:71], v[72:73]
	v_pk_fma_f32 v[68:69], v[80:81], v[80:81], v[68:69]
	v_and_b32_e32 v83, 0xffff0000, v67
	v_pk_add_f32 v[68:69], v[68:69], v[68:69] op_sel:[0,1] op_sel_hi:[1,0]
	v_and_b32_e32 v82, 0xffff0000, v66
	v_lshlrev_b32_e32 v99, 16, v62
	v_and_b32_e32 v97, 0xffff0000, v62
	v_lshlrev_b32_e32 v94, 16, v63
	v_and_b32_e32 v95, 0xffff0000, v63
	v_pk_add_f32 v[62:63], v[134:135], v[134:135] op_sel:[0,1] op_sel_hi:[1,0]
	v_lshlrev_b32_e32 v79, 16, v67
	v_lshlrev_b32_e32 v78, 16, v66
	v_pk_mul_f32 v[66:67], v[82:83], v[82:83]
	v_lshlrev_b32_e32 v70, 16, v64
	v_and_b32_e32 v71, 0xffff0000, v64
	v_lshlrev_b32_e32 v72, 16, v65
	v_and_b32_e32 v73, 0xffff0000, v65
	v_mov_b32_e32 v98, v62
	v_mov_b32_e32 v64, v68
	v_mov_b32_e32 v65, v99
	v_pk_fma_f32 v[66:67], v[78:79], v[78:79], v[66:67]
	v_pk_add_f32 v[62:63], v[62:63], v[68:69]
	v_pk_mul_f32 v[64:65], v[98:99], v[64:65]
	v_mul_f32_e32 v96, v97, v97
	v_mov_b32_e32 v63, v65
	v_pk_add_f32 v[64:65], v[66:67], v[66:67] op_sel:[0,1] op_sel_hi:[1,0]
	v_mul_f32_e32 v66, v73, v73
	v_mov_b32_e32 v65, v96
	v_pk_add_f32 v[62:63], v[62:63], v[64:65]
	v_mul_f32_e32 v64, v71, v71
	v_mul_f32_e32 v120, v94, v94
	v_mul_f32_e32 v122, v95, v95
	v_pk_fma_f32 v[64:65], v[70:71], v[70:71], v[64:65] op_sel_hi:[1,1,0]
	v_pk_fma_f32 v[66:67], v[72:73], v[72:73], v[66:67] op_sel_hi:[1,1,0]
	v_mov_b32_e32 v65, v120
	v_mov_b32_e32 v67, v122
	v_pk_add_f32 v[64:65], v[64:65], v[66:67]
	v_lshlrev_b32_e32 v106, 16, v88
	v_pk_add_f32 v[62:63], v[62:63], v[64:65]
	v_and_b32_e32 v107, 0xffff0000, v88
	v_add_f32_e32 v62, v62, v63
	ds_bpermute_b32 v63, v182, v62
	v_lshlrev_b32_e32 v108, 16, v89
	v_and_b32_e32 v109, 0xffff0000, v89
	v_mov_b32_e32 v120, v123
	v_lshlrev_b32_e32 v88, 16, v86
	s_waitcnt lgkmcnt(0)
	v_add_f32_e32 v62, v62, v63
	ds_bpermute_b32 v63, v198, v62
	v_and_b32_e32 v89, 0xffff0000, v86
	v_lshlrev_b32_e32 v86, 16, v87
	v_and_b32_e32 v87, 0xffff0000, v87
	v_lshlrev_b32_e32 v104, 16, v84
	s_waitcnt lgkmcnt(0)
	v_add_f32_e32 v62, v62, v63
	ds_bpermute_b32 v63, v199, v62
	v_and_b32_e32 v105, 0xffff0000, v84
	v_lshlrev_b32_e32 v84, 16, v85
	v_and_b32_e32 v85, 0xffff0000, v85
	v_mov_b32_e32 v96, v99
	s_waitcnt lgkmcnt(0)
	v_add_f32_e32 v62, v62, v63
	ds_bpermute_b32 v63, v200, v62
	s_ashr_i32 s83, s82, 31
	s_lshl_b64 s[4:5], s[82:83], 12
	s_waitcnt lgkmcnt(0)
	v_add_f32_e32 v62, v62, v63
	ds_bpermute_b32 v63, v201, v62
	s_waitcnt lgkmcnt(0)
	v_add_f32_e32 v62, v62, v63
	ds_bpermute_b32 v63, v222, v62
	s_waitcnt lgkmcnt(0)
	v_add_f32_e32 v62, v62, v63
	v_fmamk_f32 v62, v62, 0x3a000000, v204
	v_cmp_gt_f32_e32 vcc, s34, v62
	v_mul_f32_e32 v63, 0x4b800000, v62
	s_nop 0
	v_cndmask_b32_e32 v62, v62, v63, vcc
	v_rsq_f32_e32 v62, v62
	s_nop 0
	v_mul_f32_e32 v63, 0x45800000, v62
	v_cndmask_b32_e32 v62, v62, v63, vcc
	v_mul_f32_e32 v98, v163, v62
	ds_read_b128 v[62:65], v253
	s_waitcnt lgkmcnt(0)
	v_pk_mul_f32 v[66:67], v[62:63], v[130:131]
	v_pk_mul_f32 v[62:63], v[64:65], v[132:133]
	v_pk_fma_f32 v[64:65], v[66:67], v[98:99], v[116:117] op_sel_hi:[1,0,1]
	ds_read_b128 v[66:69], v253 offset:1024
	v_mov_b32_e32 v116, v126
	v_mov_b32_e32 v117, v128
	v_mov_b32_e32 v128, v127
	v_pk_fma_f32 v[62:63], v[62:63], v[98:99], v[118:119] op_sel_hi:[1,0,1]
	s_waitcnt lgkmcnt(0)
; __device__ __forceinline__ unsigned pk2(float lo, float hi) { const f32x2 v = {lo, hi}; const bf16x2_cv b = __builtin_convertvector(v, bf16x2_cv); return __builtin_bit_cast(unsigned, b); }
; __device__ __forceinline__ unsigned pk2(float lo, float hi) { return f2bf(lo) | (f2bf(hi) << 16); }
; template <bool XIN_BF, bool XOUT_BF>
; __device__ __forceinline__ void ew_rows(const void* xsrc, void* xdst, const bf16* y, float scale, const float* gpost, const float* gpre, bf16* hout, int gw, int ngw, int lane) {
;     ...
;                 for (int j = 0; j < 8; ++j) { const f32x4 g = ((const f32x4*)gpost)[lane + 64 * j]; xv[j] = xv[j] + yv[j] * g * rs; }
;                 if (XOUT_BF) { v2u* xo = (v2u*)((bf16*)xdst + (size_t)row * DM) + lane;
; #pragma unroll
;                     for (int j = 0; j < 8; ++j) xo[64 * j] = (v2u){pk2(xv[j].x, xv[j].y), pk2(xv[j].z, xv[j].w)};
;                 } else { f32x4* xo = (f32x4*)((float*)xdst + (size_t)row * DM) + lane;
; #pragma unroll
;                     for (int j = 0; j < 8; ++j) xo[64 * j] = xv[j]; }
;             }
;             if (hout) {
;                 float s2 = 0.f;
; #pragma unroll
;                 for (int j = 0; j < 8; ++j) s2 += (xv[j].x * xv[j].x + xv[j].y * xv[j].y) + (xv[j].z * xv[j].z + xv[j].w * xv[j].w);
	v_pk_mul_f32 v[116:117], v[66:67], v[116:117]
	v_pk_mul_f32 v[66:67], v[68:69], v[128:129]
	v_pk_fma_f32 v[68:69], v[116:117], v[98:99], v[110:111] op_sel_hi:[1,0,1]
	v_pk_fma_f32 v[66:67], v[66:67], v[98:99], v[112:113] op_sel_hi:[1,0,1]
	ds_read_b128 v[110:113], v253 offset:2048
	s_waitcnt lgkmcnt(0)
	v_pk_mul_f32 v[110:111], v[110:111], v[74:75]
	v_pk_mul_f32 v[74:75], v[112:113], v[76:77]
	v_pk_fma_f32 v[76:77], v[110:111], v[98:99], v[106:107] op_sel_hi:[1,0,1]
	v_pk_fma_f32 v[74:75], v[74:75], v[98:99], v[108:109] op_sel_hi:[1,0,1]
	ds_read_b128 v[106:109], v253 offset:3072
	v_mov_b32_e32 v110, v80
	v_mov_b32_e32 v111, v114
	v_mov_b32_e32 v114, v81
	s_waitcnt lgkmcnt(0)
	v_pk_mul_f32 v[108:109], v[124:125], v[108:109]
	v_pk_mul_f32 v[106:107], v[120:121], v[106:107]
	v_pk_fma_f32 v[86:87], v[108:109], v[98:99], v[86:87] op_sel_hi:[1,0,1]
	v_pk_fma_f32 v[88:89], v[106:107], v[98:99], v[88:89] op_sel_hi:[1,0,1]
	ds_read_b128 v[106:109], v253 offset:4096
	s_waitcnt lgkmcnt(0)
	v_pk_mul_f32 v[106:107], v[106:107], v[110:111]
	v_pk_mul_f32 v[80:81], v[108:109], v[114:115]
	v_mov_b32_e32 v108, v79
	v_pk_fma_f32 v[80:81], v[80:81], v[98:99], v[84:85] op_sel_hi:[1,0,1]
	v_pk_fma_f32 v[84:85], v[106:107], v[98:99], v[104:105] op_sel_hi:[1,0,1]
	ds_read_b128 v[104:107], v253 offset:5120
	v_mov_b32_e32 v109, v83
	v_mov_b32_e32 v79, v82
	s_waitcnt lgkmcnt(0)
	v_pk_mul_f32 v[106:107], v[106:107], v[108:109]
	v_pk_mul_f32 v[78:79], v[104:105], v[78:79]
	s_nop 0
	v_pk_fma_f32 v[82:83], v[78:79], v[98:99], v[100:101] op_sel_hi:[1,0,1]
	v_pk_fma_f32 v[78:79], v[106:107], v[98:99], v[102:103] op_sel_hi:[1,0,1]
	ds_read_b128 v[100:103], v253 offset:6144
	s_waitcnt lgkmcnt(0)
	v_pk_mul_f32 v[102:103], v[102:103], v[72:73]
	v_pk_mul_f32 v[70:71], v[100:101], v[70:71]
	s_nop 0
	v_pk_fma_f32 v[72:73], v[70:71], v[98:99], v[0:1] op_sel_hi:[1,0,1]
	v_pk_fma_f32 v[70:71], v[102:103], v[98:99], v[2:3] op_sel_hi:[1,0,1]
	ds_read_b128 v[0:3], v253 offset:7168
	s_waitcnt lgkmcnt(0)
	v_pk_mul_f32 v[96:97], v[96:97], v[0:1]
	v_pk_mul_f32 v[0:1], v[94:95], v[2:3]
	v_bfe_u32 v94, v63, 16, 1
	v_pk_fma_f32 v[0:1], v[0:1], v[98:99], v[92:93] op_sel_hi:[1,0,1]
	v_bfe_u32 v92, v64, 16, 1
	v_add3_u32 v92, v64, v92, s46
	v_bfe_u32 v93, v65, 16, 1
	v_lshrrev_b32_e32 v92, 16, v92
	v_add3_u32 v93, v65, v93, s46
	v_and_or_b32 v92, v93, s33, v92
	v_bfe_u32 v93, v62, 16, 1
	v_add3_u32 v93, v62, v93, s46
	v_lshrrev_b32_e32 v93, 16, v93
	v_add3_u32 v94, v63, v94, s46
	v_pk_fma_f32 v[2:3], v[96:97], v[98:99], v[90:91] op_sel_hi:[1,0,1]
	v_lshl_add_u64 v[90:91], v[4:5], 0, s[4:5]
	v_and_or_b32 v93, v94, s33, v93
	global_store_dwordx2 v[90:91], v[92:93], off
	v_bfe_u32 v92, v68, 16, 1
	v_add3_u32 v92, v68, v92, s46
	v_bfe_u32 v93, v69, 16, 1
	v_lshrrev_b32_e32 v92, 16, v92
	v_add3_u32 v93, v69, v93, s46
	v_and_or_b32 v92, v93, s33, v92
	v_bfe_u32 v93, v66, 16, 1
	v_add3_u32 v93, v66, v93, s46
	v_bfe_u32 v94, v67, 16, 1
	v_lshrrev_b32_e32 v93, 16, v93
	v_add3_u32 v94, v67, v94, s46
	v_and_or_b32 v93, v94, s33, v93
	global_store_dwordx2 v[90:91], v[92:93], off offset:512
	v_bfe_u32 v92, v76, 16, 1
	v_add3_u32 v92, v76, v92, s46
	v_bfe_u32 v93, v77, 16, 1
	v_lshrrev_b32_e32 v92, 16, v92
	v_add3_u32 v93, v77, v93, s46
	v_and_or_b32 v92, v93, s33, v92
	v_bfe_u32 v93, v74, 16, 1
	v_add3_u32 v93, v74, v93, s46
	v_bfe_u32 v94, v75, 16, 1
	v_lshrrev_b32_e32 v93, 16, v93
	v_add3_u32 v94, v75, v94, s46
	v_and_or_b32 v93, v94, s33, v93
	global_store_dwordx2 v[90:91], v[92:93], off offset:1024
	v_bfe_u32 v92, v88, 16, 1
	v_add3_u32 v92, v88, v92, s46
	v_bfe_u32 v93, v89, 16, 1
	v_lshrrev_b32_e32 v92, 16, v92
	v_add3_u32 v93, v89, v93, s46
	v_and_or_b32 v92, v93, s33, v92
	v_bfe_u32 v93, v86, 16, 1
	v_add3_u32 v93, v86, v93, s46
	v_bfe_u32 v94, v87, 16, 1
	v_lshrrev_b32_e32 v93, 16, v93
	v_add3_u32 v94, v87, v94, s46
	v_and_or_b32 v93, v94, s33, v93
	global_store_dwordx2 v[90:91], v[92:93], off offset:1536
	v_bfe_u32 v92, v84, 16, 1
	v_add3_u32 v92, v84, v92, s46
	v_bfe_u32 v93, v85, 16, 1
	v_lshrrev_b32_e32 v92, 16, v92
	v_add3_u32 v93, v85, v93, s46
	v_and_or_b32 v92, v93, s33, v92
	v_bfe_u32 v93, v80, 16, 1
	v_add3_u32 v93, v80, v93, s46
	v_bfe_u32 v94, v81, 16, 1
	v_lshrrev_b32_e32 v93, 16, v93
	v_add3_u32 v94, v81, v94, s46
	v_and_or_b32 v93, v94, s33, v93
	global_store_dwordx2 v[90:91], v[92:93], off offset:2048
	v_bfe_u32 v92, v82, 16, 1
	v_add3_u32 v92, v82, v92, s46
	v_bfe_u32 v93, v83, 16, 1
	v_lshrrev_b32_e32 v92, 16, v92
	v_add3_u32 v93, v83, v93, s46
	v_and_or_b32 v92, v93, s33, v92
	v_bfe_u32 v93, v78, 16, 1
	v_add3_u32 v93, v78, v93, s46
	v_bfe_u32 v94, v79, 16, 1
	v_lshrrev_b32_e32 v93, 16, v93
	v_add3_u32 v94, v79, v94, s46
	v_and_or_b32 v93, v94, s33, v93
	global_store_dwordx2 v[90:91], v[92:93], off offset:2560
	v_bfe_u32 v92, v72, 16, 1
	v_add3_u32 v92, v72, v92, s46
	v_bfe_u32 v93, v73, 16, 1
	v_lshrrev_b32_e32 v92, 16, v92
	v_add3_u32 v93, v73, v93, s46
	v_and_or_b32 v92, v93, s33, v92
	v_bfe_u32 v93, v70, 16, 1
	v_add3_u32 v93, v70, v93, s46
	v_bfe_u32 v94, v71, 16, 1
	v_lshrrev_b32_e32 v93, 16, v93
	v_add3_u32 v94, v71, v94, s46
	v_and_or_b32 v93, v94, s33, v93
	global_store_dwordx2 v[90:91], v[92:93], off offset:3072
	v_bfe_u32 v92, v2, 16, 1
	v_add3_u32 v92, v2, v92, s46
	v_bfe_u32 v93, v3, 16, 1
	v_lshrrev_b32_e32 v92, 16, v92
	v_add3_u32 v93, v3, v93, s46
	v_and_or_b32 v92, v93, s33, v92
	v_bfe_u32 v93, v0, 16, 1
	v_add3_u32 v93, v0, v93, s46
	v_bfe_u32 v94, v1, 16, 1
	v_lshrrev_b32_e32 v93, 16, v93
	v_add3_u32 v94, v1, v94, s46
	v_and_or_b32 v93, v94, s33, v93
	global_store_dwordx2 v[90:91], v[92:93], off offset:3584
	v_mov_b32_e32 v92, v65
	v_mov_b32_e32 v93, v69
; __device__ __forceinline__ unsigned pk2(float lo, float hi) { const f32x2 v = {lo, hi}; const bf16x2_cv b = __builtin_convertvector(v, bf16x2_cv); return __builtin_bit_cast(unsigned, b); }
; __device__ __forceinline__ unsigned pk2(float lo, float hi) { return f2bf(lo) | (f2bf(hi) << 16); }
; template <bool XIN_BF, bool XOUT_BF>
; __device__ __forceinline__ void ew_rows(const void* xsrc, void* xdst, const bf16* y, float scale, const float* gpost, const float* gpre, bf16* hout, int gw, int ngw, int lane) {
;     ...
;                 for (int j = 0; j < 8; ++j) s2 += (xv[j].x * xv[j].x + xv[j].y * xv[j].y) + (xv[j].z * xv[j].z + xv[j].w * xv[j].w);
;                 const float rs2 = rsqrtf(wave_sum(s2) * (1.0f / DM) + 1e-6f);
;                 v2u* ho = (v2u*)(hout + (size_t)row * DM) + lane;
; #pragma unroll
;                 for (int j = 0; j < 8; ++j) { const f32x4 g = ((const f32x4*)gpre)[lane + 64 * j]; const f32x4 t = xv[j] * g * rs2; ho[64 * j] = (v2u){pk2(t.x, t.y), pk2(t.z, t.w)}; }
	v_mov_b32_e32 v90, v64
	v_mov_b32_e32 v91, v68
	v_pk_mul_f32 v[92:93], v[92:93], v[92:93]
	v_mov_b32_e32 v94, v63
	v_mov_b32_e32 v95, v67
	v_pk_fma_f32 v[90:91], v[90:91], v[90:91], v[92:93]
	v_mov_b32_e32 v92, v62
	v_mov_b32_e32 v93, v66
	v_pk_mul_f32 v[94:95], v[94:95], v[94:95]
	s_nop 0
	v_pk_fma_f32 v[92:93], v[92:93], v[92:93], v[94:95]
	v_pk_mul_f32 v[94:95], v[76:77], v[76:77]
	v_pk_add_f32 v[90:91], v[90:91], v[92:93]
	v_pk_mul_f32 v[92:93], v[74:75], v[74:75]
	v_pk_add_f32 v[90:91], v[90:91], v[90:91] op_sel_hi:[0,1]
	v_pk_mov_b32 v[96:97], v[94:95], v[92:93] op_sel:[1,0]
	v_mov_b32_e32 v95, v93
	v_mul_f32_e32 v90, v88, v88
	v_pk_add_f32 v[92:93], v[96:97], v[94:95]
	v_pk_fma_f32 v[94:95], v[88:89], v[88:89], v[90:91] op_sel_hi:[1,1,0]
	v_mul_f32_e32 v90, v86, v86
	v_pk_add_f32 v[92:93], v[92:93], v[92:93] op_sel_hi:[0,1]
	v_pk_fma_f32 v[96:97], v[86:87], v[86:87], v[90:91] op_sel_hi:[1,1,0]
	v_mul_f32_e32 v94, v84, v84
	v_mul_f32_e32 v96, v85, v85
	v_mul_f32_e32 v92, v80, v80
	v_mul_f32_e32 v90, v81, v81
	v_pk_add_f32 v[94:95], v[94:95], v[96:97]
	v_pk_add_f32 v[90:91], v[92:93], v[90:91]
	v_pk_mul_f32 v[92:93], v[78:79], v[78:79]
	v_pk_add_f32 v[90:91], v[94:95], v[90:91]
	v_pk_mul_f32 v[94:95], v[82:83], v[82:83]
	v_pk_add_f32 v[90:91], v[90:91], v[90:91] op_sel_hi:[0,1]
	v_pk_mov_b32 v[96:97], v[94:95], v[92:93] op_sel:[1,0]
	v_mov_b32_e32 v95, v93
	v_mul_f32_e32 v90, v72, v72
	v_pk_add_f32 v[92:93], v[96:97], v[94:95]
	v_pk_fma_f32 v[94:95], v[72:73], v[72:73], v[90:91] op_sel_hi:[1,1,0]
	v_mul_f32_e32 v90, v70, v70
	v_pk_add_f32 v[92:93], v[92:93], v[92:93] op_sel_hi:[0,1]
	v_pk_fma_f32 v[96:97], v[70:71], v[70:71], v[90:91] op_sel_hi:[1,1,0]
	v_mul_f32_e32 v94, v2, v2
	v_mul_f32_e32 v96, v3, v3
	v_mul_f32_e32 v92, v0, v0
	v_mul_f32_e32 v90, v1, v1
	v_pk_add_f32 v[94:95], v[94:95], v[96:97]
	v_pk_add_f32 v[90:91], v[92:93], v[90:91]
	s_nop 0
	v_pk_add_f32 v[90:91], v[94:95], v[90:91]
	ds_read_b128 v[94:97], v253 offset:8192
	v_add_f32_e32 v90, v90, v91
	ds_bpermute_b32 v91, v182, v90
	s_waitcnt lgkmcnt(0)
	v_add_f32_e32 v90, v90, v91
	ds_bpermute_b32 v91, v198, v90
	s_waitcnt lgkmcnt(0)
	v_add_f32_e32 v90, v90, v91
	ds_bpermute_b32 v91, v199, v90
	s_waitcnt lgkmcnt(0)
	v_add_f32_e32 v90, v90, v91
	ds_bpermute_b32 v91, v200, v90
	s_waitcnt lgkmcnt(0)
	v_add_f32_e32 v90, v90, v91
	ds_bpermute_b32 v91, v201, v90
	s_waitcnt lgkmcnt(0)
	v_add_f32_e32 v90, v90, v91
	ds_bpermute_b32 v91, v222, v90
	s_waitcnt lgkmcnt(0)
	v_add_f32_e32 v90, v90, v91
	v_fmamk_f32 v90, v90, 0x3a000000, v204
	v_cmp_gt_f32_e32 vcc, s34, v90
	v_mul_f32_e32 v91, 0x4b800000, v90
	s_waitcnt lgkmcnt(0)
	v_pk_mul_f32 v[64:65], v[64:65], v[94:95]
	v_cndmask_b32_e32 v90, v90, v91, vcc
	v_rsq_f32_e32 v90, v90
	v_pk_mul_f32 v[62:63], v[62:63], v[96:97]
	v_mul_f32_e32 v91, 0x45800000, v90
	v_cndmask_b32_e32 v92, v90, v91, vcc
	v_pk_mul_f32 v[64:65], v[64:65], v[92:93] op_sel_hi:[1,0]
	v_pk_mul_f32 v[62:63], v[62:63], v[92:93] op_sel_hi:[1,0]
	v_bfe_u32 v93, v64, 16, 1
	v_add3_u32 v64, v64, v93, s46
	v_bfe_u32 v93, v65, 16, 1
	v_lshrrev_b32_e32 v64, 16, v64
	v_add3_u32 v65, v65, v93, s46
	v_and_or_b32 v64, v65, s33, v64
	v_bfe_u32 v65, v62, 16, 1
	v_add3_u32 v62, v62, v65, s46
	v_bfe_u32 v65, v63, 16, 1
	v_lshrrev_b32_e32 v62, 16, v62
	v_add3_u32 v63, v63, v65, s46
	v_lshl_add_u64 v[90:91], v[8:9], 0, s[4:5]
	v_and_or_b32 v65, v63, s33, v62
	global_store_dwordx2 v[90:91], v[64:65], off
	ds_read_b128 v[62:65], v253 offset:9216
	s_andn2_b64 vcc, exec, s[80:81]
	s_waitcnt lgkmcnt(0)
	v_pk_mul_f32 v[62:63], v[68:69], v[62:63]
	s_nop 0
	v_pk_mul_f32 v[62:63], v[62:63], v[92:93] op_sel_hi:[1,0]
	v_pk_mul_f32 v[64:65], v[66:67], v[64:65]
	v_bfe_u32 v66, v62, 16, 1
	v_add3_u32 v62, v62, v66, s46
	v_bfe_u32 v66, v63, 16, 1
	v_pk_mul_f32 v[64:65], v[64:65], v[92:93] op_sel_hi:[1,0]
	v_lshrrev_b32_e32 v62, 16, v62
	v_add3_u32 v63, v63, v66, s46
	v_and_or_b32 v62, v63, s33, v62
	v_bfe_u32 v63, v64, 16, 1
	v_add3_u32 v63, v64, v63, s46
	v_bfe_u32 v64, v65, 16, 1
	v_lshrrev_b32_e32 v63, 16, v63
	v_add3_u32 v64, v65, v64, s46
	v_and_or_b32 v63, v64, s33, v63
	global_store_dwordx2 v[90:91], v[62:63], off offset:512
	ds_read_b128 v[62:65], v253 offset:10240
	s_waitcnt lgkmcnt(0)
	v_pk_mul_f32 v[62:63], v[76:77], v[62:63]
	s_nop 0
	v_pk_mul_f32 v[62:63], v[62:63], v[92:93] op_sel_hi:[1,0]
	v_pk_mul_f32 v[64:65], v[74:75], v[64:65]
	v_bfe_u32 v66, v62, 16, 1
	v_add3_u32 v62, v62, v66, s46
	v_bfe_u32 v66, v63, 16, 1
	v_pk_mul_f32 v[64:65], v[64:65], v[92:93] op_sel_hi:[1,0]
	v_lshrrev_b32_e32 v62, 16, v62
	v_add3_u32 v63, v63, v66, s46
	v_and_or_b32 v62, v63, s33, v62
	v_bfe_u32 v63, v64, 16, 1
	v_add3_u32 v63, v64, v63, s46
	v_bfe_u32 v64, v65, 16, 1
	v_lshrrev_b32_e32 v63, 16, v63
	v_add3_u32 v64, v65, v64, s46
	v_and_or_b32 v63, v64, s33, v63
	global_store_dwordx2 v[90:91], v[62:63], off offset:1024
	ds_read_b128 v[62:65], v253 offset:11264
	s_waitcnt lgkmcnt(0)
	v_pk_mul_f32 v[62:63], v[88:89], v[62:63]
	s_nop 0
	v_pk_mul_f32 v[62:63], v[62:63], v[92:93] op_sel_hi:[1,0]
	v_pk_mul_f32 v[64:65], v[86:87], v[64:65]
	v_bfe_u32 v66, v62, 16, 1
	v_add3_u32 v62, v62, v66, s46
	v_bfe_u32 v66, v63, 16, 1
	v_pk_mul_f32 v[64:65], v[64:65], v[92:93] op_sel_hi:[1,0]
	v_lshrrev_b32_e32 v62, 16, v62
	v_add3_u32 v63, v63, v66, s46
	v_and_or_b32 v62, v63, s33, v62
	v_bfe_u32 v63, v64, 16, 1
	v_add3_u32 v63, v64, v63, s46
	v_bfe_u32 v64, v65, 16, 1
	v_lshrrev_b32_e32 v63, 16, v63
	v_add3_u32 v64, v65, v64, s46
	v_and_or_b32 v63, v64, s33, v63
	global_store_dwordx2 v[90:91], v[62:63], off offset:1536
	ds_read_b128 v[62:65], v253 offset:12288
	s_waitcnt lgkmcnt(0)
; __device__ __forceinline__ unsigned pk2(float lo, float hi) { const f32x2 v = {lo, hi}; const bf16x2_cv b = __builtin_convertvector(v, bf16x2_cv); return __builtin_bit_cast(unsigned, b); }
; __device__ __forceinline__ unsigned pk2(float lo, float hi) { return f2bf(lo) | (f2bf(hi) << 16); }
; template <bool XIN_BF, bool XOUT_BF>
; __device__ __forceinline__ void ew_rows(const void* xsrc, void* xdst, const bf16* y, float scale, const float* gpost, const float* gpre, bf16* hout, int gw, int ngw, int lane) {
;     ...
;         for (int r = 0; r < NR; ++r) { const int row = row0 + r * ngw; if (row >= TOK) break;
;             f32x4 xv[8];
; #pragma unroll
;             for (int j = 0; j < 8; ++j) { if (XIN_BF) { const v2u w = xb[XIN_BF ? r : 0][j]; xv[j] = (f32x4){__uint_as_float(w.x << 16), __uint_as_float(w.x & 0xffff0000u), __uint_as_float(w.y << 16), __uint_as_float(w.y & 0xffff0000u)}; } else xv[j] = xf[XIN_BF ? 0 : r][j]; }
;             if (y) {
;                 f32x4 yv[8]; float ss = 0.f;
; #pragma unroll
;                 for (int j = 0; j < 8; ++j) { const v2u w = yb[r][j]; yv[j] = (f32x4){__uint_as_float(w.x << 16), __uint_as_float(w.x & 0xffff0000u), __uint_as_float(w.y << 16), __uint_as_float(w.y & 0xffff0000u)};
;                     ss += (yv[j].x * yv[j].x + yv[j].y * yv[j].y) + (yv[j].z * yv[j].z + yv[j].w * yv[j].w); }
;     ...
;                 for (int j = 0; j < 8; ++j) { const f32x4 g = ((const f32x4*)gpre)[lane + 64 * j]; const f32x4 t = xv[j] * g * rs2; ho[64 * j] = (v2u){pk2(t.x, t.y), pk2(t.z, t.w)}; }
	v_pk_mul_f32 v[62:63], v[84:85], v[62:63]
	s_nop 0
	v_pk_mul_f32 v[62:63], v[62:63], v[92:93] op_sel_hi:[1,0]
	v_pk_mul_f32 v[64:65], v[80:81], v[64:65]
	v_bfe_u32 v66, v62, 16, 1
	v_add3_u32 v62, v62, v66, s46
	v_bfe_u32 v66, v63, 16, 1
	v_pk_mul_f32 v[64:65], v[64:65], v[92:93] op_sel_hi:[1,0]
	v_lshrrev_b32_e32 v62, 16, v62
	v_add3_u32 v63, v63, v66, s46
	v_and_or_b32 v62, v63, s33, v62
	v_bfe_u32 v63, v64, 16, 1
	v_add3_u32 v63, v64, v63, s46
	v_bfe_u32 v64, v65, 16, 1
	v_lshrrev_b32_e32 v63, 16, v63
	v_add3_u32 v64, v65, v64, s46
	v_and_or_b32 v63, v64, s33, v63
	global_store_dwordx2 v[90:91], v[62:63], off offset:2048
	ds_read_b128 v[62:65], v253 offset:13312
	s_waitcnt lgkmcnt(0)
	v_pk_mul_f32 v[62:63], v[82:83], v[62:63]
	s_nop 0
	v_pk_mul_f32 v[62:63], v[62:63], v[92:93] op_sel_hi:[1,0]
	v_pk_mul_f32 v[64:65], v[78:79], v[64:65]
	v_bfe_u32 v66, v62, 16, 1
	v_add3_u32 v62, v62, v66, s46
	v_bfe_u32 v66, v63, 16, 1
	v_pk_mul_f32 v[64:65], v[64:65], v[92:93] op_sel_hi:[1,0]
	v_lshrrev_b32_e32 v62, 16, v62
	v_add3_u32 v63, v63, v66, s46
	v_and_or_b32 v62, v63, s33, v62
	v_bfe_u32 v63, v64, 16, 1
	v_add3_u32 v63, v64, v63, s46
	v_bfe_u32 v64, v65, 16, 1
	v_lshrrev_b32_e32 v63, 16, v63
	v_add3_u32 v64, v65, v64, s46
	v_and_or_b32 v63, v64, s33, v63
	global_store_dwordx2 v[90:91], v[62:63], off offset:2560
	ds_read_b128 v[62:65], v253 offset:14336
	s_waitcnt lgkmcnt(0)
	v_pk_mul_f32 v[62:63], v[72:73], v[62:63]
	s_nop 0
	v_pk_mul_f32 v[62:63], v[62:63], v[92:93] op_sel_hi:[1,0]
	v_pk_mul_f32 v[64:65], v[70:71], v[64:65]
	v_bfe_u32 v66, v62, 16, 1
	v_add3_u32 v62, v62, v66, s46
	v_bfe_u32 v66, v63, 16, 1
	v_pk_mul_f32 v[64:65], v[64:65], v[92:93] op_sel_hi:[1,0]
	v_lshrrev_b32_e32 v62, 16, v62
	v_add3_u32 v63, v63, v66, s46
	v_and_or_b32 v62, v63, s33, v62
	v_bfe_u32 v63, v64, 16, 1
	v_add3_u32 v63, v64, v63, s46
	v_bfe_u32 v64, v65, 16, 1
	v_lshrrev_b32_e32 v63, 16, v63
	v_add3_u32 v64, v65, v64, s46
	v_and_or_b32 v63, v64, s33, v63
	global_store_dwordx2 v[90:91], v[62:63], off offset:3072
	ds_read_b128 v[62:65], v253 offset:15360
	s_waitcnt lgkmcnt(0)
	v_pk_mul_f32 v[2:3], v[2:3], v[62:63]
	s_nop 0
	v_pk_mul_f32 v[2:3], v[2:3], v[92:93] op_sel_hi:[1,0]
	v_pk_mul_f32 v[0:1], v[0:1], v[64:65]
	v_bfe_u32 v62, v2, 16, 1
	v_add3_u32 v2, v2, v62, s46
	v_bfe_u32 v62, v3, 16, 1
	v_pk_mul_f32 v[0:1], v[0:1], v[92:93] op_sel_hi:[1,0]
	v_lshrrev_b32_e32 v2, 16, v2
	v_add3_u32 v3, v3, v62, s46
	v_and_or_b32 v2, v3, s33, v2
	v_bfe_u32 v3, v0, 16, 1
	v_add3_u32 v0, v0, v3, s46
	v_bfe_u32 v3, v1, 16, 1
	v_lshrrev_b32_e32 v0, 16, v0
	v_add3_u32 v1, v1, v3, s46
	v_and_or_b32 v3, v1, s33, v0
	global_store_dwordx2 v[90:91], v[2:3], off offset:3584
	s_cbranch_vccnz .LBB0_746
	v_and_b32_e32 v99, 0xffff0000, v44
	v_and_b32_e32 v101, 0xffff0000, v45
	v_lshlrev_b32_e32 v98, 16, v44
	v_lshlrev_b32_e32 v100, 16, v45
	v_mul_f32_e32 v44, v101, v101
	v_and_b32_e32 v97, 0xffff0000, v43
	v_and_b32_e32 v96, 0xffff0000, v42
	v_lshlrev_b32_e32 v91, 16, v38
	v_and_b32_e32 v89, 0xffff0000, v38
	v_mul_f32_e32 v38, v99, v99
	v_lshlrev_b32_e32 v84, 16, v60
	v_and_b32_e32 v85, 0xffff0000, v60
	v_lshlrev_b32_e32 v86, 16, v61
	v_and_b32_e32 v87, 0xffff0000, v61
	v_lshlrev_b32_e32 v78, 16, v58
	v_and_b32_e32 v79, 0xffff0000, v58
	v_lshlrev_b32_e32 v80, 16, v59
	v_and_b32_e32 v81, 0xffff0000, v59
	v_lshlrev_b32_e32 v58, 16, v46
	v_and_b32_e32 v59, 0xffff0000, v46
	v_lshlrev_b32_e32 v60, 16, v47
	v_and_b32_e32 v61, 0xffff0000, v47
	v_pk_fma_f32 v[46:47], v[100:101], v[100:101], v[44:45] op_sel_hi:[1,1,0]
	v_lshlrev_b32_e32 v95, 16, v43
	v_lshlrev_b32_e32 v94, 16, v42
	v_pk_mul_f32 v[42:43], v[96:97], v[96:97]
	v_lshlrev_b32_e32 v92, 16, v39
	v_and_b32_e32 v93, 0xffff0000, v39
	v_pk_fma_f32 v[38:39], v[98:99], v[98:99], v[38:39] op_sel_hi:[1,1,0]
	v_lshlrev_b32_e32 v0, 16, v48
	v_and_b32_e32 v1, 0xffff0000, v48
	v_lshlrev_b32_e32 v2, 16, v49
	v_and_b32_e32 v3, 0xffff0000, v49
	v_pk_fma_f32 v[48:49], v[94:95], v[94:95], v[42:43]
	v_lshlrev_b32_e32 v42, 16, v40
	v_and_b32_e32 v43, 0xffff0000, v40
	v_lshlrev_b32_e32 v44, 16, v41
	v_and_b32_e32 v45, 0xffff0000, v41
	v_mov_b32_e32 v90, v38
	v_mov_b32_e32 v40, v46
	v_mov_b32_e32 v41, v91
	v_pk_add_f32 v[38:39], v[38:39], v[46:47]
	v_pk_mul_f32 v[40:41], v[90:91], v[40:41]
	v_lshlrev_b32_e32 v68, 16, v50
	v_and_b32_e32 v69, 0xffff0000, v50
	v_mul_f32_e32 v50, v89, v89
	v_mov_b32_e32 v39, v41
	v_pk_add_f32 v[40:41], v[48:49], v[48:49] op_sel:[0,1] op_sel_hi:[1,0]
	v_mul_f32_e32 v46, v45, v45
	v_mov_b32_e32 v41, v50
	v_pk_add_f32 v[38:39], v[38:39], v[40:41]
	v_mul_f32_e32 v40, v43, v43
	v_lshlrev_b32_e32 v70, 16, v51
	v_and_b32_e32 v71, 0xffff0000, v51
	v_mul_f32_e32 v51, v92, v92
	v_mul_f32_e32 v62, v93, v93
	v_pk_fma_f32 v[40:41], v[42:43], v[42:43], v[40:41] op_sel_hi:[1,1,0]
	v_pk_fma_f32 v[46:47], v[44:45], v[44:45], v[46:47] op_sel_hi:[1,1,0]
	v_mov_b32_e32 v41, v51
	v_mov_b32_e32 v47, v62
	v_and_b32_e32 v83, 0xffff0000, v37
	v_and_b32_e32 v82, 0xffff0000, v36
	v_pk_add_f32 v[40:41], v[40:41], v[46:47]
	v_lshlrev_b32_e32 v49, 16, v37
	v_lshlrev_b32_e32 v48, 16, v36
	v_pk_mul_f32 v[36:37], v[82:83], v[82:83]
	v_pk_add_f32 v[102:103], v[38:39], v[40:41]
	v_pk_fma_f32 v[36:37], v[48:49], v[48:49], v[36:37]
	v_and_b32_e32 v51, 0xffff0000, v35
	v_pk_add_f32 v[36:37], v[36:37], v[36:37] op_sel:[0,1] op_sel_hi:[1,0]
	v_and_b32_e32 v50, 0xffff0000, v34
	v_lshlrev_b32_e32 v67, 16, v30
	v_and_b32_e32 v65, 0xffff0000, v30
	v_lshlrev_b32_e32 v62, 16, v31
	v_and_b32_e32 v63, 0xffff0000, v31
	v_pk_add_f32 v[30:31], v[102:103], v[102:103] op_sel:[0,1] op_sel_hi:[1,0]
	v_lshlrev_b32_e32 v47, 16, v35
	v_lshlrev_b32_e32 v46, 16, v34
	v_pk_mul_f32 v[34:35], v[50:51], v[50:51]
	v_lshlrev_b32_e32 v38, 16, v32
	v_and_b32_e32 v39, 0xffff0000, v32
	v_lshlrev_b32_e32 v40, 16, v33
	v_and_b32_e32 v41, 0xffff0000, v33
	v_mov_b32_e32 v66, v30
	v_mov_b32_e32 v32, v36
	v_mov_b32_e32 v33, v67
	v_pk_fma_f32 v[34:35], v[46:47], v[46:47], v[34:35]
	v_pk_add_f32 v[30:31], v[30:31], v[36:37]
	v_pk_mul_f32 v[32:33], v[66:67], v[32:33]
	v_mul_f32_e32 v64, v65, v65
	v_mov_b32_e32 v31, v33
	v_pk_add_f32 v[32:33], v[34:35], v[34:35] op_sel:[0,1] op_sel_hi:[1,0]
	v_mul_f32_e32 v34, v41, v41
	v_mov_b32_e32 v33, v64
	v_pk_add_f32 v[30:31], v[30:31], v[32:33]
	v_mul_f32_e32 v32, v39, v39
	v_mul_f32_e32 v88, v62, v62
	v_mul_f32_e32 v90, v63, v63
	v_pk_fma_f32 v[32:33], v[38:39], v[38:39], v[32:33] op_sel_hi:[1,1,0]
	v_pk_fma_f32 v[34:35], v[40:41], v[40:41], v[34:35] op_sel_hi:[1,1,0]
	v_mov_b32_e32 v33, v88
	v_mov_b32_e32 v35, v90
	v_pk_add_f32 v[32:33], v[32:33], v[34:35]
	v_lshlrev_b32_e32 v74, 16, v56
	v_pk_add_f32 v[30:31], v[30:31], v[32:33]
	v_and_b32_e32 v75, 0xffff0000, v56
	v_add_f32_e32 v30, v30, v31
	ds_bpermute_b32 v31, v182, v30
	v_lshlrev_b32_e32 v76, 16, v57
	v_and_b32_e32 v77, 0xffff0000, v57
	v_mov_b32_e32 v88, v91
	v_lshlrev_b32_e32 v56, 16, v54
	s_waitcnt lgkmcnt(0)
; __device__ __forceinline__ unsigned pk2(float lo, float hi) { const f32x2 v = {lo, hi}; const bf16x2_cv b = __builtin_convertvector(v, bf16x2_cv); return __builtin_bit_cast(unsigned, b); }
; __device__ __forceinline__ unsigned pk2(float lo, float hi) { return f2bf(lo) | (f2bf(hi) << 16); }
; template <bool XIN_BF, bool XOUT_BF>
; __device__ __forceinline__ void ew_rows(const void* xsrc, void* xdst, const bf16* y, float scale, const float* gpost, const float* gpre, bf16* hout, int gw, int ngw, int lane) {
;     ...
;                     ss += (yv[j].x * yv[j].x + yv[j].y * yv[j].y) + (yv[j].z * yv[j].z + yv[j].w * yv[j].w); }
;                 const float rs = rsqrtf(wave_sum(ss) * (1.0f / DM) + 1e-6f) * scale;
; #pragma unroll
;                 for (int j = 0; j < 8; ++j) { const f32x4 g = ((const f32x4*)gpost)[lane + 64 * j]; xv[j] = xv[j] + yv[j] * g * rs; }
;                 if (XOUT_BF) { v2u* xo = (v2u*)((bf16*)xdst + (size_t)row * DM) + lane;
; #pragma unroll
;                     for (int j = 0; j < 8; ++j) xo[64 * j] = (v2u){pk2(xv[j].x, xv[j].y), pk2(xv[j].z, xv[j].w)};
	v_add_f32_e32 v30, v30, v31
	ds_bpermute_b32 v31, v198, v30
	v_and_b32_e32 v57, 0xffff0000, v54
	v_lshlrev_b32_e32 v54, 16, v55
	v_and_b32_e32 v55, 0xffff0000, v55
	v_lshlrev_b32_e32 v72, 16, v52
	s_waitcnt lgkmcnt(0)
	v_add_f32_e32 v30, v30, v31
	ds_bpermute_b32 v31, v199, v30
	v_and_b32_e32 v73, 0xffff0000, v52
	v_lshlrev_b32_e32 v52, 16, v53
	v_and_b32_e32 v53, 0xffff0000, v53
	v_mov_b32_e32 v64, v67
	s_waitcnt lgkmcnt(0)
	v_add_f32_e32 v30, v30, v31
	ds_bpermute_b32 v31, v200, v30
	s_ashr_i32 s79, s78, 31
	s_lshl_b64 s[4:5], s[78:79], 12
	s_waitcnt lgkmcnt(0)
	v_add_f32_e32 v30, v30, v31
	ds_bpermute_b32 v31, v201, v30
	s_waitcnt lgkmcnt(0)
	v_add_f32_e32 v30, v30, v31
	ds_bpermute_b32 v31, v222, v30
	s_waitcnt lgkmcnt(0)
	v_add_f32_e32 v30, v30, v31
	v_fmamk_f32 v30, v30, 0x3a000000, v204
	v_cmp_gt_f32_e32 vcc, s34, v30
	v_mul_f32_e32 v31, 0x4b800000, v30
	s_nop 0
	v_cndmask_b32_e32 v30, v30, v31, vcc
	v_rsq_f32_e32 v30, v30
	s_nop 0
	v_mul_f32_e32 v31, 0x45800000, v30
	v_cndmask_b32_e32 v30, v30, v31, vcc
	v_mul_f32_e32 v66, v163, v30
	ds_read_b128 v[30:33], v253
	s_waitcnt lgkmcnt(0)
	v_pk_mul_f32 v[34:35], v[30:31], v[98:99]
	v_pk_mul_f32 v[30:31], v[32:33], v[100:101]
	v_pk_fma_f32 v[32:33], v[34:35], v[66:67], v[84:85] op_sel_hi:[1,0,1]
	ds_read_b128 v[34:37], v253 offset:1024
	v_mov_b32_e32 v84, v94
	v_mov_b32_e32 v85, v96
	v_mov_b32_e32 v96, v95
	v_pk_fma_f32 v[30:31], v[30:31], v[66:67], v[86:87] op_sel_hi:[1,0,1]
	s_waitcnt lgkmcnt(0)
	v_pk_mul_f32 v[84:85], v[34:35], v[84:85]
	v_pk_mul_f32 v[34:35], v[36:37], v[96:97]
	v_pk_fma_f32 v[36:37], v[84:85], v[66:67], v[78:79] op_sel_hi:[1,0,1]
	v_pk_fma_f32 v[34:35], v[34:35], v[66:67], v[80:81] op_sel_hi:[1,0,1]
	ds_read_b128 v[78:81], v253 offset:2048
	s_waitcnt lgkmcnt(0)
	v_pk_mul_f32 v[78:79], v[78:79], v[42:43]
	v_pk_mul_f32 v[42:43], v[80:81], v[44:45]
	v_pk_fma_f32 v[44:45], v[78:79], v[66:67], v[74:75] op_sel_hi:[1,0,1]
	v_pk_fma_f32 v[42:43], v[42:43], v[66:67], v[76:77] op_sel_hi:[1,0,1]
	ds_read_b128 v[74:77], v253 offset:3072
	v_mov_b32_e32 v78, v48
	v_mov_b32_e32 v79, v82
	v_mov_b32_e32 v82, v49
	s_waitcnt lgkmcnt(0)
	v_pk_mul_f32 v[76:77], v[92:93], v[76:77]
	v_pk_mul_f32 v[74:75], v[88:89], v[74:75]
	v_pk_fma_f32 v[54:55], v[76:77], v[66:67], v[54:55] op_sel_hi:[1,0,1]
	v_pk_fma_f32 v[56:57], v[74:75], v[66:67], v[56:57] op_sel_hi:[1,0,1]
	ds_read_b128 v[74:77], v253 offset:4096
	s_waitcnt lgkmcnt(0)
	v_pk_mul_f32 v[74:75], v[74:75], v[78:79]
	v_pk_mul_f32 v[48:49], v[76:77], v[82:83]
	v_mov_b32_e32 v76, v47
	v_pk_fma_f32 v[48:49], v[48:49], v[66:67], v[52:53] op_sel_hi:[1,0,1]
	v_pk_fma_f32 v[52:53], v[74:75], v[66:67], v[72:73] op_sel_hi:[1,0,1]
	ds_read_b128 v[72:75], v253 offset:5120
	v_mov_b32_e32 v77, v51
	v_mov_b32_e32 v47, v50
	s_waitcnt lgkmcnt(0)
	v_pk_mul_f32 v[74:75], v[74:75], v[76:77]
	v_pk_mul_f32 v[46:47], v[72:73], v[46:47]
	s_nop 0
	v_pk_fma_f32 v[50:51], v[46:47], v[66:67], v[68:69] op_sel_hi:[1,0,1]
	v_pk_fma_f32 v[46:47], v[74:75], v[66:67], v[70:71] op_sel_hi:[1,0,1]
	ds_read_b128 v[68:71], v253 offset:6144
	s_waitcnt lgkmcnt(0)
	v_pk_mul_f32 v[70:71], v[70:71], v[40:41]
	v_pk_mul_f32 v[38:39], v[68:69], v[38:39]
	s_nop 0
	v_pk_fma_f32 v[40:41], v[38:39], v[66:67], v[0:1] op_sel_hi:[1,0,1]
	v_pk_fma_f32 v[38:39], v[70:71], v[66:67], v[2:3] op_sel_hi:[1,0,1]
	ds_read_b128 v[0:3], v253 offset:7168
	s_waitcnt lgkmcnt(0)
	v_pk_mul_f32 v[64:65], v[64:65], v[0:1]
	v_pk_mul_f32 v[0:1], v[62:63], v[2:3]
	v_bfe_u32 v62, v31, 16, 1
	v_pk_fma_f32 v[0:1], v[0:1], v[66:67], v[60:61] op_sel_hi:[1,0,1]
	v_bfe_u32 v60, v32, 16, 1
	v_add3_u32 v60, v32, v60, s46
	v_bfe_u32 v61, v33, 16, 1
	v_lshrrev_b32_e32 v60, 16, v60
	v_add3_u32 v61, v33, v61, s46
	v_and_or_b32 v60, v61, s33, v60
	v_bfe_u32 v61, v30, 16, 1
	v_add3_u32 v61, v30, v61, s46
	v_lshrrev_b32_e32 v61, 16, v61
	v_add3_u32 v62, v31, v62, s46
	v_pk_fma_f32 v[2:3], v[64:65], v[66:67], v[58:59] op_sel_hi:[1,0,1]
	v_lshl_add_u64 v[58:59], v[4:5], 0, s[4:5]
	v_and_or_b32 v61, v62, s33, v61
	global_store_dwordx2 v[58:59], v[60:61], off
	v_bfe_u32 v60, v36, 16, 1
	v_add3_u32 v60, v36, v60, s46
	v_bfe_u32 v61, v37, 16, 1
	v_lshrrev_b32_e32 v60, 16, v60
	v_add3_u32 v61, v37, v61, s46
	v_and_or_b32 v60, v61, s33, v60
	v_bfe_u32 v61, v34, 16, 1
	v_add3_u32 v61, v34, v61, s46
	v_bfe_u32 v62, v35, 16, 1
	v_lshrrev_b32_e32 v61, 16, v61
	v_add3_u32 v62, v35, v62, s46
	v_and_or_b32 v61, v62, s33, v61
	global_store_dwordx2 v[58:59], v[60:61], off offset:512
	v_bfe_u32 v60, v44, 16, 1
	v_add3_u32 v60, v44, v60, s46
	v_bfe_u32 v61, v45, 16, 1
	v_lshrrev_b32_e32 v60, 16, v60
	v_add3_u32 v61, v45, v61, s46
	v_and_or_b32 v60, v61, s33, v60
	v_bfe_u32 v61, v42, 16, 1
	v_add3_u32 v61, v42, v61, s46
	v_bfe_u32 v62, v43, 16, 1
	v_lshrrev_b32_e32 v61, 16, v61
	v_add3_u32 v62, v43, v62, s46
	v_and_or_b32 v61, v62, s33, v61
	global_store_dwordx2 v[58:59], v[60:61], off offset:1024
	v_bfe_u32 v60, v56, 16, 1
	v_add3_u32 v60, v56, v60, s46
	v_bfe_u32 v61, v57, 16, 1
	v_lshrrev_b32_e32 v60, 16, v60
	v_add3_u32 v61, v57, v61, s46
	v_and_or_b32 v60, v61, s33, v60
	v_bfe_u32 v61, v54, 16, 1
	v_add3_u32 v61, v54, v61, s46
	v_bfe_u32 v62, v55, 16, 1
	v_lshrrev_b32_e32 v61, 16, v61
	v_add3_u32 v62, v55, v62, s46
	v_and_or_b32 v61, v62, s33, v61
	global_store_dwordx2 v[58:59], v[60:61], off offset:1536
	v_bfe_u32 v60, v52, 16, 1
	v_add3_u32 v60, v52, v60, s46
	v_bfe_u32 v61, v53, 16, 1
	v_lshrrev_b32_e32 v60, 16, v60
	v_add3_u32 v61, v53, v61, s46
	v_and_or_b32 v60, v61, s33, v60
	v_bfe_u32 v61, v48, 16, 1
	v_add3_u32 v61, v48, v61, s46
	v_bfe_u32 v62, v49, 16, 1
	v_lshrrev_b32_e32 v61, 16, v61
	v_add3_u32 v62, v49, v62, s46
; __device__ __forceinline__ unsigned pk2(float lo, float hi) { const f32x2 v = {lo, hi}; const bf16x2_cv b = __builtin_convertvector(v, bf16x2_cv); return __builtin_bit_cast(unsigned, b); }
; __device__ __forceinline__ unsigned pk2(float lo, float hi) { return f2bf(lo) | (f2bf(hi) << 16); }
; template <bool XIN_BF, bool XOUT_BF>
; __device__ __forceinline__ void ew_rows(const void* xsrc, void* xdst, const bf16* y, float scale, const float* gpost, const float* gpre, bf16* hout, int gw, int ngw, int lane) {
;     ...
;                     for (int j = 0; j < 8; ++j) xo[64 * j] = (v2u){pk2(xv[j].x, xv[j].y), pk2(xv[j].z, xv[j].w)};
;                 } else { f32x4* xo = (f32x4*)((float*)xdst + (size_t)row * DM) + lane;
; #pragma unroll
;                     for (int j = 0; j < 8; ++j) xo[64 * j] = xv[j]; }
;             }
;             if (hout) {
;                 float s2 = 0.f;
; #pragma unroll
;                 for (int j = 0; j < 8; ++j) s2 += (xv[j].x * xv[j].x + xv[j].y * xv[j].y) + (xv[j].z * xv[j].z + xv[j].w * xv[j].w);
;                 const float rs2 = rsqrtf(wave_sum(s2) * (1.0f / DM) + 1e-6f);
;                 v2u* ho = (v2u*)(hout + (size_t)row * DM) + lane;
; #pragma unroll
;                 for (int j = 0; j < 8; ++j) { const f32x4 g = ((const f32x4*)gpre)[lane + 64 * j]; const f32x4 t = xv[j] * g * rs2; ho[64 * j] = (v2u){pk2(t.x, t.y), pk2(t.z, t.w)}; }
	v_and_or_b32 v61, v62, s33, v61
	global_store_dwordx2 v[58:59], v[60:61], off offset:2048
	v_bfe_u32 v60, v50, 16, 1
	v_add3_u32 v60, v50, v60, s46
	v_bfe_u32 v61, v51, 16, 1
	v_lshrrev_b32_e32 v60, 16, v60
	v_add3_u32 v61, v51, v61, s46
	v_and_or_b32 v60, v61, s33, v60
	v_bfe_u32 v61, v46, 16, 1
	v_add3_u32 v61, v46, v61, s46
	v_bfe_u32 v62, v47, 16, 1
	v_lshrrev_b32_e32 v61, 16, v61
	v_add3_u32 v62, v47, v62, s46
	v_and_or_b32 v61, v62, s33, v61
	global_store_dwordx2 v[58:59], v[60:61], off offset:2560
	v_bfe_u32 v60, v40, 16, 1
	v_add3_u32 v60, v40, v60, s46
	v_bfe_u32 v61, v41, 16, 1
	v_lshrrev_b32_e32 v60, 16, v60
	v_add3_u32 v61, v41, v61, s46
	v_and_or_b32 v60, v61, s33, v60
	v_bfe_u32 v61, v38, 16, 1
	v_add3_u32 v61, v38, v61, s46
	v_bfe_u32 v62, v39, 16, 1
	v_lshrrev_b32_e32 v61, 16, v61
	v_add3_u32 v62, v39, v62, s46
	v_and_or_b32 v61, v62, s33, v61
	global_store_dwordx2 v[58:59], v[60:61], off offset:3072
	v_bfe_u32 v60, v2, 16, 1
	v_add3_u32 v60, v2, v60, s46
	v_bfe_u32 v61, v3, 16, 1
	v_lshrrev_b32_e32 v60, 16, v60
	v_add3_u32 v61, v3, v61, s46
	v_and_or_b32 v60, v61, s33, v60
	v_bfe_u32 v61, v0, 16, 1
	v_add3_u32 v61, v0, v61, s46
	v_bfe_u32 v62, v1, 16, 1
	v_lshrrev_b32_e32 v61, 16, v61
	v_add3_u32 v62, v1, v62, s46
	v_and_or_b32 v61, v62, s33, v61
	global_store_dwordx2 v[58:59], v[60:61], off offset:3584
	v_mov_b32_e32 v60, v33
	v_mov_b32_e32 v61, v37
	v_mov_b32_e32 v58, v32
	v_mov_b32_e32 v59, v36
	v_pk_mul_f32 v[60:61], v[60:61], v[60:61]
	v_mov_b32_e32 v62, v31
	v_mov_b32_e32 v63, v35
	v_pk_fma_f32 v[58:59], v[58:59], v[58:59], v[60:61]
	v_mov_b32_e32 v60, v30
	v_mov_b32_e32 v61, v34
	v_pk_mul_f32 v[62:63], v[62:63], v[62:63]
	s_nop 0
	v_pk_fma_f32 v[60:61], v[60:61], v[60:61], v[62:63]
	v_pk_mul_f32 v[62:63], v[44:45], v[44:45]
	v_pk_add_f32 v[58:59], v[58:59], v[60:61]
	v_pk_mul_f32 v[60:61], v[42:43], v[42:43]
	v_pk_add_f32 v[58:59], v[58:59], v[58:59] op_sel_hi:[0,1]
	v_pk_mov_b32 v[64:65], v[62:63], v[60:61] op_sel:[1,0]
	v_mov_b32_e32 v63, v61
	v_mul_f32_e32 v58, v56, v56
	v_pk_add_f32 v[60:61], v[64:65], v[62:63]
	v_pk_fma_f32 v[62:63], v[56:57], v[56:57], v[58:59] op_sel_hi:[1,1,0]
	v_mul_f32_e32 v58, v54, v54
	v_pk_add_f32 v[60:61], v[60:61], v[60:61] op_sel_hi:[0,1]
	v_pk_fma_f32 v[64:65], v[54:55], v[54:55], v[58:59] op_sel_hi:[1,1,0]
	v_mul_f32_e32 v62, v52, v52
	v_mul_f32_e32 v64, v53, v53
	v_mul_f32_e32 v60, v48, v48
	v_mul_f32_e32 v58, v49, v49
	v_pk_add_f32 v[62:63], v[62:63], v[64:65]
	v_pk_add_f32 v[58:59], v[60:61], v[58:59]
	v_pk_mul_f32 v[60:61], v[46:47], v[46:47]
	v_pk_add_f32 v[58:59], v[62:63], v[58:59]
	v_pk_mul_f32 v[62:63], v[50:51], v[50:51]
	v_pk_add_f32 v[58:59], v[58:59], v[58:59] op_sel_hi:[0,1]
	v_pk_mov_b32 v[64:65], v[62:63], v[60:61] op_sel:[1,0]
	v_mov_b32_e32 v63, v61
	v_mul_f32_e32 v58, v40, v40
	v_pk_add_f32 v[60:61], v[64:65], v[62:63]
	v_pk_fma_f32 v[62:63], v[40:41], v[40:41], v[58:59] op_sel_hi:[1,1,0]
	v_mul_f32_e32 v58, v38, v38
	v_pk_add_f32 v[60:61], v[60:61], v[60:61] op_sel_hi:[0,1]
	v_pk_fma_f32 v[64:65], v[38:39], v[38:39], v[58:59] op_sel_hi:[1,1,0]
	v_mul_f32_e32 v62, v2, v2
	v_mul_f32_e32 v64, v3, v3
	v_mul_f32_e32 v60, v0, v0
	v_mul_f32_e32 v58, v1, v1
	v_pk_add_f32 v[62:63], v[62:63], v[64:65]
	v_pk_add_f32 v[58:59], v[60:61], v[58:59]
	s_nop 0
	v_pk_add_f32 v[58:59], v[62:63], v[58:59]
	ds_read_b128 v[62:65], v253 offset:8192
	v_add_f32_e32 v58, v58, v59
	ds_bpermute_b32 v59, v182, v58
	s_waitcnt lgkmcnt(0)
	v_add_f32_e32 v58, v58, v59
	ds_bpermute_b32 v59, v198, v58
	s_waitcnt lgkmcnt(0)
	v_add_f32_e32 v58, v58, v59
	ds_bpermute_b32 v59, v199, v58
	s_waitcnt lgkmcnt(0)
	v_add_f32_e32 v58, v58, v59
	ds_bpermute_b32 v59, v200, v58
	s_waitcnt lgkmcnt(0)
	v_add_f32_e32 v58, v58, v59
	ds_bpermute_b32 v59, v201, v58
	s_waitcnt lgkmcnt(0)
	v_add_f32_e32 v58, v58, v59
	ds_bpermute_b32 v59, v222, v58
	s_waitcnt lgkmcnt(0)
	v_add_f32_e32 v58, v58, v59
	v_fmamk_f32 v58, v58, 0x3a000000, v204
	v_cmp_gt_f32_e32 vcc, s34, v58
	v_mul_f32_e32 v59, 0x4b800000, v58
	s_waitcnt lgkmcnt(0)
	v_pk_mul_f32 v[32:33], v[32:33], v[62:63]
	v_cndmask_b32_e32 v58, v58, v59, vcc
	v_rsq_f32_e32 v58, v58
	v_pk_mul_f32 v[30:31], v[30:31], v[64:65]
	v_mul_f32_e32 v59, 0x45800000, v58
	v_cndmask_b32_e32 v60, v58, v59, vcc
	v_pk_mul_f32 v[32:33], v[32:33], v[60:61] op_sel_hi:[1,0]
	v_pk_mul_f32 v[30:31], v[30:31], v[60:61] op_sel_hi:[1,0]
	v_bfe_u32 v61, v32, 16, 1
	v_add3_u32 v32, v32, v61, s46
	v_bfe_u32 v61, v33, 16, 1
	v_lshrrev_b32_e32 v32, 16, v32
	v_add3_u32 v33, v33, v61, s46
	v_and_or_b32 v32, v33, s33, v32
	v_bfe_u32 v33, v30, 16, 1
	v_add3_u32 v30, v30, v33, s46
	v_bfe_u32 v33, v31, 16, 1
	v_lshrrev_b32_e32 v30, 16, v30
	v_add3_u32 v31, v31, v33, s46
	v_lshl_add_u64 v[58:59], v[8:9], 0, s[4:5]
	v_and_or_b32 v33, v31, s33, v30
	global_store_dwordx2 v[58:59], v[32:33], off
	ds_read_b128 v[30:33], v253 offset:9216
	s_waitcnt lgkmcnt(0)
; __device__ __forceinline__ unsigned pk2(float lo, float hi) { const f32x2 v = {lo, hi}; const bf16x2_cv b = __builtin_convertvector(v, bf16x2_cv); return __builtin_bit_cast(unsigned, b); }
; __device__ __forceinline__ unsigned pk2(float lo, float hi) { return f2bf(lo) | (f2bf(hi) << 16); }
; template <bool XIN_BF, bool XOUT_BF>
; __device__ __forceinline__ void ew_rows(const void* xsrc, void* xdst, const bf16* y, float scale, const float* gpost, const float* gpre, bf16* hout, int gw, int ngw, int lane) {
;     ...
;                 for (int j = 0; j < 8; ++j) { const f32x4 g = ((const f32x4*)gpre)[lane + 64 * j]; const f32x4 t = xv[j] * g * rs2; ho[64 * j] = (v2u){pk2(t.x, t.y), pk2(t.z, t.w)}; }
	v_pk_mul_f32 v[30:31], v[36:37], v[30:31]
	s_nop 0
	v_pk_mul_f32 v[30:31], v[30:31], v[60:61] op_sel_hi:[1,0]
	v_pk_mul_f32 v[32:33], v[34:35], v[32:33]
	v_bfe_u32 v34, v30, 16, 1
	v_add3_u32 v30, v30, v34, s46
	v_bfe_u32 v34, v31, 16, 1
	v_pk_mul_f32 v[32:33], v[32:33], v[60:61] op_sel_hi:[1,0]
	v_lshrrev_b32_e32 v30, 16, v30
	v_add3_u32 v31, v31, v34, s46
	v_and_or_b32 v30, v31, s33, v30
	v_bfe_u32 v31, v32, 16, 1
	v_add3_u32 v31, v32, v31, s46
	v_bfe_u32 v32, v33, 16, 1
	v_lshrrev_b32_e32 v31, 16, v31
	v_add3_u32 v32, v33, v32, s46
	v_and_or_b32 v31, v32, s33, v31
	global_store_dwordx2 v[58:59], v[30:31], off offset:512
	ds_read_b128 v[30:33], v253 offset:10240
	s_waitcnt lgkmcnt(0)
	v_pk_mul_f32 v[30:31], v[44:45], v[30:31]
	s_nop 0
	v_pk_mul_f32 v[30:31], v[30:31], v[60:61] op_sel_hi:[1,0]
	v_pk_mul_f32 v[32:33], v[42:43], v[32:33]
	v_bfe_u32 v34, v30, 16, 1
	v_add3_u32 v30, v30, v34, s46
	v_bfe_u32 v34, v31, 16, 1
	v_pk_mul_f32 v[32:33], v[32:33], v[60:61] op_sel_hi:[1,0]
	v_lshrrev_b32_e32 v30, 16, v30
	v_add3_u32 v31, v31, v34, s46
	v_and_or_b32 v30, v31, s33, v30
	v_bfe_u32 v31, v32, 16, 1
	v_add3_u32 v31, v32, v31, s46
	v_bfe_u32 v32, v33, 16, 1
	v_lshrrev_b32_e32 v31, 16, v31
	v_add3_u32 v32, v33, v32, s46
	v_and_or_b32 v31, v32, s33, v31
	global_store_dwordx2 v[58:59], v[30:31], off offset:1024
	ds_read_b128 v[30:33], v253 offset:11264
	s_waitcnt lgkmcnt(0)
	v_pk_mul_f32 v[30:31], v[56:57], v[30:31]
	s_nop 0
	v_pk_mul_f32 v[30:31], v[30:31], v[60:61] op_sel_hi:[1,0]
	v_pk_mul_f32 v[32:33], v[54:55], v[32:33]
	v_bfe_u32 v34, v30, 16, 1
	v_add3_u32 v30, v30, v34, s46
	v_bfe_u32 v34, v31, 16, 1
	v_pk_mul_f32 v[32:33], v[32:33], v[60:61] op_sel_hi:[1,0]
	v_lshrrev_b32_e32 v30, 16, v30
	v_add3_u32 v31, v31, v34, s46
	v_and_or_b32 v30, v31, s33, v30
	v_bfe_u32 v31, v32, 16, 1
	v_add3_u32 v31, v32, v31, s46
	v_bfe_u32 v32, v33, 16, 1
	v_lshrrev_b32_e32 v31, 16, v31
	v_add3_u32 v32, v33, v32, s46
	v_and_or_b32 v31, v32, s33, v31
	global_store_dwordx2 v[58:59], v[30:31], off offset:1536
	ds_read_b128 v[30:33], v253 offset:12288
	s_waitcnt lgkmcnt(0)
	v_pk_mul_f32 v[30:31], v[52:53], v[30:31]
	s_nop 0
	v_pk_mul_f32 v[30:31], v[30:31], v[60:61] op_sel_hi:[1,0]
	v_pk_mul_f32 v[32:33], v[48:49], v[32:33]
	v_bfe_u32 v34, v30, 16, 1
	v_add3_u32 v30, v30, v34, s46
	v_bfe_u32 v34, v31, 16, 1
	v_pk_mul_f32 v[32:33], v[32:33], v[60:61] op_sel_hi:[1,0]
	v_lshrrev_b32_e32 v30, 16, v30
	v_add3_u32 v31, v31, v34, s46
	v_and_or_b32 v30, v31, s33, v30
	v_bfe_u32 v31, v32, 16, 1
	v_add3_u32 v31, v32, v31, s46
	v_bfe_u32 v32, v33, 16, 1
	v_lshrrev_b32_e32 v31, 16, v31
	v_add3_u32 v32, v33, v32, s46
	v_and_or_b32 v31, v32, s33, v31
	global_store_dwordx2 v[58:59], v[30:31], off offset:2048
	ds_read_b128 v[30:33], v253 offset:13312
	s_waitcnt lgkmcnt(0)
	v_pk_mul_f32 v[30:31], v[50:51], v[30:31]
	s_nop 0
	v_pk_mul_f32 v[30:31], v[30:31], v[60:61] op_sel_hi:[1,0]
	v_pk_mul_f32 v[32:33], v[46:47], v[32:33]
	v_bfe_u32 v34, v30, 16, 1
	v_add3_u32 v30, v30, v34, s46
	v_bfe_u32 v34, v31, 16, 1
	v_pk_mul_f32 v[32:33], v[32:33], v[60:61] op_sel_hi:[1,0]
	v_lshrrev_b32_e32 v30, 16, v30
	v_add3_u32 v31, v31, v34, s46
	v_and_or_b32 v30, v31, s33, v30
	v_bfe_u32 v31, v32, 16, 1
	v_add3_u32 v31, v32, v31, s46
	v_bfe_u32 v32, v33, 16, 1
	v_lshrrev_b32_e32 v31, 16, v31
	v_add3_u32 v32, v33, v32, s46
	v_and_or_b32 v31, v32, s33, v31
	global_store_dwordx2 v[58:59], v[30:31], off offset:2560
	ds_read_b128 v[30:33], v253 offset:14336
	s_waitcnt lgkmcnt(0)
	v_pk_mul_f32 v[30:31], v[40:41], v[30:31]
	s_nop 0
	v_pk_mul_f32 v[30:31], v[30:31], v[60:61] op_sel_hi:[1,0]
	v_pk_mul_f32 v[32:33], v[38:39], v[32:33]
	v_bfe_u32 v34, v30, 16, 1
	v_add3_u32 v30, v30, v34, s46
	v_bfe_u32 v34, v31, 16, 1
	v_pk_mul_f32 v[32:33], v[32:33], v[60:61] op_sel_hi:[1,0]
	v_lshrrev_b32_e32 v30, 16, v30
	v_add3_u32 v31, v31, v34, s46
	v_and_or_b32 v30, v31, s33, v30
	v_bfe_u32 v31, v32, 16, 1
	v_add3_u32 v31, v32, v31, s46
	v_bfe_u32 v32, v33, 16, 1
	v_lshrrev_b32_e32 v31, 16, v31
	v_add3_u32 v32, v33, v32, s46
	v_and_or_b32 v31, v32, s33, v31
	global_store_dwordx2 v[58:59], v[30:31], off offset:3072
	ds_read_b128 v[30:33], v253 offset:15360
	s_waitcnt lgkmcnt(0)
	v_pk_mul_f32 v[2:3], v[2:3], v[30:31]
	s_nop 0
	v_pk_mul_f32 v[2:3], v[2:3], v[60:61] op_sel_hi:[1,0]
	v_pk_mul_f32 v[0:1], v[0:1], v[32:33]
	v_bfe_u32 v30, v2, 16, 1
	v_add3_u32 v2, v2, v30, s46
	v_bfe_u32 v30, v3, 16, 1
	v_pk_mul_f32 v[0:1], v[0:1], v[60:61] op_sel_hi:[1,0]
	v_lshrrev_b32_e32 v2, 16, v2
	v_add3_u32 v3, v3, v30, s46
	v_and_or_b32 v2, v3, s33, v2
	v_bfe_u32 v3, v0, 16, 1
	v_add3_u32 v0, v0, v3, s46
	v_bfe_u32 v3, v1, 16, 1
	v_lshrrev_b32_e32 v0, 16, v0
	v_add3_u32 v1, v1, v3, s46
	v_and_or_b32 v3, v1, s33, v0
	global_store_dwordx2 v[58:59], v[2:3], off offset:3584
	s_branch .LBB0_746

; template <bool XIN_BF, bool XOUT_BF>
; __device__ __forceinline__ void ew_rows(const void* xsrc, void* xdst, const bf16* y, float scale, const float* gpost, const float* gpre, bf16* hout, int gw, int ngw, int lane) {
;     ...
;     for (int row0 = gw; row0 < TOK; row0 += NR * ngw) {
;         v2u xb[XIN_BF ? NR : 1][8]; f32x4 xf[XIN_BF ? 1 : NR][8]; v2u yb[NR][8];
; #pragma unroll
;         for (int r = 0; r < NR; ++r) { const int row = (row0 + r * ngw < TOK) ? row0 + r * ngw : row0;
;             if (XIN_BF) { const v2u* xr = (const v2u*)((const bf16*)xsrc + (size_t)row * DM) + lane;
; #pragma unroll
;                 for (int j = 0; j < 8; ++j) xb[XIN_BF ? r : 0][j] = xr[64 * j];
;             } else { const f32x4* xr = (const f32x4*)((const float*)xsrc + (size_t)row * DM) + lane;
; #pragma unroll
;                 for (int j = 0; j < 8; ++j) xf[XIN_BF ? 0 : r][j] = xr[64 * j]; }
;             if (y) { const v2u* yr = (const v2u*)(y + (size_t)row * DM) + lane;
; #pragma unroll
;                 for (int j = 0; j < 8; ++j) yb[r][j] = yr[64 * j]; }
;         }
;         asm volatile("" ::: "memory");
; #pragma unroll
;         for (int r = 0; r < NR; ++r) { const int row = row0 + r * ngw; if (row >= TOK) break;
;             f32x4 xv[8];
; #pragma unroll
;             for (int j = 0; j < 8; ++j) { if (XIN_BF) { const v2u w = xb[XIN_BF ? r : 0][j]; xv[j] = (f32x4){__uint_as_float(w.x << 16), __uint_as_float(w.x & 0xffff0000u), __uint_as_float(w.y << 16), __uint_as_float(w.y & 0xffff0000u)}; } else xv[j] = xf[XIN_BF ? 0 : r][j]; }
;             if (y) {
;                 f32x4 yv[8]; float ss = 0.f;
; #pragma unroll
;                 for (int j = 0; j < 8; ++j) { const v2u w = yb[r][j]; yv[j] = (f32x4){__uint_as_float(w.x << 16), __uint_as_float(w.x & 0xffff0000u), __uint_as_float(w.y << 16), __uint_as_float(w.y & 0xffff0000u)};
;                     ss += (yv[j].x * yv[j].x + yv[j].y * yv[j].y) + (yv[j].z * yv[j].z + yv[j].w * yv[j].w); }
;                 const float rs = rsqrtf(wave_sum(ss) * (1.0f / DM) + 1e-6f) * scale;
.LBB0_772:
	v_lshl_add_u64 v[110:111], s[12:13], 0, v[160:161]
	v_add_co_u32_e32 v0, vcc, 0x10000000, v110
	global_load_dwordx4 v[60:63], v[92:93], off offset:-4096
	global_load_dwordx4 v[56:59], v[92:93], off offset:-3072
	global_load_dwordx4 v[52:55], v[92:93], off offset:-2048
	global_load_dwordx4 v[48:51], v[92:93], off offset:-1024
	global_load_dwordx4 v[44:47], v[92:93], off
	global_load_dwordx4 v[40:43], v[92:93], off offset:1024
	global_load_dwordx4 v[36:39], v[92:93], off offset:2048
	global_load_dwordx4 v[32:35], v[92:93], off offset:3072
	v_addc_co_u32_e32 v1, vcc, 0, v111, vcc
	global_load_dwordx2 v[112:113], v[0:1], off
	global_load_dwordx2 v[114:115], v[0:1], off offset:512
	global_load_dwordx2 v[124:125], v[0:1], off offset:1024
	global_load_dwordx2 v[126:127], v[0:1], off offset:1536
	global_load_dwordx2 v[122:123], v[0:1], off offset:2048
	global_load_dwordx2 v[120:121], v[0:1], off offset:2560
	global_load_dwordx2 v[118:119], v[0:1], off offset:3072
	global_load_dwordx2 v[116:117], v[0:1], off offset:3584
	s_add_i32 s54, s3, s0
	s_cmpk_lt_i32 s54, 0x4000
	s_cselect_b32 s4, s54, s0
	s_ashr_i32 s5, s4, 31
	s_lshl_b64 s[28:29], s[4:5], 13
	v_lshl_add_u64 v[0:1], v[66:67], 0, s[28:29]
	s_lshl_b64 s[4:5], s[4:5], 12
	global_load_dwordx4 v[28:31], v[0:1], off
	global_load_dwordx4 v[24:27], v[0:1], off offset:1024
	global_load_dwordx4 v[20:23], v[0:1], off offset:2048
	global_load_dwordx4 v[16:19], v[0:1], off offset:3072
	v_add_co_u32_e32 v0, vcc, s48, v0
	v_lshl_add_u64 v[94:95], v[64:65], 0, s[4:5]
	s_nop 0
	v_addc_co_u32_e32 v1, vcc, 0, v1, vcc
	global_load_dwordx4 v[12:15], v[0:1], off
	global_load_dwordx4 v[8:11], v[0:1], off offset:1024
	global_load_dwordx4 v[4:7], v[0:1], off offset:2048
	s_nop 0
	global_load_dwordx4 v[0:3], v[0:1], off offset:3072
	s_nop 0
	global_load_dwordx2 v[108:109], v[94:95], off
	global_load_dwordx2 v[106:107], v[94:95], off offset:512
	global_load_dwordx2 v[104:105], v[94:95], off offset:1024
	global_load_dwordx2 v[102:103], v[94:95], off offset:1536
	global_load_dwordx2 v[100:101], v[94:95], off offset:2048
	global_load_dwordx2 v[98:99], v[94:95], off offset:2560
	global_load_dwordx2 v[96:97], v[94:95], off offset:3072
	s_nop 0
	global_load_dwordx2 v[94:95], v[94:95], off offset:3584
	s_cmpk_gt_i32 s54, 0x3fff
	s_waitcnt vmcnt(23)
	v_and_b32_e32 v147, 0xffff0000, v113
	v_lshlrev_b32_e32 v144, 16, v112
	v_and_b32_e32 v145, 0xffff0000, v112
	v_lshlrev_b32_e32 v146, 16, v113
	v_mul_f32_e32 v112, v147, v147
	s_waitcnt vmcnt(22)
	v_and_b32_e32 v139, 0xffff0000, v115
	v_and_b32_e32 v138, 0xffff0000, v114
	v_pk_fma_f32 v[132:133], v[146:147], v[146:147], v[112:113] op_sel_hi:[1,1,0]
	v_lshlrev_b32_e32 v137, 16, v115
	v_lshlrev_b32_e32 v136, 16, v114
	v_pk_mul_f32 v[112:113], v[138:139], v[138:139]
	s_waitcnt vmcnt(21)
	v_lshlrev_b32_e32 v128, 16, v124
	v_pk_fma_f32 v[134:135], v[136:137], v[136:137], v[112:113]
	s_waitcnt vmcnt(20)
	v_and_b32_e32 v113, 0xffff0000, v126
	v_mul_f32_e32 v112, v145, v145
	v_and_b32_e32 v129, 0xffff0000, v124
	v_lshlrev_b32_e32 v130, 16, v125
	v_and_b32_e32 v131, 0xffff0000, v125
	v_lshlrev_b32_e32 v115, 16, v126
	v_pk_fma_f32 v[124:125], v[144:145], v[144:145], v[112:113] op_sel_hi:[1,1,0]
	v_mov_b32_e32 v140, v132
	v_mov_b32_e32 v114, v124
	v_mov_b32_e32 v141, v115
	v_pk_add_f32 v[124:125], v[124:125], v[132:133]
	v_pk_mul_f32 v[132:133], v[114:115], v[140:141]
	v_mul_f32_e32 v142, v113, v113
	v_mov_b32_e32 v125, v133
	v_pk_add_f32 v[132:133], v[134:135], v[134:135] op_sel:[0,1] op_sel_hi:[1,0]
	v_mul_f32_e32 v112, v129, v129
	v_mov_b32_e32 v133, v142
	v_lshlrev_b32_e32 v126, 16, v127
	v_and_b32_e32 v127, 0xffff0000, v127
	v_pk_add_f32 v[124:125], v[124:125], v[132:133]
	v_pk_fma_f32 v[132:133], v[128:129], v[128:129], v[112:113] op_sel_hi:[1,1,0]
	v_mul_f32_e32 v112, v131, v131
	v_mul_f32_e32 v143, v126, v126
	v_mul_f32_e32 v148, v127, v127
	v_pk_fma_f32 v[134:135], v[130:131], v[130:131], v[112:113] op_sel_hi:[1,1,0]
	v_mov_b32_e32 v133, v143
	v_mov_b32_e32 v135, v148
	s_waitcnt vmcnt(19)
	v_and_b32_e32 v143, 0xffff0000, v123
	v_and_b32_e32 v142, 0xffff0000, v122
	v_pk_add_f32 v[132:133], v[132:133], v[134:135]
	v_lshlrev_b32_e32 v141, 16, v123
	v_lshlrev_b32_e32 v140, 16, v122
	v_pk_mul_f32 v[122:123], v[142:143], v[142:143]
	s_waitcnt vmcnt(18)
	v_and_b32_e32 v135, 0xffff0000, v121
	v_and_b32_e32 v134, 0xffff0000, v120
	v_pk_add_f32 v[148:149], v[124:125], v[132:133]
	v_pk_fma_f32 v[122:123], v[140:141], v[140:141], v[122:123]
	v_lshlrev_b32_e32 v133, 16, v121
	v_lshlrev_b32_e32 v132, 16, v120
	v_pk_mul_f32 v[120:121], v[134:135], v[134:135]
	v_pk_add_f32 v[150:151], v[122:123], v[122:123] op_sel:[0,1] op_sel_hi:[1,0]
	v_pk_fma_f32 v[152:153], v[132:133], v[132:133], v[120:121]
	s_waitcnt vmcnt(16)
	v_lshlrev_b32_e32 v121, 16, v116
	v_pk_add_f32 v[148:149], v[148:149], v[148:149] op_sel:[0,1] op_sel_hi:[1,0]
	v_mov_b32_e32 v154, v150
	v_mov_b32_e32 v120, v148
	v_mov_b32_e32 v155, v121
	v_pk_add_f32 v[148:149], v[148:149], v[150:151]
	v_pk_mul_f32 v[150:151], v[120:121], v[154:155]
	ds_read_b128 v[154:157], v253
	v_lshlrev_b32_e32 v124, 16, v119
	v_and_b32_e32 v125, 0xffff0000, v119
	v_and_b32_e32 v119, 0xffff0000, v116
	v_and_b32_e32 v123, 0xffff0000, v118
	v_mul_f32_e32 v112, v119, v119
	v_mov_b32_e32 v149, v151
	v_pk_add_f32 v[150:151], v[152:153], v[152:153] op_sel:[0,1] op_sel_hi:[1,0]
	v_lshlrev_b32_e32 v122, 16, v118
	v_lshlrev_b32_e32 v116, 16, v117
	v_mov_b32_e32 v151, v112
	v_mul_f32_e32 v112, v123, v123
	v_and_b32_e32 v117, 0xffff0000, v117
	v_mul_f32_e32 v114, v116, v116
	v_pk_add_f32 v[148:149], v[148:149], v[150:151]
	v_pk_fma_f32 v[150:151], v[122:123], v[122:123], v[112:113] op_sel_hi:[1,1,0]
	v_mul_f32_e32 v112, v125, v125
	v_mul_f32_e32 v118, v117, v117
	v_mov_b32_e32 v151, v114
	v_pk_fma_f32 v[152:153], v[124:125], v[124:125], v[112:113] op_sel_hi:[1,1,0]
	v_and_b32_e32 v114, 64, v210
	v_mov_b32_e32 v153, v118
	v_add_u32_e32 v114, 64, v114
	v_xor_b32_e32 v118, 1, v210
	v_pk_add_f32 v[150:151], v[150:151], v[152:153]
	v_cmp_lt_i32_e32 vcc, v118, v114
	v_pk_add_f32 v[148:149], v[148:149], v[150:151]
	s_waitcnt vmcnt(0) lgkmcnt(0)
; __device__ __forceinline__ unsigned pk2(float lo, float hi) { const f32x2 v = {lo, hi}; const bf16x2_cv b = __builtin_convertvector(v, bf16x2_cv); return __builtin_bit_cast(unsigned, b); }
; __device__ __forceinline__ unsigned pk2(float lo, float hi) { return f2bf(lo) | (f2bf(hi) << 16); }
; __device__ __forceinline__ float wave_sum(float v) {
; #pragma unroll
;     for (int o = 1; o < 64; o <<= 1) v += __shfl_xor(v, o);
;     return v;
; }
; template <bool XIN_BF, bool XOUT_BF>
; __device__ __forceinline__ void ew_rows(const void* xsrc, void* xdst, const bf16* y, float scale, const float* gpost, const float* gpre, bf16* hout, int gw, int ngw, int lane) {
;     ...
;                 const float rs = rsqrtf(wave_sum(ss) * (1.0f / DM) + 1e-6f) * scale;
; #pragma unroll
;                 for (int j = 0; j < 8; ++j) { const f32x4 g = ((const f32x4*)gpost)[lane + 64 * j]; xv[j] = xv[j] + yv[j] * g * rs; }
;                 if (XOUT_BF) { v2u* xo = (v2u*)((bf16*)xdst + (size_t)row * DM) + lane;
; #pragma unroll
;                     for (int j = 0; j < 8; ++j) xo[64 * j] = (v2u){pk2(xv[j].x, xv[j].y), pk2(xv[j].z, xv[j].w)};
	v_pk_mul_f32 v[144:145], v[154:155], v[144:145]
	v_cndmask_b32_e32 v118, v210, v118, vcc
	v_add_f32_e32 v112, v148, v149
	v_lshlrev_b32_e32 v148, 2, v118
	ds_bpermute_b32 v118, v148, v112
	v_pk_mul_f32 v[146:147], v[156:157], v[146:147]
	v_mov_b32_e32 v155, v138
	v_mov_b32_e32 v138, v137
	v_mov_b32_e32 v154, v136
	s_waitcnt lgkmcnt(0)
	v_add_f32_e32 v112, v112, v118
	v_xor_b32_e32 v118, 2, v210
	v_cmp_lt_i32_e32 vcc, v118, v114
	s_nop 1
	v_cndmask_b32_e32 v118, v210, v118, vcc
	v_lshlrev_b32_e32 v149, 2, v118
	ds_bpermute_b32 v118, v149, v112
	s_waitcnt lgkmcnt(0)
	v_add_f32_e32 v112, v112, v118
	v_xor_b32_e32 v118, 4, v210
	v_cmp_lt_i32_e32 vcc, v118, v114
	s_nop 1
	v_cndmask_b32_e32 v118, v210, v118, vcc
	v_lshlrev_b32_e32 v150, 2, v118
	ds_bpermute_b32 v118, v150, v112
	s_waitcnt lgkmcnt(0)
	v_add_f32_e32 v112, v112, v118
	v_xor_b32_e32 v118, 8, v210
	v_cmp_lt_i32_e32 vcc, v118, v114
	s_nop 1
	v_cndmask_b32_e32 v118, v210, v118, vcc
	v_lshlrev_b32_e32 v151, 2, v118
	ds_bpermute_b32 v118, v151, v112
	s_waitcnt lgkmcnt(0)
	v_add_f32_e32 v112, v112, v118
	v_xor_b32_e32 v118, 16, v210
	v_cmp_lt_i32_e32 vcc, v118, v114
	s_nop 1
	v_cndmask_b32_e32 v118, v210, v118, vcc
	v_lshlrev_b32_e32 v152, 2, v118
	ds_bpermute_b32 v118, v152, v112
	s_waitcnt lgkmcnt(0)
	v_add_f32_e32 v112, v112, v118
	v_xor_b32_e32 v118, 32, v210
	v_cmp_lt_i32_e32 vcc, v118, v114
	s_nop 1
	v_cndmask_b32_e32 v114, v210, v118, vcc
	v_lshlrev_b32_e32 v153, 2, v114
	ds_bpermute_b32 v114, v153, v112
	v_mov_b32_e32 v118, v121
	s_waitcnt lgkmcnt(0)
	v_add_f32_e32 v112, v112, v114
	v_fmamk_f32 v112, v112, 0x3a000000, v204
	v_cmp_gt_f32_e32 vcc, s34, v112
	v_mul_f32_e32 v114, 0x4b800000, v112
	s_nop 0
	v_cndmask_b32_e32 v112, v112, v114, vcc
	v_rsq_f32_e32 v112, v112
	s_nop 0
	v_mul_f32_e32 v114, 0x45800000, v112
	v_cndmask_b32_e32 v112, v112, v114, vcc
	v_mul_f32_e32 v120, v163, v112
	v_pk_fma_f32 v[62:63], v[146:147], v[120:121], v[62:63] op_sel_hi:[1,0,1]
	v_pk_fma_f32 v[60:61], v[144:145], v[120:121], v[60:61] op_sel_hi:[1,0,1]
	ds_read_b128 v[144:147], v253 offset:1024
	v_mov_b32_e32 v112, v115
	s_waitcnt lgkmcnt(0)
	v_pk_mul_f32 v[136:137], v[146:147], v[138:139]
	s_nop 0
	v_pk_fma_f32 v[58:59], v[136:137], v[120:121], v[58:59] op_sel_hi:[1,0,1]
	ds_read_b128 v[136:139], v253 offset:2048
	v_pk_mul_f32 v[144:145], v[144:145], v[154:155]
	s_waitcnt lgkmcnt(0)
	v_pk_mul_f32 v[128:129], v[136:137], v[128:129]
	v_pk_mul_f32 v[130:131], v[138:139], v[130:131]
	v_pk_fma_f32 v[52:53], v[128:129], v[120:121], v[52:53] op_sel_hi:[1,0,1]
	v_pk_fma_f32 v[54:55], v[130:131], v[120:121], v[54:55] op_sel_hi:[1,0,1]
	ds_read_b128 v[128:131], v253 offset:3072
	v_pk_fma_f32 v[56:57], v[144:145], v[120:121], v[56:57] op_sel_hi:[1,0,1]
	s_waitcnt lgkmcnt(0)
	v_pk_mul_f32 v[126:127], v[126:127], v[130:131]
	v_pk_mul_f32 v[112:113], v[112:113], v[128:129]
	s_nop 0
	v_pk_fma_f32 v[114:115], v[112:113], v[120:121], v[48:49] op_sel_hi:[1,0,1]
	v_pk_fma_f32 v[112:113], v[126:127], v[120:121], v[50:51] op_sel_hi:[1,0,1]
	ds_read_b128 v[48:51], v253 offset:4096
	v_mov_b32_e32 v126, v140
	v_mov_b32_e32 v127, v142
	v_mov_b32_e32 v142, v141
	s_waitcnt lgkmcnt(0)
	v_pk_mul_f32 v[126:127], v[48:49], v[126:127]
	v_pk_mul_f32 v[48:49], v[50:51], v[142:143]
	v_pk_fma_f32 v[50:51], v[126:127], v[120:121], v[44:45] op_sel_hi:[1,0,1]
	v_pk_fma_f32 v[48:49], v[48:49], v[120:121], v[46:47] op_sel_hi:[1,0,1]
	ds_read_b128 v[44:47], v253 offset:5120
	v_mov_b32_e32 v126, v133
	v_mov_b32_e32 v127, v135
	v_mov_b32_e32 v133, v134
	s_waitcnt lgkmcnt(0)
	v_pk_mul_f32 v[126:127], v[46:47], v[126:127]
	v_pk_mul_f32 v[44:45], v[44:45], v[132:133]
	s_nop 0
	v_pk_fma_f32 v[46:47], v[44:45], v[120:121], v[40:41] op_sel_hi:[1,0,1]
	v_pk_fma_f32 v[44:45], v[126:127], v[120:121], v[42:43] op_sel_hi:[1,0,1]
	ds_read_b128 v[40:43], v253 offset:6144
	s_waitcnt lgkmcnt(0)
	v_pk_mul_f32 v[124:125], v[42:43], v[124:125]
	v_pk_mul_f32 v[40:41], v[40:41], v[122:123]
	s_nop 0
	v_pk_fma_f32 v[42:43], v[40:41], v[120:121], v[36:37] op_sel_hi:[1,0,1]
	v_pk_fma_f32 v[40:41], v[124:125], v[120:121], v[38:39] op_sel_hi:[1,0,1]
	ds_read_b128 v[36:39], v253 offset:7168
	s_waitcnt lgkmcnt(0)
	v_pk_mul_f32 v[38:39], v[116:117], v[38:39]
	s_nop 0
	v_pk_fma_f32 v[34:35], v[38:39], v[120:121], v[34:35] op_sel_hi:[1,0,1]
	v_bfe_u32 v38, v60, 16, 1
	v_add3_u32 v38, v60, v38, s46
	v_bfe_u32 v39, v61, 16, 1
	v_lshrrev_b32_e32 v38, 16, v38
	v_add3_u32 v39, v61, v39, s46
	v_and_or_b32 v38, v39, s33, v38
	v_bfe_u32 v39, v62, 16, 1
	v_add3_u32 v39, v62, v39, s46
	v_bfe_u32 v116, v63, 16, 1
	v_pk_mul_f32 v[36:37], v[118:119], v[36:37]
	v_lshrrev_b32_e32 v39, 16, v39
	v_add3_u32 v116, v63, v116, s46
	v_pk_fma_f32 v[32:33], v[36:37], v[120:121], v[32:33] op_sel_hi:[1,0,1]
	v_lshl_add_u64 v[36:37], s[14:15], 0, v[160:161]
	v_and_or_b32 v39, v116, s33, v39
	global_store_dwordx2 v[36:37], v[38:39], off
	v_bfe_u32 v38, v56, 16, 1
	v_add3_u32 v38, v56, v38, s46
	v_bfe_u32 v39, v57, 16, 1
	v_lshrrev_b32_e32 v38, 16, v38
	v_add3_u32 v39, v57, v39, s46
	v_and_or_b32 v38, v39, s33, v38
	v_bfe_u32 v39, v58, 16, 1
	v_add3_u32 v39, v58, v39, s46
	v_bfe_u32 v116, v59, 16, 1
	v_lshrrev_b32_e32 v39, 16, v39
	v_add3_u32 v116, v59, v116, s46
	v_and_or_b32 v39, v116, s33, v39
	global_store_dwordx2 v[36:37], v[38:39], off offset:512
	v_bfe_u32 v38, v52, 16, 1
	v_add3_u32 v38, v52, v38, s46
	v_bfe_u32 v39, v53, 16, 1
	v_lshrrev_b32_e32 v38, 16, v38
	v_add3_u32 v39, v53, v39, s46
	v_and_or_b32 v38, v39, s33, v38
	v_bfe_u32 v39, v54, 16, 1
	v_add3_u32 v39, v54, v39, s46
	v_bfe_u32 v116, v55, 16, 1
	v_lshrrev_b32_e32 v39, 16, v39
	v_add3_u32 v116, v55, v116, s46
	v_and_or_b32 v39, v116, s33, v39
; __device__ __forceinline__ unsigned pk2(float lo, float hi) { const f32x2 v = {lo, hi}; const bf16x2_cv b = __builtin_convertvector(v, bf16x2_cv); return __builtin_bit_cast(unsigned, b); }
; __device__ __forceinline__ unsigned pk2(float lo, float hi) { return f2bf(lo) | (f2bf(hi) << 16); }
; template <bool XIN_BF, bool XOUT_BF>
; __device__ __forceinline__ void ew_rows(const void* xsrc, void* xdst, const bf16* y, float scale, const float* gpost, const float* gpre, bf16* hout, int gw, int ngw, int lane) {
;     ...
;                 if (XOUT_BF) { v2u* xo = (v2u*)((bf16*)xdst + (size_t)row * DM) + lane;
; #pragma unroll
;                     for (int j = 0; j < 8; ++j) xo[64 * j] = (v2u){pk2(xv[j].x, xv[j].y), pk2(xv[j].z, xv[j].w)};
;                 } else { f32x4* xo = (f32x4*)((float*)xdst + (size_t)row * DM) + lane;
; #pragma unroll
;                     for (int j = 0; j < 8; ++j) xo[64 * j] = xv[j]; }
;             }
;             if (hout) {
;                 float s2 = 0.f;
; #pragma unroll
;                 for (int j = 0; j < 8; ++j) s2 += (xv[j].x * xv[j].x + xv[j].y * xv[j].y) + (xv[j].z * xv[j].z + xv[j].w * xv[j].w);
;                 const float rs2 = rsqrtf(wave_sum(s2) * (1.0f / DM) + 1e-6f);
;                 v2u* ho = (v2u*)(hout + (size_t)row * DM) + lane;
; #pragma unroll
;                 for (int j = 0; j < 8; ++j) { const f32x4 g = ((const f32x4*)gpre)[lane + 64 * j]; const f32x4 t = xv[j] * g * rs2; ho[64 * j] = (v2u){pk2(t.x, t.y), pk2(t.z, t.w)}; }
	global_store_dwordx2 v[36:37], v[38:39], off offset:1024
	v_bfe_u32 v38, v114, 16, 1
	v_add3_u32 v38, v114, v38, s46
	v_bfe_u32 v39, v115, 16, 1
	v_lshrrev_b32_e32 v38, 16, v38
	v_add3_u32 v39, v115, v39, s46
	v_and_or_b32 v38, v39, s33, v38
	v_bfe_u32 v39, v112, 16, 1
	v_add3_u32 v39, v112, v39, s46
	v_bfe_u32 v116, v113, 16, 1
	v_lshrrev_b32_e32 v39, 16, v39
	v_add3_u32 v116, v113, v116, s46
	v_and_or_b32 v39, v116, s33, v39
	global_store_dwordx2 v[36:37], v[38:39], off offset:1536
	v_bfe_u32 v38, v50, 16, 1
	v_add3_u32 v38, v50, v38, s46
	v_bfe_u32 v39, v51, 16, 1
	v_lshrrev_b32_e32 v38, 16, v38
	v_add3_u32 v39, v51, v39, s46
	v_and_or_b32 v38, v39, s33, v38
	v_bfe_u32 v39, v48, 16, 1
	v_add3_u32 v39, v48, v39, s46
	v_bfe_u32 v116, v49, 16, 1
	v_lshrrev_b32_e32 v39, 16, v39
	v_add3_u32 v116, v49, v116, s46
	v_and_or_b32 v39, v116, s33, v39
	global_store_dwordx2 v[36:37], v[38:39], off offset:2048
	v_bfe_u32 v38, v46, 16, 1
	v_add3_u32 v38, v46, v38, s46
	v_bfe_u32 v39, v47, 16, 1
	v_lshrrev_b32_e32 v38, 16, v38
	v_add3_u32 v39, v47, v39, s46
	v_and_or_b32 v38, v39, s33, v38
	v_bfe_u32 v39, v44, 16, 1
	v_add3_u32 v39, v44, v39, s46
	v_bfe_u32 v116, v45, 16, 1
	v_lshrrev_b32_e32 v39, 16, v39
	v_add3_u32 v116, v45, v116, s46
	v_and_or_b32 v39, v116, s33, v39
	global_store_dwordx2 v[36:37], v[38:39], off offset:2560
	v_bfe_u32 v38, v42, 16, 1
	v_add3_u32 v38, v42, v38, s46
	v_bfe_u32 v39, v43, 16, 1
	v_lshrrev_b32_e32 v38, 16, v38
	v_add3_u32 v39, v43, v39, s46
	v_and_or_b32 v38, v39, s33, v38
	v_bfe_u32 v39, v40, 16, 1
	v_add3_u32 v39, v40, v39, s46
	v_bfe_u32 v116, v41, 16, 1
	v_lshrrev_b32_e32 v39, 16, v39
	v_add3_u32 v116, v41, v116, s46
	v_and_or_b32 v39, v116, s33, v39
	global_store_dwordx2 v[36:37], v[38:39], off offset:3072
	v_bfe_u32 v38, v32, 16, 1
	v_add3_u32 v38, v32, v38, s46
	v_bfe_u32 v39, v33, 16, 1
	v_lshrrev_b32_e32 v38, 16, v38
	v_add3_u32 v39, v33, v39, s46
	v_and_or_b32 v38, v39, s33, v38
	v_bfe_u32 v39, v34, 16, 1
	v_add3_u32 v39, v34, v39, s46
	v_bfe_u32 v116, v35, 16, 1
	v_lshrrev_b32_e32 v39, 16, v39
	v_add3_u32 v116, v35, v116, s46
	v_and_or_b32 v39, v116, s33, v39
	global_store_dwordx2 v[36:37], v[38:39], off offset:3584
	v_mov_b32_e32 v38, v61
	v_mov_b32_e32 v39, v57
	v_mov_b32_e32 v36, v60
	v_mov_b32_e32 v37, v56
	v_pk_mul_f32 v[38:39], v[38:39], v[38:39]
	v_mov_b32_e32 v116, v63
	v_mov_b32_e32 v117, v59
	v_pk_fma_f32 v[36:37], v[36:37], v[36:37], v[38:39]
	v_mov_b32_e32 v38, v62
	v_mov_b32_e32 v39, v58
	v_pk_mul_f32 v[116:117], v[116:117], v[116:117]
	s_nop 0
	v_pk_fma_f32 v[38:39], v[38:39], v[38:39], v[116:117]
	v_pk_mul_f32 v[116:117], v[52:53], v[52:53]
	v_pk_add_f32 v[36:37], v[36:37], v[38:39]
	v_pk_mul_f32 v[38:39], v[54:55], v[54:55]
	v_pk_add_f32 v[36:37], v[36:37], v[36:37] op_sel_hi:[0,1]
	v_pk_mov_b32 v[118:119], v[116:117], v[38:39] op_sel:[1,0]
	v_mov_b32_e32 v117, v39
	v_mul_f32_e32 v36, v114, v114
	v_pk_add_f32 v[38:39], v[118:119], v[116:117]
	v_pk_fma_f32 v[116:117], v[114:115], v[114:115], v[36:37] op_sel_hi:[1,1,0]
	v_mul_f32_e32 v36, v112, v112
	v_pk_add_f32 v[38:39], v[38:39], v[38:39] op_sel_hi:[0,1]
	v_pk_fma_f32 v[118:119], v[112:113], v[112:113], v[36:37] op_sel_hi:[1,1,0]
	v_mul_f32_e32 v116, v50, v50
	v_mul_f32_e32 v118, v51, v51
	v_mul_f32_e32 v38, v48, v48
	v_mul_f32_e32 v36, v49, v49
	v_pk_add_f32 v[116:117], v[116:117], v[118:119]
	v_pk_add_f32 v[36:37], v[38:39], v[36:37]
	v_pk_mul_f32 v[38:39], v[44:45], v[44:45]
	v_pk_add_f32 v[36:37], v[116:117], v[36:37]
	v_pk_mul_f32 v[116:117], v[46:47], v[46:47]
	v_pk_add_f32 v[36:37], v[36:37], v[36:37] op_sel_hi:[0,1]
	v_pk_mov_b32 v[118:119], v[116:117], v[38:39] op_sel:[1,0]
	v_mov_b32_e32 v117, v39
	v_mul_f32_e32 v36, v42, v42
	v_pk_add_f32 v[38:39], v[118:119], v[116:117]
	v_pk_fma_f32 v[116:117], v[42:43], v[42:43], v[36:37] op_sel_hi:[1,1,0]
	v_mul_f32_e32 v36, v40, v40
	v_pk_add_f32 v[38:39], v[38:39], v[38:39] op_sel_hi:[0,1]
	v_pk_fma_f32 v[118:119], v[40:41], v[40:41], v[36:37] op_sel_hi:[1,1,0]
	v_mul_f32_e32 v116, v32, v32
	v_mul_f32_e32 v118, v33, v33
	v_mul_f32_e32 v38, v34, v34
	v_mul_f32_e32 v36, v35, v35
	v_pk_add_f32 v[116:117], v[116:117], v[118:119]
	v_pk_add_f32 v[36:37], v[38:39], v[36:37]
	s_nop 0
	v_pk_add_f32 v[36:37], v[116:117], v[36:37]
	ds_read_b128 v[116:119], v253 offset:8192
	v_add_f32_e32 v36, v36, v37
	ds_bpermute_b32 v37, v148, v36
	s_waitcnt lgkmcnt(0)
	v_add_f32_e32 v36, v36, v37
	ds_bpermute_b32 v37, v149, v36
	s_waitcnt lgkmcnt(0)
	v_add_f32_e32 v36, v36, v37
	ds_bpermute_b32 v37, v150, v36
	s_waitcnt lgkmcnt(0)
	v_add_f32_e32 v36, v36, v37
	ds_bpermute_b32 v37, v151, v36
	s_waitcnt lgkmcnt(0)
	v_add_f32_e32 v36, v36, v37
	ds_bpermute_b32 v37, v152, v36
	s_waitcnt lgkmcnt(0)
	v_add_f32_e32 v36, v36, v37
	ds_bpermute_b32 v37, v153, v36
	s_waitcnt lgkmcnt(0)
	v_add_f32_e32 v36, v36, v37
	v_fmamk_f32 v36, v36, 0x3a000000, v204
	v_cmp_gt_f32_e32 vcc, s34, v36
	v_mul_f32_e32 v37, 0x4b800000, v36
	s_waitcnt lgkmcnt(0)
	v_pk_mul_f32 v[38:39], v[60:61], v[116:117]
	v_cndmask_b32_e32 v36, v36, v37, vcc
	v_rsq_f32_e32 v36, v36
	v_pk_mul_f32 v[60:61], v[62:63], v[118:119]
	v_mul_f32_e32 v37, 0x45800000, v36
	v_cndmask_b32_e32 v36, v36, v37, vcc
	v_pk_mul_f32 v[38:39], v[38:39], v[36:37] op_sel_hi:[1,0]
	v_pk_mul_f32 v[60:61], v[60:61], v[36:37] op_sel_hi:[1,0]
	v_bfe_u32 v37, v38, 16, 1
	v_add3_u32 v37, v38, v37, s46
	v_bfe_u32 v38, v39, 16, 1
	v_lshrrev_b32_e32 v37, 16, v37
	v_add3_u32 v38, v39, v38, s46
	v_and_or_b32 v62, v38, s33, v37
	v_bfe_u32 v37, v60, 16, 1
	v_add3_u32 v37, v60, v37, s46
	v_bfe_u32 v38, v61, 16, 1
	v_lshrrev_b32_e32 v37, 16, v37
	v_add3_u32 v38, v61, v38, s46
	v_and_or_b32 v63, v38, s33, v37
	v_add_co_u32_e32 v38, vcc, s20, v110
	s_nop 1
	v_addc_co_u32_e32 v39, vcc, 0, v111, vcc
	global_store_dwordx2 v[38:39], v[62:63], off
	ds_read_b128 v[60:63], v253 offset:9216
	s_waitcnt lgkmcnt(0)
; __device__ __forceinline__ unsigned pk2(float lo, float hi) { const f32x2 v = {lo, hi}; const bf16x2_cv b = __builtin_convertvector(v, bf16x2_cv); return __builtin_bit_cast(unsigned, b); }
; __device__ __forceinline__ unsigned pk2(float lo, float hi) { return f2bf(lo) | (f2bf(hi) << 16); }
; template <bool XIN_BF, bool XOUT_BF>
; __device__ __forceinline__ void ew_rows(const void* xsrc, void* xdst, const bf16* y, float scale, const float* gpost, const float* gpre, bf16* hout, int gw, int ngw, int lane) {
;     ...
;                 v2u* ho = (v2u*)(hout + (size_t)row * DM) + lane;
; #pragma unroll
;                 for (int j = 0; j < 8; ++j) { const f32x4 g = ((const f32x4*)gpre)[lane + 64 * j]; const f32x4 t = xv[j] * g * rs2; ho[64 * j] = (v2u){pk2(t.x, t.y), pk2(t.z, t.w)}; }
	v_pk_mul_f32 v[56:57], v[56:57], v[60:61]
	v_pk_mul_f32 v[58:59], v[58:59], v[62:63]
	v_pk_mul_f32 v[56:57], v[56:57], v[36:37] op_sel_hi:[1,0]
	v_pk_mul_f32 v[58:59], v[58:59], v[36:37] op_sel_hi:[1,0]
	v_bfe_u32 v37, v56, 16, 1
	v_add3_u32 v37, v56, v37, s46
	v_bfe_u32 v56, v57, 16, 1
	v_lshrrev_b32_e32 v37, 16, v37
	v_add3_u32 v56, v57, v56, s46
	v_and_or_b32 v56, v56, s33, v37
	v_bfe_u32 v37, v58, 16, 1
	v_add3_u32 v37, v58, v37, s46
	v_bfe_u32 v57, v59, 16, 1
	v_lshrrev_b32_e32 v37, 16, v37
	v_add3_u32 v57, v59, v57, s46
	v_and_or_b32 v57, v57, s33, v37
	global_store_dwordx2 v[38:39], v[56:57], off offset:512
	ds_read_b128 v[56:59], v253 offset:10240
	s_waitcnt lgkmcnt(0)
	v_pk_mul_f32 v[52:53], v[52:53], v[56:57]
	v_pk_mul_f32 v[54:55], v[54:55], v[58:59]
	v_pk_mul_f32 v[52:53], v[52:53], v[36:37] op_sel_hi:[1,0]
	v_pk_mul_f32 v[54:55], v[54:55], v[36:37] op_sel_hi:[1,0]
	v_bfe_u32 v37, v52, 16, 1
	v_add3_u32 v37, v52, v37, s46
	v_bfe_u32 v52, v53, 16, 1
	v_lshrrev_b32_e32 v37, 16, v37
	v_add3_u32 v52, v53, v52, s46
	v_and_or_b32 v52, v52, s33, v37
	v_bfe_u32 v37, v54, 16, 1
	v_add3_u32 v37, v54, v37, s46
	v_bfe_u32 v53, v55, 16, 1
	v_lshrrev_b32_e32 v37, 16, v37
	v_add3_u32 v53, v55, v53, s46
	v_and_or_b32 v53, v53, s33, v37
	global_store_dwordx2 v[38:39], v[52:53], off offset:1024
	ds_read_b128 v[52:55], v253 offset:11264
	s_waitcnt lgkmcnt(0)
	v_pk_mul_f32 v[52:53], v[114:115], v[52:53]
	v_pk_mul_f32 v[54:55], v[112:113], v[54:55]
	v_pk_mul_f32 v[52:53], v[52:53], v[36:37] op_sel_hi:[1,0]
	v_pk_mul_f32 v[54:55], v[54:55], v[36:37] op_sel_hi:[1,0]
	v_bfe_u32 v37, v52, 16, 1
	v_add3_u32 v37, v52, v37, s46
	v_bfe_u32 v52, v53, 16, 1
	v_lshrrev_b32_e32 v37, 16, v37
	v_add3_u32 v52, v53, v52, s46
	v_and_or_b32 v52, v52, s33, v37
	v_bfe_u32 v37, v54, 16, 1
	v_add3_u32 v37, v54, v37, s46
	v_bfe_u32 v53, v55, 16, 1
	v_lshrrev_b32_e32 v37, 16, v37
	v_add3_u32 v53, v55, v53, s46
	v_and_or_b32 v53, v53, s33, v37
	global_store_dwordx2 v[38:39], v[52:53], off offset:1536
	ds_read_b128 v[52:55], v253 offset:12288
	s_waitcnt lgkmcnt(0)
	v_pk_mul_f32 v[50:51], v[50:51], v[52:53]
	v_pk_mul_f32 v[48:49], v[48:49], v[54:55]
	v_pk_mul_f32 v[50:51], v[50:51], v[36:37] op_sel_hi:[1,0]
	v_pk_mul_f32 v[48:49], v[48:49], v[36:37] op_sel_hi:[1,0]
	v_bfe_u32 v37, v50, 16, 1
	v_add3_u32 v37, v50, v37, s46
	v_bfe_u32 v50, v51, 16, 1
	v_lshrrev_b32_e32 v37, 16, v37
	v_add3_u32 v50, v51, v50, s46
	v_and_or_b32 v50, v50, s33, v37
	v_bfe_u32 v37, v48, 16, 1
	v_add3_u32 v37, v48, v37, s46
	v_bfe_u32 v48, v49, 16, 1
	v_lshrrev_b32_e32 v37, 16, v37
	v_add3_u32 v48, v49, v48, s46
	v_and_or_b32 v51, v48, s33, v37
	global_store_dwordx2 v[38:39], v[50:51], off offset:2048
	ds_read_b128 v[48:51], v253 offset:13312
	s_waitcnt lgkmcnt(0)
	v_pk_mul_f32 v[46:47], v[46:47], v[48:49]
	v_pk_mul_f32 v[44:45], v[44:45], v[50:51]
	v_pk_mul_f32 v[46:47], v[46:47], v[36:37] op_sel_hi:[1,0]
	v_pk_mul_f32 v[44:45], v[44:45], v[36:37] op_sel_hi:[1,0]
	v_bfe_u32 v37, v46, 16, 1
	v_add3_u32 v37, v46, v37, s46
	v_bfe_u32 v46, v47, 16, 1
	v_lshrrev_b32_e32 v37, 16, v37
	v_add3_u32 v46, v47, v46, s46
	v_and_or_b32 v46, v46, s33, v37
	v_bfe_u32 v37, v44, 16, 1
	v_add3_u32 v37, v44, v37, s46
	v_bfe_u32 v44, v45, 16, 1
	v_lshrrev_b32_e32 v37, 16, v37
	v_add3_u32 v44, v45, v44, s46
	v_and_or_b32 v47, v44, s33, v37
	global_store_dwordx2 v[38:39], v[46:47], off offset:2560
	ds_read_b128 v[44:47], v253 offset:14336
	s_waitcnt lgkmcnt(0)
	v_pk_mul_f32 v[42:43], v[42:43], v[44:45]
	v_pk_mul_f32 v[40:41], v[40:41], v[46:47]
	v_pk_mul_f32 v[42:43], v[42:43], v[36:37] op_sel_hi:[1,0]
	v_pk_mul_f32 v[40:41], v[40:41], v[36:37] op_sel_hi:[1,0]
	v_bfe_u32 v37, v42, 16, 1
	v_add3_u32 v37, v42, v37, s46
	v_bfe_u32 v42, v43, 16, 1
	v_lshrrev_b32_e32 v37, 16, v37
	v_add3_u32 v42, v43, v42, s46
	v_and_or_b32 v42, v42, s33, v37
	v_bfe_u32 v37, v40, 16, 1
	v_add3_u32 v37, v40, v37, s46
	v_bfe_u32 v40, v41, 16, 1
	v_lshrrev_b32_e32 v37, 16, v37
	v_add3_u32 v40, v41, v40, s46
	v_and_or_b32 v43, v40, s33, v37
	global_store_dwordx2 v[38:39], v[42:43], off offset:3072
	ds_read_b128 v[40:43], v253 offset:15360
	s_waitcnt lgkmcnt(0)
	v_pk_mul_f32 v[32:33], v[32:33], v[40:41]
	v_pk_mul_f32 v[34:35], v[34:35], v[42:43]
	v_pk_mul_f32 v[32:33], v[32:33], v[36:37] op_sel_hi:[1,0]
	v_pk_mul_f32 v[34:35], v[34:35], v[36:37] op_sel_hi:[1,0]
	v_bfe_u32 v36, v32, 16, 1
	v_add3_u32 v32, v32, v36, s46
	v_bfe_u32 v36, v33, 16, 1
	v_lshrrev_b32_e32 v32, 16, v32
	v_add3_u32 v33, v33, v36, s46
	v_and_or_b32 v32, v33, s33, v32
	v_bfe_u32 v33, v34, 16, 1
	v_add3_u32 v33, v34, v33, s46
	v_bfe_u32 v34, v35, 16, 1
	v_lshrrev_b32_e32 v33, 16, v33
	v_add3_u32 v34, v35, v34, s46
	v_and_or_b32 v33, v34, s33, v33
	global_store_dwordx2 v[38:39], v[32:33], off offset:3584
	s_cbranch_scc1 .LBB0_771
; __device__ __forceinline__ float wave_sum(float v) {
; #pragma unroll
;     for (int o = 1; o < 64; o <<= 1) v += __shfl_xor(v, o);
;     return v;
; template <bool XIN_BF, bool XOUT_BF>
; __device__ __forceinline__ void ew_rows(const void* xsrc, void* xdst, const bf16* y, float scale, const float* gpost, const float* gpre, bf16* hout, int gw, int ngw, int lane) {
;     ...
;             for (int j = 0; j < 8; ++j) { if (XIN_BF) { const v2u w = xb[XIN_BF ? r : 0][j]; xv[j] = (f32x4){__uint_as_float(w.x << 16), __uint_as_float(w.x & 0xffff0000u), __uint_as_float(w.y << 16), __uint_as_float(w.y & 0xffff0000u)}; } else xv[j] = xf[XIN_BF ? 0 : r][j]; }
;             if (y) {
;                 f32x4 yv[8]; float ss = 0.f;
; #pragma unroll
;                 for (int j = 0; j < 8; ++j) { const v2u w = yb[r][j]; yv[j] = (f32x4){__uint_as_float(w.x << 16), __uint_as_float(w.x & 0xffff0000u), __uint_as_float(w.y << 16), __uint_as_float(w.y & 0xffff0000u)};
;                     ss += (yv[j].x * yv[j].x + yv[j].y * yv[j].y) + (yv[j].z * yv[j].z + yv[j].w * yv[j].w); }
;                 const float rs = rsqrtf(wave_sum(ss) * (1.0f / DM) + 1e-6f) * scale;
; #pragma unroll
;                 for (int j = 0; j < 8; ++j) { const f32x4 g = ((const f32x4*)gpost)[lane + 64 * j]; xv[j] = xv[j] + yv[j] * g * rs; }
	v_lshlrev_b32_e32 v110, 16, v108
	v_and_b32_e32 v111, 0xffff0000, v108
	v_lshlrev_b32_e32 v108, 16, v109
	v_and_b32_e32 v109, 0xffff0000, v109
	v_mul_f32_e32 v32, v109, v109
	v_and_b32_e32 v63, 0xffff0000, v107
	v_and_b32_e32 v62, 0xffff0000, v106
	v_pk_fma_f32 v[34:35], v[108:109], v[108:109], v[32:33] op_sel_hi:[1,1,0]
	v_lshlrev_b32_e32 v61, 16, v107
	v_lshlrev_b32_e32 v60, 16, v106
	v_pk_mul_f32 v[32:33], v[62:63], v[62:63]
	v_lshlrev_b32_e32 v53, 16, v102
	v_pk_fma_f32 v[36:37], v[60:61], v[60:61], v[32:33]
	v_and_b32_e32 v33, 0xffff0000, v102
	v_mul_f32_e32 v32, v111, v111
	v_pk_fma_f32 v[38:39], v[110:111], v[110:111], v[32:33] op_sel_hi:[1,1,0]
	v_mov_b32_e32 v40, v34
	v_mov_b32_e32 v52, v38
	v_mov_b32_e32 v41, v53
	v_and_b32_e32 v57, 0xffff0000, v104
	v_mul_f32_e32 v42, v33, v33
	v_pk_add_f32 v[34:35], v[38:39], v[34:35]
	v_pk_mul_f32 v[38:39], v[52:53], v[40:41]
	v_pk_add_f32 v[36:37], v[36:37], v[36:37] op_sel:[0,1] op_sel_hi:[1,0]
	v_lshlrev_b32_e32 v56, 16, v104
	v_and_b32_e32 v59, 0xffff0000, v105
	v_mov_b32_e32 v35, v39
	v_mov_b32_e32 v37, v42
	v_mul_f32_e32 v32, v57, v57
	v_lshlrev_b32_e32 v58, 16, v105
	v_lshlrev_b32_e32 v54, 16, v103
	v_and_b32_e32 v55, 0xffff0000, v103
	v_pk_add_f32 v[34:35], v[34:35], v[36:37]
	v_pk_fma_f32 v[36:37], v[56:57], v[56:57], v[32:33] op_sel_hi:[1,1,0]
	v_mul_f32_e32 v32, v59, v59
	v_mul_f32_e32 v43, v54, v54
	v_mul_f32_e32 v44, v55, v55
	v_pk_fma_f32 v[38:39], v[58:59], v[58:59], v[32:33] op_sel_hi:[1,1,0]
	v_mov_b32_e32 v37, v43
	v_mov_b32_e32 v39, v44
	v_pk_add_f32 v[36:37], v[36:37], v[38:39]
	v_and_b32_e32 v51, 0xffff0000, v101
	v_and_b32_e32 v50, 0xffff0000, v100
	v_pk_add_f32 v[102:103], v[34:35], v[36:37]
	v_lshlrev_b32_e32 v49, 16, v101
	v_lshlrev_b32_e32 v48, 16, v100
	v_pk_mul_f32 v[34:35], v[50:51], v[50:51]
	v_and_b32_e32 v47, 0xffff0000, v99
	v_pk_fma_f32 v[34:35], v[48:49], v[48:49], v[34:35]
	v_and_b32_e32 v46, 0xffff0000, v98
	v_pk_add_f32 v[100:101], v[34:35], v[34:35] op_sel:[0,1] op_sel_hi:[1,0]
	v_lshlrev_b32_e32 v45, 16, v99
	v_lshlrev_b32_e32 v44, 16, v98
	v_pk_mul_f32 v[34:35], v[46:47], v[46:47]
	v_lshlrev_b32_e32 v39, 16, v94
	v_pk_fma_f32 v[98:99], v[44:45], v[44:45], v[34:35]
	v_and_b32_e32 v37, 0xffff0000, v94
	v_lshlrev_b32_e32 v34, 16, v95
	v_and_b32_e32 v35, 0xffff0000, v95
	v_pk_add_f32 v[94:95], v[102:103], v[102:103] op_sel:[0,1] op_sel_hi:[1,0]
	v_lshlrev_b32_e32 v40, 16, v96
	v_and_b32_e32 v41, 0xffff0000, v96
	v_lshlrev_b32_e32 v42, 16, v97
	v_and_b32_e32 v43, 0xffff0000, v97
	v_mov_b32_e32 v38, v94
	v_mov_b32_e32 v96, v100
	v_mov_b32_e32 v97, v39
	v_pk_add_f32 v[94:95], v[94:95], v[100:101]
	v_pk_mul_f32 v[96:97], v[38:39], v[96:97]
	v_mul_f32_e32 v32, v37, v37
	v_mov_b32_e32 v95, v97
	v_pk_add_f32 v[96:97], v[98:99], v[98:99] op_sel:[0,1] op_sel_hi:[1,0]
	v_mul_f32_e32 v36, v34, v34
	v_mov_b32_e32 v97, v32
	v_mul_f32_e32 v32, v41, v41
	v_pk_add_f32 v[94:95], v[94:95], v[96:97]
	v_pk_fma_f32 v[96:97], v[40:41], v[40:41], v[32:33] op_sel_hi:[1,1,0]
	v_mul_f32_e32 v32, v43, v43
	v_mul_f32_e32 v52, v35, v35
	v_pk_fma_f32 v[98:99], v[42:43], v[42:43], v[32:33] op_sel_hi:[1,1,0]
	v_mov_b32_e32 v97, v36
	v_mov_b32_e32 v99, v52
	v_pk_add_f32 v[96:97], v[96:97], v[98:99]
	v_mov_b32_e32 v99, v62
	v_pk_add_f32 v[94:95], v[94:95], v[96:97]
	v_mov_b32_e32 v62, v61
	v_add_f32_e32 v32, v94, v95
	ds_read_b128 v[94:97], v253
	ds_bpermute_b32 v36, v148, v32
	v_mov_b32_e32 v98, v60
	s_ashr_i32 s55, s54, 31
	s_lshl_b64 s[4:5], s[54:55], 12
	s_waitcnt lgkmcnt(0)
	v_add_f32_e32 v32, v32, v36
	ds_bpermute_b32 v36, v149, v32
	s_waitcnt lgkmcnt(0)
	v_add_f32_e32 v32, v32, v36
	ds_bpermute_b32 v36, v150, v32
	s_waitcnt lgkmcnt(0)
	v_add_f32_e32 v32, v32, v36
	ds_bpermute_b32 v36, v151, v32
	s_waitcnt lgkmcnt(0)
	v_add_f32_e32 v32, v32, v36
	ds_bpermute_b32 v36, v152, v32
	s_waitcnt lgkmcnt(0)
	v_add_f32_e32 v32, v32, v36
	ds_bpermute_b32 v36, v153, v32
	s_waitcnt lgkmcnt(0)
	v_add_f32_e32 v32, v32, v36
	v_fmamk_f32 v32, v32, 0x3a000000, v204
	v_cmp_gt_f32_e32 vcc, s34, v32
	v_mul_f32_e32 v36, 0x4b800000, v32
	s_waitcnt lgkmcnt(0)
	v_pk_mul_f32 v[94:95], v[94:95], v[110:111]
	v_cndmask_b32_e32 v32, v32, v36, vcc
	v_rsq_f32_e32 v32, v32
	v_pk_mul_f32 v[96:97], v[96:97], v[108:109]
	v_mul_f32_e32 v36, 0x45800000, v32
	v_cndmask_b32_e32 v32, v32, v36, vcc
	v_mul_f32_e32 v38, v163, v32
	v_pk_fma_f32 v[30:31], v[96:97], v[38:39], v[30:31] op_sel_hi:[1,0,1]
	v_pk_fma_f32 v[28:29], v[94:95], v[38:39], v[28:29] op_sel_hi:[1,0,1]
	ds_read_b128 v[94:97], v253 offset:1024
	v_mov_b32_e32 v32, v53
	v_mov_b32_e32 v36, v39
	s_waitcnt lgkmcnt(0)
	v_pk_mul_f32 v[60:61], v[96:97], v[62:63]
	s_nop 0
	v_pk_fma_f32 v[26:27], v[60:61], v[38:39], v[26:27] op_sel_hi:[1,0,1]
	ds_read_b128 v[60:63], v253 offset:2048
	v_pk_mul_f32 v[94:95], v[94:95], v[98:99]
	s_waitcnt lgkmcnt(0)
	v_pk_mul_f32 v[56:57], v[60:61], v[56:57]
	v_pk_mul_f32 v[58:59], v[62:63], v[58:59]
	v_pk_fma_f32 v[20:21], v[56:57], v[38:39], v[20:21] op_sel_hi:[1,0,1]
	v_pk_fma_f32 v[22:23], v[58:59], v[38:39], v[22:23] op_sel_hi:[1,0,1]
	ds_read_b128 v[56:59], v253 offset:3072
	v_pk_fma_f32 v[24:25], v[94:95], v[38:39], v[24:25] op_sel_hi:[1,0,1]
	s_waitcnt lgkmcnt(0)
	v_pk_mul_f32 v[54:55], v[54:55], v[58:59]
	s_nop 0
	v_pk_fma_f32 v[18:19], v[54:55], v[38:39], v[18:19] op_sel_hi:[1,0,1]
	ds_read_b128 v[52:55], v253 offset:4096
	v_pk_mul_f32 v[32:33], v[32:33], v[56:57]
	s_nop 0
	v_pk_fma_f32 v[32:33], v[32:33], v[38:39], v[16:17] op_sel_hi:[1,0,1]
	v_mov_b32_e32 v17, v50
	v_mov_b32_e32 v50, v49
	v_mov_b32_e32 v16, v48
	s_waitcnt lgkmcnt(0)
; __device__ __forceinline__ unsigned pk2(float lo, float hi) { const f32x2 v = {lo, hi}; const bf16x2_cv b = __builtin_convertvector(v, bf16x2_cv); return __builtin_bit_cast(unsigned, b); }
; __device__ __forceinline__ unsigned pk2(float lo, float hi) { return f2bf(lo) | (f2bf(hi) << 16); }
; template <bool XIN_BF, bool XOUT_BF>
; __device__ __forceinline__ void ew_rows(const void* xsrc, void* xdst, const bf16* y, float scale, const float* gpost, const float* gpre, bf16* hout, int gw, int ngw, int lane) {
;     ...
;                 for (int j = 0; j < 8; ++j) { const v2u w = yb[r][j]; yv[j] = (f32x4){__uint_as_float(w.x << 16), __uint_as_float(w.x & 0xffff0000u), __uint_as_float(w.y << 16), __uint_as_float(w.y & 0xffff0000u)};
;                     ss += (yv[j].x * yv[j].x + yv[j].y * yv[j].y) + (yv[j].z * yv[j].z + yv[j].w * yv[j].w); }
;                 const float rs = rsqrtf(wave_sum(ss) * (1.0f / DM) + 1e-6f) * scale;
; #pragma unroll
;                 for (int j = 0; j < 8; ++j) { const f32x4 g = ((const f32x4*)gpost)[lane + 64 * j]; xv[j] = xv[j] + yv[j] * g * rs; }
;                 if (XOUT_BF) { v2u* xo = (v2u*)((bf16*)xdst + (size_t)row * DM) + lane;
; #pragma unroll
;                     for (int j = 0; j < 8; ++j) xo[64 * j] = (v2u){pk2(xv[j].x, xv[j].y), pk2(xv[j].z, xv[j].w)};
;                 } else { f32x4* xo = (f32x4*)((float*)xdst + (size_t)row * DM) + lane;
; #pragma unroll
;                     for (int j = 0; j < 8; ++j) xo[64 * j] = xv[j]; }
;             }
;             if (hout) {
;                 float s2 = 0.f;
; #pragma unroll
;                 for (int j = 0; j < 8; ++j) s2 += (xv[j].x * xv[j].x + xv[j].y * xv[j].y) + (xv[j].z * xv[j].z + xv[j].w * xv[j].w);
;                 const float rs2 = rsqrtf(wave_sum(s2) * (1.0f / DM) + 1e-6f);
	v_pk_mul_f32 v[48:49], v[54:55], v[50:51]
	s_nop 0
	v_pk_fma_f32 v[14:15], v[48:49], v[38:39], v[14:15] op_sel_hi:[1,0,1]
	ds_read_b128 v[48:51], v253 offset:5120
	v_pk_mul_f32 v[16:17], v[52:53], v[16:17]
	s_nop 0
	v_pk_fma_f32 v[16:17], v[16:17], v[38:39], v[12:13] op_sel_hi:[1,0,1]
	v_mov_b32_e32 v12, v45
	v_mov_b32_e32 v13, v47
	v_mov_b32_e32 v45, v46
	s_waitcnt lgkmcnt(0)
	v_pk_mul_f32 v[50:51], v[50:51], v[12:13]
	v_pk_mul_f32 v[12:13], v[48:49], v[44:45]
	ds_read_b128 v[44:47], v253 offset:6144
	v_pk_fma_f32 v[12:13], v[12:13], v[38:39], v[8:9] op_sel_hi:[1,0,1]
	v_pk_fma_f32 v[10:11], v[50:51], v[38:39], v[10:11] op_sel_hi:[1,0,1]
	s_waitcnt lgkmcnt(0)
	v_pk_mul_f32 v[42:43], v[46:47], v[42:43]
	v_pk_mul_f32 v[8:9], v[44:45], v[40:41]
	s_nop 0
	v_pk_fma_f32 v[8:9], v[8:9], v[38:39], v[4:5] op_sel_hi:[1,0,1]
	v_pk_fma_f32 v[4:5], v[42:43], v[38:39], v[6:7] op_sel_hi:[1,0,1]
	ds_read_b128 v[40:43], v253 offset:7168
	s_waitcnt lgkmcnt(0)
	v_pk_mul_f32 v[34:35], v[34:35], v[42:43]
	s_nop 0
	v_pk_fma_f32 v[2:3], v[34:35], v[38:39], v[2:3] op_sel_hi:[1,0,1]
	v_bfe_u32 v34, v28, 16, 1
	v_add3_u32 v34, v28, v34, s46
	v_bfe_u32 v35, v29, 16, 1
	v_lshrrev_b32_e32 v34, 16, v34
	v_add3_u32 v35, v29, v35, s46
	v_and_or_b32 v34, v35, s33, v34
	v_bfe_u32 v35, v30, 16, 1
	v_pk_mul_f32 v[6:7], v[36:37], v[40:41]
	v_add3_u32 v35, v30, v35, s46
	v_bfe_u32 v36, v31, 16, 1
	v_lshrrev_b32_e32 v35, 16, v35
	v_add3_u32 v36, v31, v36, s46
	v_pk_fma_f32 v[0:1], v[6:7], v[38:39], v[0:1] op_sel_hi:[1,0,1]
	v_lshl_add_u64 v[6:7], v[68:69], 0, s[4:5]
	v_and_or_b32 v35, v36, s33, v35
	global_store_dwordx2 v[6:7], v[34:35], off
	v_bfe_u32 v34, v24, 16, 1
	v_add3_u32 v34, v24, v34, s46
	v_bfe_u32 v35, v25, 16, 1
	v_lshrrev_b32_e32 v34, 16, v34
	v_add3_u32 v35, v25, v35, s46
	v_and_or_b32 v34, v35, s33, v34
	v_bfe_u32 v35, v26, 16, 1
	v_add3_u32 v35, v26, v35, s46
	v_bfe_u32 v36, v27, 16, 1
	v_lshrrev_b32_e32 v35, 16, v35
	v_add3_u32 v36, v27, v36, s46
	v_and_or_b32 v35, v36, s33, v35
	global_store_dwordx2 v[6:7], v[34:35], off offset:512
	v_bfe_u32 v34, v20, 16, 1
	v_add3_u32 v34, v20, v34, s46
	v_bfe_u32 v35, v21, 16, 1
	v_lshrrev_b32_e32 v34, 16, v34
	v_add3_u32 v35, v21, v35, s46
	v_and_or_b32 v34, v35, s33, v34
	v_bfe_u32 v35, v22, 16, 1
	v_add3_u32 v35, v22, v35, s46
	v_bfe_u32 v36, v23, 16, 1
	v_lshrrev_b32_e32 v35, 16, v35
	v_add3_u32 v36, v23, v36, s46
	v_and_or_b32 v35, v36, s33, v35
	global_store_dwordx2 v[6:7], v[34:35], off offset:1024
	v_bfe_u32 v34, v32, 16, 1
	v_add3_u32 v34, v32, v34, s46
	v_bfe_u32 v35, v33, 16, 1
	v_lshrrev_b32_e32 v34, 16, v34
	v_add3_u32 v35, v33, v35, s46
	v_and_or_b32 v34, v35, s33, v34
	v_bfe_u32 v35, v18, 16, 1
	v_add3_u32 v35, v18, v35, s46
	v_bfe_u32 v36, v19, 16, 1
	v_lshrrev_b32_e32 v35, 16, v35
	v_add3_u32 v36, v19, v36, s46
	v_and_or_b32 v35, v36, s33, v35
	global_store_dwordx2 v[6:7], v[34:35], off offset:1536
	v_bfe_u32 v34, v16, 16, 1
	v_add3_u32 v34, v16, v34, s46
	v_bfe_u32 v35, v17, 16, 1
	v_lshrrev_b32_e32 v34, 16, v34
	v_add3_u32 v35, v17, v35, s46
	v_and_or_b32 v34, v35, s33, v34
	v_bfe_u32 v35, v14, 16, 1
	v_add3_u32 v35, v14, v35, s46
	v_bfe_u32 v36, v15, 16, 1
	v_lshrrev_b32_e32 v35, 16, v35
	v_add3_u32 v36, v15, v36, s46
	v_and_or_b32 v35, v36, s33, v35
	global_store_dwordx2 v[6:7], v[34:35], off offset:2048
	v_bfe_u32 v34, v12, 16, 1
	v_add3_u32 v34, v12, v34, s46
	v_bfe_u32 v35, v13, 16, 1
	v_lshrrev_b32_e32 v34, 16, v34
	v_add3_u32 v35, v13, v35, s46
	v_and_or_b32 v34, v35, s33, v34
	v_bfe_u32 v35, v10, 16, 1
	v_add3_u32 v35, v10, v35, s46
	v_bfe_u32 v36, v11, 16, 1
	v_lshrrev_b32_e32 v35, 16, v35
	v_add3_u32 v36, v11, v36, s46
	v_and_or_b32 v35, v36, s33, v35
	global_store_dwordx2 v[6:7], v[34:35], off offset:2560
	v_bfe_u32 v34, v8, 16, 1
	v_add3_u32 v34, v8, v34, s46
	v_bfe_u32 v35, v9, 16, 1
	v_lshrrev_b32_e32 v34, 16, v34
	v_add3_u32 v35, v9, v35, s46
	v_and_or_b32 v34, v35, s33, v34
	v_bfe_u32 v35, v4, 16, 1
	v_add3_u32 v35, v4, v35, s46
	v_bfe_u32 v36, v5, 16, 1
	v_lshrrev_b32_e32 v35, 16, v35
	v_add3_u32 v36, v5, v36, s46
	v_and_or_b32 v35, v36, s33, v35
	global_store_dwordx2 v[6:7], v[34:35], off offset:3072
	v_bfe_u32 v34, v0, 16, 1
	v_add3_u32 v34, v0, v34, s46
	v_bfe_u32 v35, v1, 16, 1
	v_lshrrev_b32_e32 v34, 16, v34
	v_add3_u32 v35, v1, v35, s46
	v_and_or_b32 v34, v35, s33, v34
	v_bfe_u32 v35, v2, 16, 1
	v_add3_u32 v35, v2, v35, s46
	v_bfe_u32 v36, v3, 16, 1
	v_lshrrev_b32_e32 v35, 16, v35
	v_add3_u32 v36, v3, v36, s46
	v_and_or_b32 v35, v36, s33, v35
	global_store_dwordx2 v[6:7], v[34:35], off offset:3584
	v_mov_b32_e32 v34, v29
	v_mov_b32_e32 v35, v25
	v_mov_b32_e32 v6, v28
	v_mov_b32_e32 v7, v24
	v_pk_mul_f32 v[34:35], v[34:35], v[34:35]
	v_mov_b32_e32 v36, v31
	v_mov_b32_e32 v37, v27
	v_pk_fma_f32 v[6:7], v[6:7], v[6:7], v[34:35]
	v_mov_b32_e32 v34, v30
	v_mov_b32_e32 v35, v26
	v_pk_mul_f32 v[36:37], v[36:37], v[36:37]
	s_nop 0
	v_pk_fma_f32 v[34:35], v[34:35], v[34:35], v[36:37]
	v_pk_mul_f32 v[36:37], v[20:21], v[20:21]
	v_pk_add_f32 v[6:7], v[6:7], v[34:35]
	v_pk_mul_f32 v[34:35], v[22:23], v[22:23]
	v_pk_add_f32 v[6:7], v[6:7], v[6:7] op_sel_hi:[0,1]
	v_pk_mov_b32 v[38:39], v[36:37], v[34:35] op_sel:[1,0]
	v_mov_b32_e32 v37, v35
	v_mul_f32_e32 v6, v32, v32
	v_pk_add_f32 v[34:35], v[38:39], v[36:37]
	v_pk_fma_f32 v[36:37], v[32:33], v[32:33], v[6:7] op_sel_hi:[1,1,0]
	v_mul_f32_e32 v6, v18, v18
	v_pk_add_f32 v[34:35], v[34:35], v[34:35] op_sel_hi:[0,1]
	v_pk_fma_f32 v[38:39], v[18:19], v[18:19], v[6:7] op_sel_hi:[1,1,0]
	v_mul_f32_e32 v36, v16, v16
	v_mul_f32_e32 v38, v17, v17
	v_mul_f32_e32 v34, v14, v14
	v_mul_f32_e32 v6, v15, v15
	v_pk_add_f32 v[36:37], v[36:37], v[38:39]
	v_pk_add_f32 v[6:7], v[34:35], v[6:7]
	v_pk_mul_f32 v[34:35], v[10:11], v[10:11]
	v_pk_add_f32 v[6:7], v[36:37], v[6:7]
	v_pk_mul_f32 v[36:37], v[12:13], v[12:13]
	v_pk_add_f32 v[6:7], v[6:7], v[6:7] op_sel_hi:[0,1]
	v_pk_mov_b32 v[38:39], v[36:37], v[34:35] op_sel:[1,0]
	v_mov_b32_e32 v37, v35
	v_mul_f32_e32 v6, v8, v8
	v_pk_add_f32 v[34:35], v[38:39], v[36:37]
	v_pk_fma_f32 v[36:37], v[8:9], v[8:9], v[6:7] op_sel_hi:[1,1,0]
	v_mul_f32_e32 v6, v4, v4
	v_pk_add_f32 v[34:35], v[34:35], v[34:35] op_sel_hi:[0,1]
	v_pk_fma_f32 v[38:39], v[4:5], v[4:5], v[6:7] op_sel_hi:[1,1,0]
	v_mul_f32_e32 v36, v0, v0
	v_mul_f32_e32 v38, v1, v1
	v_mul_f32_e32 v34, v2, v2
	v_mul_f32_e32 v6, v3, v3
	v_pk_add_f32 v[36:37], v[36:37], v[38:39]
	v_pk_add_f32 v[6:7], v[34:35], v[6:7]
	s_nop 0
	v_pk_add_f32 v[6:7], v[36:37], v[6:7]
	ds_read_b128 v[36:39], v253 offset:8192
	v_add_f32_e32 v6, v6, v7
	ds_bpermute_b32 v7, v148, v6
	s_waitcnt lgkmcnt(0)
; __device__ __forceinline__ unsigned pk2(float lo, float hi) { const f32x2 v = {lo, hi}; const bf16x2_cv b = __builtin_convertvector(v, bf16x2_cv); return __builtin_bit_cast(unsigned, b); }
; __device__ __forceinline__ unsigned pk2(float lo, float hi) { return f2bf(lo) | (f2bf(hi) << 16); }
; __device__ __forceinline__ float wave_sum(float v) {
; #pragma unroll
;     for (int o = 1; o < 64; o <<= 1) v += __shfl_xor(v, o);
;     return v;
; template <bool XIN_BF, bool XOUT_BF>
; __device__ __forceinline__ void ew_rows(const void* xsrc, void* xdst, const bf16* y, float scale, const float* gpost, const float* gpre, bf16* hout, int gw, int ngw, int lane) {
;     ...
;                 const float rs2 = rsqrtf(wave_sum(s2) * (1.0f / DM) + 1e-6f);
;                 v2u* ho = (v2u*)(hout + (size_t)row * DM) + lane;
; #pragma unroll
;                 for (int j = 0; j < 8; ++j) { const f32x4 g = ((const f32x4*)gpre)[lane + 64 * j]; const f32x4 t = xv[j] * g * rs2; ho[64 * j] = (v2u){pk2(t.x, t.y), pk2(t.z, t.w)}; }
	v_add_f32_e32 v6, v6, v7
	ds_bpermute_b32 v7, v149, v6
	s_waitcnt lgkmcnt(0)
	v_add_f32_e32 v6, v6, v7
	ds_bpermute_b32 v7, v150, v6
	s_waitcnt lgkmcnt(0)
	v_add_f32_e32 v6, v6, v7
	ds_bpermute_b32 v7, v151, v6
	s_waitcnt lgkmcnt(0)
	v_add_f32_e32 v6, v6, v7
	ds_bpermute_b32 v7, v152, v6
	s_waitcnt lgkmcnt(0)
	v_add_f32_e32 v6, v6, v7
	ds_bpermute_b32 v7, v153, v6
	s_waitcnt lgkmcnt(0)
	v_add_f32_e32 v6, v6, v7
	v_fmamk_f32 v6, v6, 0x3a000000, v204
	v_cmp_gt_f32_e32 vcc, s34, v6
	v_mul_f32_e32 v7, 0x4b800000, v6
	s_waitcnt lgkmcnt(0)
	v_pk_mul_f32 v[28:29], v[28:29], v[36:37]
	v_cndmask_b32_e32 v6, v6, v7, vcc
	v_rsq_f32_e32 v6, v6
	v_pk_mul_f32 v[30:31], v[30:31], v[38:39]
	v_mul_f32_e32 v7, 0x45800000, v6
	v_cndmask_b32_e32 v34, v6, v7, vcc
	v_pk_mul_f32 v[28:29], v[28:29], v[34:35] op_sel_hi:[1,0]
	v_pk_mul_f32 v[30:31], v[30:31], v[34:35] op_sel_hi:[1,0]
	v_bfe_u32 v35, v28, 16, 1
	v_add3_u32 v28, v28, v35, s46
	v_bfe_u32 v35, v29, 16, 1
	v_lshrrev_b32_e32 v28, 16, v28
	v_add3_u32 v29, v29, v35, s46
	v_and_or_b32 v28, v29, s33, v28
	v_bfe_u32 v29, v30, 16, 1
	v_add3_u32 v29, v30, v29, s46
	v_bfe_u32 v30, v31, 16, 1
	v_lshrrev_b32_e32 v29, 16, v29
	v_add3_u32 v30, v31, v30, s46
	v_lshl_add_u64 v[6:7], v[70:71], 0, s[4:5]
	v_and_or_b32 v29, v30, s33, v29
	global_store_dwordx2 v[6:7], v[28:29], off
	ds_read_b128 v[28:31], v253 offset:9216
	s_waitcnt lgkmcnt(0)
	v_pk_mul_f32 v[24:25], v[24:25], v[28:29]
	s_nop 0
	v_pk_mul_f32 v[24:25], v[24:25], v[34:35] op_sel_hi:[1,0]
	v_pk_mul_f32 v[26:27], v[26:27], v[30:31]
	v_bfe_u32 v28, v24, 16, 1
	v_add3_u32 v24, v24, v28, s46
	v_bfe_u32 v28, v25, 16, 1
	v_pk_mul_f32 v[26:27], v[26:27], v[34:35] op_sel_hi:[1,0]
	v_lshrrev_b32_e32 v24, 16, v24
	v_add3_u32 v25, v25, v28, s46
	v_and_or_b32 v24, v25, s33, v24
	v_bfe_u32 v25, v26, 16, 1
	v_add3_u32 v25, v26, v25, s46
	v_bfe_u32 v26, v27, 16, 1
	v_lshrrev_b32_e32 v25, 16, v25
	v_add3_u32 v26, v27, v26, s46
	v_and_or_b32 v25, v26, s33, v25
	global_store_dwordx2 v[6:7], v[24:25], off offset:512
	ds_read_b128 v[24:27], v253 offset:10240
	s_waitcnt lgkmcnt(0)
	v_pk_mul_f32 v[20:21], v[20:21], v[24:25]
	s_nop 0
	v_pk_mul_f32 v[20:21], v[20:21], v[34:35] op_sel_hi:[1,0]
	v_pk_mul_f32 v[22:23], v[22:23], v[26:27]
	v_bfe_u32 v24, v20, 16, 1
	v_add3_u32 v20, v20, v24, s46
	v_bfe_u32 v24, v21, 16, 1
	v_pk_mul_f32 v[22:23], v[22:23], v[34:35] op_sel_hi:[1,0]
	v_lshrrev_b32_e32 v20, 16, v20
	v_add3_u32 v21, v21, v24, s46
	v_and_or_b32 v20, v21, s33, v20
	v_bfe_u32 v21, v22, 16, 1
	v_add3_u32 v21, v22, v21, s46
	v_bfe_u32 v22, v23, 16, 1
	v_lshrrev_b32_e32 v21, 16, v21
	v_add3_u32 v22, v23, v22, s46
	v_and_or_b32 v21, v22, s33, v21
	global_store_dwordx2 v[6:7], v[20:21], off offset:1024
	ds_read_b128 v[20:23], v253 offset:11264
	s_waitcnt lgkmcnt(0)
	v_pk_mul_f32 v[20:21], v[32:33], v[20:21]
	s_nop 0
	v_pk_mul_f32 v[20:21], v[20:21], v[34:35] op_sel_hi:[1,0]
	v_pk_mul_f32 v[18:19], v[18:19], v[22:23]
	v_bfe_u32 v22, v20, 16, 1
	v_add3_u32 v20, v20, v22, s46
	v_bfe_u32 v22, v21, 16, 1
	v_pk_mul_f32 v[18:19], v[18:19], v[34:35] op_sel_hi:[1,0]
	v_lshrrev_b32_e32 v20, 16, v20
	v_add3_u32 v21, v21, v22, s46
	v_and_or_b32 v20, v21, s33, v20
	v_bfe_u32 v21, v18, 16, 1
	v_add3_u32 v18, v18, v21, s46
	v_bfe_u32 v21, v19, 16, 1
	v_lshrrev_b32_e32 v18, 16, v18
	v_add3_u32 v19, v19, v21, s46
	v_and_or_b32 v21, v19, s33, v18
	global_store_dwordx2 v[6:7], v[20:21], off offset:1536
	ds_read_b128 v[18:21], v253 offset:12288
	s_waitcnt lgkmcnt(0)
	v_pk_mul_f32 v[16:17], v[16:17], v[18:19]
	s_nop 0
	v_pk_mul_f32 v[16:17], v[16:17], v[34:35] op_sel_hi:[1,0]
	v_pk_mul_f32 v[14:15], v[14:15], v[20:21]
	v_bfe_u32 v18, v16, 16, 1
	v_add3_u32 v16, v16, v18, s46
	v_bfe_u32 v18, v17, 16, 1
	v_pk_mul_f32 v[14:15], v[14:15], v[34:35] op_sel_hi:[1,0]
	v_lshrrev_b32_e32 v16, 16, v16
	v_add3_u32 v17, v17, v18, s46
	v_and_or_b32 v16, v17, s33, v16
	v_bfe_u32 v17, v14, 16, 1
	v_add3_u32 v14, v14, v17, s46
	v_bfe_u32 v17, v15, 16, 1
	v_lshrrev_b32_e32 v14, 16, v14
	v_add3_u32 v15, v15, v17, s46
	v_and_or_b32 v17, v15, s33, v14
	global_store_dwordx2 v[6:7], v[16:17], off offset:2048
	ds_read_b128 v[14:17], v253 offset:13312
	s_waitcnt lgkmcnt(0)
	v_pk_mul_f32 v[12:13], v[12:13], v[14:15]
	s_nop 0
	v_pk_mul_f32 v[12:13], v[12:13], v[34:35] op_sel_hi:[1,0]
	v_pk_mul_f32 v[10:11], v[10:11], v[16:17]
	v_bfe_u32 v14, v12, 16, 1
	v_add3_u32 v12, v12, v14, s46
	v_bfe_u32 v14, v13, 16, 1
	v_pk_mul_f32 v[10:11], v[10:11], v[34:35] op_sel_hi:[1,0]
	v_lshrrev_b32_e32 v12, 16, v12
	v_add3_u32 v13, v13, v14, s46
	v_and_or_b32 v12, v13, s33, v12
	v_bfe_u32 v13, v10, 16, 1
	v_add3_u32 v10, v10, v13, s46
	v_bfe_u32 v13, v11, 16, 1
	v_lshrrev_b32_e32 v10, 16, v10
	v_add3_u32 v11, v11, v13, s46
	v_and_or_b32 v13, v11, s33, v10
	global_store_dwordx2 v[6:7], v[12:13], off offset:2560
	ds_read_b128 v[10:13], v253 offset:14336
	s_waitcnt lgkmcnt(0)
	v_pk_mul_f32 v[8:9], v[8:9], v[10:11]
	s_nop 0
	v_pk_mul_f32 v[8:9], v[8:9], v[34:35] op_sel_hi:[1,0]
	v_pk_mul_f32 v[4:5], v[4:5], v[12:13]
	v_bfe_u32 v10, v8, 16, 1
	v_add3_u32 v8, v8, v10, s46
	v_bfe_u32 v10, v9, 16, 1
	v_pk_mul_f32 v[4:5], v[4:5], v[34:35] op_sel_hi:[1,0]
	v_lshrrev_b32_e32 v8, 16, v8
	v_add3_u32 v9, v9, v10, s46
	v_and_or_b32 v8, v9, s33, v8
	v_bfe_u32 v9, v4, 16, 1
	v_add3_u32 v4, v4, v9, s46
	v_bfe_u32 v9, v5, 16, 1
	v_lshrrev_b32_e32 v4, 16, v4
	v_add3_u32 v5, v5, v9, s46
	v_and_or_b32 v9, v5, s33, v4
	global_store_dwordx2 v[6:7], v[8:9], off offset:3072
	ds_read_b128 v[8:11], v253 offset:15360
	s_waitcnt lgkmcnt(0)
	v_pk_mul_f32 v[0:1], v[0:1], v[8:9]
	s_nop 0
	v_pk_mul_f32 v[0:1], v[0:1], v[34:35] op_sel_hi:[1,0]
	v_pk_mul_f32 v[2:3], v[2:3], v[10:11]
	v_bfe_u32 v4, v0, 16, 1
	v_add3_u32 v0, v0, v4, s46
	v_bfe_u32 v4, v1, 16, 1
	v_pk_mul_f32 v[2:3], v[2:3], v[34:35] op_sel_hi:[1,0]
	v_lshrrev_b32_e32 v0, 16, v0
	v_add3_u32 v1, v1, v4, s46
	v_and_or_b32 v0, v1, s33, v0
	v_bfe_u32 v1, v2, 16, 1
	v_add3_u32 v1, v2, v1, s46
	v_bfe_u32 v2, v3, 16, 1
	v_lshrrev_b32_e32 v1, 16, v1
	v_add3_u32 v2, v3, v2, s46
	v_and_or_b32 v1, v2, s33, v1
	global_store_dwordx2 v[6:7], v[0:1], off offset:3584
	s_branch .LBB0_771
